# GEMM K-loops: per-phase s_setprio flips deleted, one static s_setprio 1 for waves 0-3 (0 for waves 4-7) before each loop
# speedup vs baseline: 1.0023x; 1.0022x over previous
; #define PG8_STAGE(bufoff, gbase, voff) do { _Pragma("unroll") for (int _i = 0; _i < 2; ++_i) \
;         __builtin_amdgcn_global_load_lds((const unsigned*)((const char*)(gbase) + (voff)[_i]), (PG8_LAS unsigned*)(lds + (bufoff) + ldsw + _i * 8192), 16, 0, 0); } while (0)
; #define PG8_LDA(dst, b, h) do { _Pragma("unroll") for (int m = 0; m < 4; ++m) _Pragma("unroll") for (int k = 0; k < 2; ++k) dst[m][k] = *(const PG8_LAS bf16x8*)(lds + PG8_SA(b, h) + aoff + m * 2048 + k * 1024); } while (0)
; #define PG8_LDB(dst, b, h) do { _Pragma("unroll") for (int n = 0; n < 2; ++n) _Pragma("unroll") for (int k = 0; k < 2; ++k) dst[n][k] = *(const PG8_LAS bf16x8*)(lds + PG8_SB(b, h) + boff + n * 2048 + k * 1024); } while (0)
; #define PG8_SCHED __builtin_amdgcn_sched_barrier(0)
; template <class Epi, class Sched, bool ALIGN_EPI = false, bool SP2 = false>
; __device__ __forceinline__ void gemm_phase(PG8_LAS unsigned char* lds, const Gemm g, const Sched& S, const Epi& E) {
;     ...
;         const bool has_next = S.next(ui + 1, nxt);
;         const char* nA = has_next ? (const char*)g.A + (size_t)nxt.pm * tstep : cA; const char* nB = has_next ? (const char*)g.Bt + (size_t)nxt.pn * tstep : cB;
;         for (int t = 0; t < nt; t += 2) {
;             const bool last = (t == nt - 2);
;             const char* a1 = cA + (size_t)(t + 1) * kstep;
;             const char* a2 = last ? nA : cA + (size_t)(t + 2) * kstep; const char* b2 = last ? nB : cB + (size_t)(t + 2) * kstep;
;             const char* a3 = a2 + kstep; const char* b3 = b2 + kstep;
;             if (last && has_next) S.a_ready(nxt);
;             if constexpr (SP2) {
;             PG8_LDB(B0, 0, 0); PG8_LDB(B1, 0, 1); PG8_SCHED; PG8_LDA(At, 0, 0); PG8_STAGE(PG8_SA(1, 1), a1 + hstep, voffA);
;     ...
;         for (int a = 0; a < 2; ++a)
; #pragma unroll
;             for (int b = 0; b < 2; ++b)
; #pragma unroll
;                 for (int m = 0; m < 4; ++m)
; #pragma unroll
;                     for (int n = 0; n < 2; ++n) acc[a][b][m][n] = (f32x4){0.f, 0.f, 0.f, 0.f};
.LBB0_85:
	s_ashr_i32 s29, s28, 31
	s_lshl_b64 s[26:27], s[28:29], 20
	s_add_u32 s30, s22, s26
	s_addc_u32 s31, s23, s27
	s_and_b64 s[26:27], s[36:37], exec
	s_cselect_b32 s29, s31, s41
	s_cselect_b32 s50, s30, s40
	s_ashr_i32 s19, s18, 31
	s_lshl_b64 s[26:27], s[18:19], 20
	v_readlane_b32 s34, v254, 40
	v_readlane_b32 s35, v254, 41
	s_add_u32 s34, s34, s26
	s_addc_u32 s35, s35, s27
	s_and_b64 s[26:27], s[36:37], exec
	s_cselect_b32 s19, s35, s39
	s_cselect_b32 s51, s34, s38
	s_add_u32 s52, s38, 0x100
	s_addc_u32 s53, s39, 0
	s_add_u32 s38, s40, 0x80080
	v_mov_b32_e32 v4, 0
	s_addc_u32 s39, s41, 0
	s_mov_b32 s54, -2
	v_mov_b32_e32 v5, v4
	v_mov_b32_e32 v6, v4
	v_mov_b32_e32 v7, v4
	v_mov_b32_e32 v8, v4
	v_mov_b32_e32 v9, v4
	v_mov_b32_e32 v10, v4
	v_mov_b32_e32 v11, v4
	v_mov_b32_e32 v16, v4
	v_mov_b32_e32 v17, v4
	v_mov_b32_e32 v18, v4
	v_mov_b32_e32 v19, v4
	v_mov_b32_e32 v24, v4
	v_mov_b32_e32 v25, v4
	v_mov_b32_e32 v26, v4
	v_mov_b32_e32 v27, v4
	s_waitcnt vmcnt(0)
	v_mov_b32_e32 v32, v4
	v_mov_b32_e32 v33, v4
	v_mov_b32_e32 v34, v4
	v_mov_b32_e32 v35, v4
	v_mov_b32_e32 v40, v4
	v_mov_b32_e32 v41, v4
	v_mov_b32_e32 v42, v4
	v_mov_b32_e32 v43, v4
	v_mov_b32_e32 v48, v4
	v_mov_b32_e32 v49, v4
	v_mov_b32_e32 v50, v4
	v_mov_b32_e32 v51, v4
	v_mov_b32_e32 v56, v4
	v_mov_b32_e32 v57, v4
	v_mov_b32_e32 v58, v4
	v_mov_b32_e32 v59, v4
	v_mov_b32_e32 v12, v4
	v_mov_b32_e32 v13, v4
	v_mov_b32_e32 v14, v4
	v_mov_b32_e32 v15, v4
	v_mov_b32_e32 v20, v4
	v_mov_b32_e32 v21, v4
	v_mov_b32_e32 v22, v4
	v_mov_b32_e32 v23, v4
	v_mov_b32_e32 v28, v4
	v_mov_b32_e32 v29, v4
	v_mov_b32_e32 v30, v4
	v_mov_b32_e32 v31, v4
	v_mov_b32_e32 v36, v4
	v_mov_b32_e32 v37, v4
	v_mov_b32_e32 v38, v4
	v_mov_b32_e32 v39, v4
	v_mov_b32_e32 v44, v4
	v_mov_b32_e32 v45, v4
	v_mov_b32_e32 v46, v4
	v_mov_b32_e32 v47, v4
	v_mov_b32_e32 v52, v4
	v_mov_b32_e32 v53, v4
	v_mov_b32_e32 v54, v4
	v_mov_b32_e32 v55, v4
	v_mov_b32_e32 v60, v4
	v_mov_b32_e32 v61, v4
	v_mov_b32_e32 v62, v4
	v_mov_b32_e32 v63, v4
	v_mov_b32_e32 v64, v4
	v_mov_b32_e32 v65, v4
	v_mov_b32_e32 v66, v4
	v_mov_b32_e32 v67, v4
	v_mov_b32_e32 v68, v4
	v_mov_b32_e32 v69, v4
	v_mov_b32_e32 v70, v4
	v_mov_b32_e32 v71, v4
	v_mov_b32_e32 v72, v4
	v_mov_b32_e32 v73, v4
	v_mov_b32_e32 v74, v4
	v_mov_b32_e32 v75, v4
	v_mov_b32_e32 v84, v4
	v_mov_b32_e32 v85, v4
	v_mov_b32_e32 v86, v4
	v_mov_b32_e32 v87, v4
	v_mov_b32_e32 v88, v4
	v_mov_b32_e32 v89, v4
	v_mov_b32_e32 v90, v4
	v_mov_b32_e32 v91, v4
	v_mov_b32_e32 v100, v4
	v_mov_b32_e32 v101, v4
	v_mov_b32_e32 v102, v4
	v_mov_b32_e32 v103, v4
	v_mov_b32_e32 v104, v4
	v_mov_b32_e32 v105, v4
	v_mov_b32_e32 v106, v4
	v_mov_b32_e32 v107, v4
	v_mov_b32_e32 v116, v4
	v_mov_b32_e32 v117, v4
	v_mov_b32_e32 v118, v4
	v_mov_b32_e32 v119, v4
	v_mov_b32_e32 v120, v4
	v_mov_b32_e32 v121, v4
	v_mov_b32_e32 v122, v4
	v_mov_b32_e32 v123, v4
	v_mov_b32_e32 v76, v4
	v_mov_b32_e32 v77, v4
	v_mov_b32_e32 v78, v4
	v_mov_b32_e32 v79, v4
	v_mov_b32_e32 v80, v4
	v_mov_b32_e32 v81, v4
	v_mov_b32_e32 v82, v4
	v_mov_b32_e32 v83, v4
	v_mov_b32_e32 v92, v4
	v_mov_b32_e32 v93, v4
	v_mov_b32_e32 v94, v4
	v_mov_b32_e32 v95, v4
	v_mov_b32_e32 v96, v4
	v_mov_b32_e32 v97, v4
	v_mov_b32_e32 v98, v4
	v_mov_b32_e32 v99, v4
	v_mov_b32_e32 v108, v4
	v_mov_b32_e32 v109, v4
	v_mov_b32_e32 v110, v4
	v_mov_b32_e32 v111, v4
	v_mov_b32_e32 v112, v4
	v_mov_b32_e32 v113, v4
	v_mov_b32_e32 v114, v4
	v_mov_b32_e32 v115, v4
	v_mov_b32_e32 v124, v4
	v_mov_b32_e32 v125, v4
	v_mov_b32_e32 v126, v4
	v_mov_b32_e32 v127, v4
	v_mov_b32_e32 v128, v4
	v_mov_b32_e32 v129, v4
	v_mov_b32_e32 v130, v4
	v_mov_b32_e32 v131, v4
	v_readfirstlane_b32 s101, v172
	s_nop 3
	s_cmp_ge_u32 s101, 0x100
	s_cbranch_scc1 .Lprio_hi_86
	s_setprio 1
	s_branch .Lprio_done_86
.Lprio_hi_86:
	s_setprio 0
.Lprio_done_86:
.LBB0_86:
	s_add_u32 s26, s38, 0xfff80080
	s_addc_u32 s27, s39, -1
	s_add_i32 s55, 0, 0x10000
	s_cmp_eq_u32 s54, 28
	s_cselect_b32 s27, s29, s27
	s_cselect_b32 s26, s50, s26
	v_add_u32_e32 v142, s55, v147
	s_cselect_b32 s41, s19, s53
	s_cselect_b32 s40, s51, s52
	s_add_i32 s58, 0, 0x14000
	ds_read_b128 v[148:151], v142
	ds_read_b128 v[156:159], v142 offset:1024
	ds_read_b128 v[160:163], v142 offset:2048
	ds_read_b128 v[164:167], v142 offset:3072
	v_add_u32_e32 v142, s58, v147
	ds_read_b128 v[168:171], v142
	ds_read_b128 v[184:187], v142 offset:1024
	ds_read_b128 v[188:191], v142 offset:2048
	ds_read_b128 v[192:195], v142 offset:3072
	v_lshl_add_u64 v[144:145], s[38:39], 0, v[140:141]
	s_add_i32 m0, s25, 0xc000
	ds_read_b128 v[196:199], v155
	ds_read_b128 v[200:203], v155 offset:1024
	ds_read_b128 v[204:207], v155 offset:2048
	ds_read_b128 v[208:211], v155 offset:3072
	ds_read_b128 v[212:215], v155 offset:4096
	ds_read_b128 v[216:219], v155 offset:5120
	ds_read_b128 v[220:223], v155 offset:6144
	ds_read_b128 v[224:227], v155 offset:7168
	global_load_lds_dwordx4 v[144:145], off
	v_lshl_add_u64 v[144:145], s[38:39], 0, v[138:139]
	s_add_i32 m0, s25, 0xe000
	s_nop 0
	global_load_lds_dwordx4 v[144:145], off
	s_waitcnt vmcnt(8)
	s_waitcnt lgkmcnt(0)
	s_barrier
; #define PG8_STAGE(bufoff, gbase, voff) do { _Pragma("unroll") for (int _i = 0; _i < 2; ++_i) \
;         __builtin_amdgcn_global_load_lds((const unsigned*)((const char*)(gbase) + (voff)[_i]), (PG8_LAS unsigned*)(lds + (bufoff) + ldsw + _i * 8192), 16, 0, 0); } while (0)
; #define PG8_LDA(dst, b, h) do { _Pragma("unroll") for (int m = 0; m < 4; ++m) _Pragma("unroll") for (int k = 0; k < 2; ++k) dst[m][k] = *(const PG8_LAS bf16x8*)(lds + PG8_SA(b, h) + aoff + m * 2048 + k * 1024); } while (0)
; #define PG8_MMA(ai, bj, At, Bt) do { __builtin_amdgcn_s_setprio(1); _Pragma("unroll") for (int m = 0; m < 4; ++m) _Pragma("unroll") for (int n = 0; n < 2; ++n) _Pragma("unroll") for (int k = 0; k < 2; ++k) \
;         acc[ai][bj][m][n] = __builtin_amdgcn_mfma_f32_16x16x32_bf16(Bt[n][k], At[m][k], acc[ai][bj][m][n], 0, 0, 0); __builtin_amdgcn_s_setprio(0); } while (0)
; #define PG8_WAIT_V(n) asm volatile("s_waitcnt vmcnt(" #n ")" ::: "memory")
; #define PG8_WAIT_L(n) asm volatile("s_waitcnt lgkmcnt(" #n ")" ::: "memory")
; #define PG8_BAR __builtin_amdgcn_s_barrier()
; #define PG8_SCHED __builtin_amdgcn_sched_barrier(0)
; template <class Epi, class Sched, bool ALIGN_EPI = false, bool SP2 = false>
; __device__ __forceinline__ void gemm_phase(PG8_LAS unsigned char* lds, const Gemm g, const Sched& S, const Epi& E) {
;     ...
;             PG8_WAIT_V(8); PG8_WAIT_L(0); PG8_BAR; PG8_MMA(0, 0, At, B0); PG8_MMA(0, 1, At, B1); PG8_BAR; PG8_SCHED;
;             PG8_LDA(At, 0, 1); PG8_STAGE(PG8_SB(0, 0), b2, voffB); PG8_STAGE(PG8_SB(0, 1), b2 + hstep, voffB); PG8_STAGE(PG8_SA(0, 0), a2, voffA);
;             PG8_WAIT_V(8); PG8_WAIT_L(0); PG8_BAR; PG8_MMA(1, 0, At, B0); PG8_MMA(1, 1, At, B1); PG8_BAR; PG8_SCHED;
	s_waitcnt lgkmcnt(0)
	v_mfma_f32_16x16x32_bf16 v[128:131], v[148:151], v[196:199], v[128:131]
	v_mfma_f32_16x16x32_bf16 v[124:127], v[160:163], v[196:199], v[124:127]
	v_mfma_f32_16x16x32_bf16 v[112:115], v[148:151], v[204:207], v[112:115]
	v_mfma_f32_16x16x32_bf16 v[108:111], v[160:163], v[204:207], v[108:111]
	v_mfma_f32_16x16x32_bf16 v[96:99], v[148:151], v[212:215], v[96:99]
	v_mfma_f32_16x16x32_bf16 v[92:95], v[160:163], v[212:215], v[92:95]
	v_mfma_f32_16x16x32_bf16 v[80:83], v[148:151], v[220:223], v[80:83]
	v_mfma_f32_16x16x32_bf16 v[76:79], v[160:163], v[220:223], v[76:79]
	v_mfma_f32_16x16x32_bf16 v[128:131], v[156:159], v[200:203], v[128:131]
	v_mfma_f32_16x16x32_bf16 v[124:127], v[164:167], v[200:203], v[124:127]
	v_mfma_f32_16x16x32_bf16 v[112:115], v[156:159], v[208:211], v[112:115]
	v_mfma_f32_16x16x32_bf16 v[108:111], v[164:167], v[208:211], v[108:111]
	v_mfma_f32_16x16x32_bf16 v[96:99], v[156:159], v[216:219], v[96:99]
	v_mfma_f32_16x16x32_bf16 v[92:95], v[164:167], v[216:219], v[92:95]
	v_mfma_f32_16x16x32_bf16 v[80:83], v[156:159], v[224:227], v[80:83]
	v_mfma_f32_16x16x32_bf16 v[76:79], v[164:167], v[224:227], v[76:79]
	v_mfma_f32_16x16x32_bf16 v[120:123], v[168:171], v[196:199], v[120:123]
	v_mfma_f32_16x16x32_bf16 v[116:119], v[188:191], v[196:199], v[116:119]
	v_mfma_f32_16x16x32_bf16 v[104:107], v[168:171], v[204:207], v[104:107]
	v_mfma_f32_16x16x32_bf16 v[100:103], v[188:191], v[204:207], v[100:103]
	v_mfma_f32_16x16x32_bf16 v[88:91], v[168:171], v[212:215], v[88:91]
	v_mfma_f32_16x16x32_bf16 v[84:87], v[188:191], v[212:215], v[84:87]
	v_mfma_f32_16x16x32_bf16 v[72:75], v[168:171], v[220:223], v[72:75]
	v_mfma_f32_16x16x32_bf16 v[68:71], v[188:191], v[220:223], v[68:71]
	v_mfma_f32_16x16x32_bf16 v[120:123], v[184:187], v[200:203], v[120:123]
	v_mfma_f32_16x16x32_bf16 v[116:119], v[192:195], v[200:203], v[116:119]
	v_mfma_f32_16x16x32_bf16 v[104:107], v[184:187], v[208:211], v[104:107]
	v_mfma_f32_16x16x32_bf16 v[100:103], v[192:195], v[208:211], v[100:103]
	v_mfma_f32_16x16x32_bf16 v[88:91], v[184:187], v[216:219], v[88:91]
	v_mfma_f32_16x16x32_bf16 v[84:87], v[192:195], v[216:219], v[84:87]
	v_mfma_f32_16x16x32_bf16 v[72:75], v[184:187], v[224:227], v[72:75]
	v_mfma_f32_16x16x32_bf16 v[68:71], v[192:195], v[224:227], v[68:71]
	s_barrier
	s_add_i32 s55, s55, s24
	v_lshl_add_u64 v[144:145], s[40:41], 0, v[174:175]
	s_mov_b32 m0, s55
	ds_read_b128 v[196:199], v155 offset:16384
	ds_read_b128 v[200:203], v155 offset:17408
	ds_read_b128 v[204:207], v155 offset:18432
	ds_read_b128 v[208:211], v155 offset:19456
	ds_read_b128 v[212:215], v155 offset:20480
	ds_read_b128 v[216:219], v155 offset:21504
	ds_read_b128 v[220:223], v155 offset:22528
	ds_read_b128 v[224:227], v155 offset:23552
	global_load_lds_dwordx4 v[144:145], off
	s_add_i32 m0, s55, 0x2000
	s_add_u32 s56, s40, 0x80000
	v_lshl_add_u64 v[228:229], s[40:41], 0, v[132:133]
	s_addc_u32 s57, s41, 0
	s_add_i32 s55, s58, s24
	global_load_lds_dwordx4 v[228:229], off
	v_lshl_add_u64 v[230:231], s[56:57], 0, v[174:175]
	s_mov_b32 m0, s55
	v_lshl_add_u64 v[232:233], s[26:27], 0, v[134:135]
	global_load_lds_dwordx4 v[230:231], off
	v_lshl_add_u64 v[230:231], s[56:57], 0, v[132:133]
	s_add_i32 m0, s55, 0x2000
	s_nop 0
	global_load_lds_dwordx4 v[230:231], off
	v_lshl_add_u64 v[230:231], s[26:27], 0, v[136:137]
	s_mov_b32 m0, s25
	s_nop 0
	global_load_lds_dwordx4 v[230:231], off
	s_mov_b32 m0, s42
	s_nop 0
	global_load_lds_dwordx4 v[232:233], off
	s_waitcnt vmcnt(8)
	s_waitcnt lgkmcnt(0)
	s_barrier
	s_waitcnt lgkmcnt(0)
	v_mfma_f32_16x16x32_bf16 v[64:67], v[148:151], v[196:199], v[64:67]
	v_mfma_f32_16x16x32_bf16 v[60:63], v[160:163], v[196:199], v[60:63]
	v_mfma_f32_16x16x32_bf16 v[52:55], v[148:151], v[204:207], v[52:55]
	v_mfma_f32_16x16x32_bf16 v[44:47], v[160:163], v[204:207], v[44:47]
	v_mfma_f32_16x16x32_bf16 v[36:39], v[148:151], v[212:215], v[36:39]
	v_mfma_f32_16x16x32_bf16 v[28:31], v[160:163], v[212:215], v[28:31]
	v_mfma_f32_16x16x32_bf16 v[20:23], v[148:151], v[220:223], v[20:23]
	v_mfma_f32_16x16x32_bf16 v[12:15], v[160:163], v[220:223], v[12:15]
	v_mfma_f32_16x16x32_bf16 v[64:67], v[156:159], v[200:203], v[64:67]
	v_mfma_f32_16x16x32_bf16 v[60:63], v[164:167], v[200:203], v[60:63]
	v_mfma_f32_16x16x32_bf16 v[52:55], v[156:159], v[208:211], v[52:55]
	v_mfma_f32_16x16x32_bf16 v[44:47], v[164:167], v[208:211], v[44:47]
	v_mfma_f32_16x16x32_bf16 v[36:39], v[156:159], v[216:219], v[36:39]
	v_mfma_f32_16x16x32_bf16 v[28:31], v[164:167], v[216:219], v[28:31]
	v_mfma_f32_16x16x32_bf16 v[20:23], v[156:159], v[224:227], v[20:23]
	v_mfma_f32_16x16x32_bf16 v[12:15], v[164:167], v[224:227], v[12:15]
	v_mfma_f32_16x16x32_bf16 v[56:59], v[168:171], v[196:199], v[56:59]
	v_mfma_f32_16x16x32_bf16 v[48:51], v[188:191], v[196:199], v[48:51]
	v_mfma_f32_16x16x32_bf16 v[40:43], v[168:171], v[204:207], v[40:43]
	v_mfma_f32_16x16x32_bf16 v[32:35], v[188:191], v[204:207], v[32:35]
	v_mfma_f32_16x16x32_bf16 v[24:27], v[168:171], v[212:215], v[24:27]
	v_mfma_f32_16x16x32_bf16 v[16:19], v[188:191], v[212:215], v[16:19]
	v_mfma_f32_16x16x32_bf16 v[8:11], v[168:171], v[220:223], v[8:11]
	v_mfma_f32_16x16x32_bf16 v[4:7], v[188:191], v[220:223], v[4:7]
	v_mfma_f32_16x16x32_bf16 v[56:59], v[184:187], v[200:203], v[56:59]
	v_mfma_f32_16x16x32_bf16 v[48:51], v[192:195], v[200:203], v[48:51]
	v_mfma_f32_16x16x32_bf16 v[40:43], v[184:187], v[208:211], v[40:43]
	v_mfma_f32_16x16x32_bf16 v[32:35], v[192:195], v[208:211], v[32:35]
	v_mfma_f32_16x16x32_bf16 v[24:27], v[184:187], v[216:219], v[24:27]
	v_mfma_f32_16x16x32_bf16 v[16:19], v[192:195], v[216:219], v[16:19]
	v_mfma_f32_16x16x32_bf16 v[8:11], v[184:187], v[224:227], v[8:11]
	v_mfma_f32_16x16x32_bf16 v[4:7], v[192:195], v[224:227], v[4:7]
	s_barrier
; #define PG8_STAGE(bufoff, gbase, voff) do { _Pragma("unroll") for (int _i = 0; _i < 2; ++_i) \
;         __builtin_amdgcn_global_load_lds((const unsigned*)((const char*)(gbase) + (voff)[_i]), (PG8_LAS unsigned*)(lds + (bufoff) + ldsw + _i * 8192), 16, 0, 0); } while (0)
; #define PG8_LDA(dst, b, h) do { _Pragma("unroll") for (int m = 0; m < 4; ++m) _Pragma("unroll") for (int k = 0; k < 2; ++k) dst[m][k] = *(const PG8_LAS bf16x8*)(lds + PG8_SA(b, h) + aoff + m * 2048 + k * 1024); } while (0)
; #define PG8_LDB(dst, b, h) do { _Pragma("unroll") for (int n = 0; n < 2; ++n) _Pragma("unroll") for (int k = 0; k < 2; ++k) dst[n][k] = *(const PG8_LAS bf16x8*)(lds + PG8_SB(b, h) + boff + n * 2048 + k * 1024); } while (0)
; #define PG8_MMA(ai, bj, At, Bt) do { __builtin_amdgcn_s_setprio(1); _Pragma("unroll") for (int m = 0; m < 4; ++m) _Pragma("unroll") for (int n = 0; n < 2; ++n) _Pragma("unroll") for (int k = 0; k < 2; ++k) \
;         acc[ai][bj][m][n] = __builtin_amdgcn_mfma_f32_16x16x32_bf16(Bt[n][k], At[m][k], acc[ai][bj][m][n], 0, 0, 0); __builtin_amdgcn_s_setprio(0); } while (0)
; #define PG8_WAIT_V(n) asm volatile("s_waitcnt vmcnt(" #n ")" ::: "memory")
; #define PG8_WAIT_L(n) asm volatile("s_waitcnt lgkmcnt(" #n ")" ::: "memory")
; #define PG8_BAR __builtin_amdgcn_s_barrier()
; #define PG8_SCHED __builtin_amdgcn_sched_barrier(0)
; template <class Epi, class Sched, bool ALIGN_EPI = false, bool SP2 = false>
; __device__ __forceinline__ void gemm_phase(PG8_LAS unsigned char* lds, const Gemm g, const Sched& S, const Epi& E) {
;     ...
;             PG8_LDB(B0, 1, 0); PG8_LDB(B1, 1, 1); PG8_SCHED; PG8_LDA(At, 1, 0); PG8_STAGE(PG8_SA(0, 1), a2 + hstep, voffA);
;             PG8_WAIT_V(8); PG8_WAIT_L(0); PG8_BAR; PG8_MMA(0, 0, At, B0); PG8_MMA(0, 1, At, B1); PG8_BAR; PG8_SCHED;
	s_add_i32 s55, 0, 0x18000
	v_add_u32_e32 v142, s55, v147
	s_add_i32 s56, 0, 0x1c000
	ds_read_b128 v[148:151], v142
	ds_read_b128 v[156:159], v142 offset:1024
	ds_read_b128 v[160:163], v142 offset:2048
	ds_read_b128 v[164:167], v142 offset:3072
	v_add_u32_e32 v142, s56, v147
	ds_read_b128 v[168:171], v142
	ds_read_b128 v[184:187], v142 offset:1024
	ds_read_b128 v[188:191], v142 offset:2048
	ds_read_b128 v[192:195], v142 offset:3072
	s_add_u32 s26, s26, 0x80000
	s_addc_u32 s27, s27, 0
	s_mov_b32 m0, s43
	v_lshl_add_u64 v[234:235], s[26:27], 0, v[136:137]
	ds_read_b128 v[196:199], v155 offset:32768
	ds_read_b128 v[200:203], v155 offset:33792
	ds_read_b128 v[204:207], v155 offset:34816
	ds_read_b128 v[208:211], v155 offset:35840
	ds_read_b128 v[212:215], v155 offset:36864
	ds_read_b128 v[216:219], v155 offset:37888
	ds_read_b128 v[220:223], v155 offset:38912
	ds_read_b128 v[224:227], v155 offset:39936
	global_load_lds_dwordx4 v[234:235], off
	v_lshl_add_u64 v[234:235], s[26:27], 0, v[134:135]
	s_mov_b32 m0, s44
	s_nop 0
	global_load_lds_dwordx4 v[234:235], off
	s_waitcnt vmcnt(8)
	s_waitcnt lgkmcnt(0)
	s_barrier
	s_waitcnt lgkmcnt(0)
	v_mfma_f32_16x16x32_bf16 v[128:131], v[148:151], v[196:199], v[128:131]
	v_mfma_f32_16x16x32_bf16 v[124:127], v[160:163], v[196:199], v[124:127]
	v_mfma_f32_16x16x32_bf16 v[112:115], v[148:151], v[204:207], v[112:115]
	v_mfma_f32_16x16x32_bf16 v[108:111], v[160:163], v[204:207], v[108:111]
	v_mfma_f32_16x16x32_bf16 v[96:99], v[148:151], v[212:215], v[96:99]
	v_mfma_f32_16x16x32_bf16 v[92:95], v[160:163], v[212:215], v[92:95]
	v_mfma_f32_16x16x32_bf16 v[80:83], v[148:151], v[220:223], v[80:83]
	v_mfma_f32_16x16x32_bf16 v[76:79], v[160:163], v[220:223], v[76:79]
	v_mfma_f32_16x16x32_bf16 v[128:131], v[156:159], v[200:203], v[128:131]
	v_mfma_f32_16x16x32_bf16 v[124:127], v[164:167], v[200:203], v[124:127]
	v_mfma_f32_16x16x32_bf16 v[112:115], v[156:159], v[208:211], v[112:115]
	v_mfma_f32_16x16x32_bf16 v[108:111], v[164:167], v[208:211], v[108:111]
	v_mfma_f32_16x16x32_bf16 v[96:99], v[156:159], v[216:219], v[96:99]
	v_mfma_f32_16x16x32_bf16 v[92:95], v[164:167], v[216:219], v[92:95]
	v_mfma_f32_16x16x32_bf16 v[80:83], v[156:159], v[224:227], v[80:83]
	v_mfma_f32_16x16x32_bf16 v[76:79], v[164:167], v[224:227], v[76:79]
	v_mfma_f32_16x16x32_bf16 v[120:123], v[168:171], v[196:199], v[120:123]
	v_mfma_f32_16x16x32_bf16 v[116:119], v[188:191], v[196:199], v[116:119]
	v_mfma_f32_16x16x32_bf16 v[104:107], v[168:171], v[204:207], v[104:107]
	v_mfma_f32_16x16x32_bf16 v[100:103], v[188:191], v[204:207], v[100:103]
	v_mfma_f32_16x16x32_bf16 v[88:91], v[168:171], v[212:215], v[88:91]
	v_mfma_f32_16x16x32_bf16 v[84:87], v[188:191], v[212:215], v[84:87]
	v_mfma_f32_16x16x32_bf16 v[72:75], v[168:171], v[220:223], v[72:75]
	v_mfma_f32_16x16x32_bf16 v[68:71], v[188:191], v[220:223], v[68:71]
	v_mfma_f32_16x16x32_bf16 v[120:123], v[184:187], v[200:203], v[120:123]
	v_mfma_f32_16x16x32_bf16 v[116:119], v[192:195], v[200:203], v[116:119]
	v_mfma_f32_16x16x32_bf16 v[104:107], v[184:187], v[208:211], v[104:107]
	v_mfma_f32_16x16x32_bf16 v[100:103], v[192:195], v[208:211], v[100:103]
	v_mfma_f32_16x16x32_bf16 v[88:91], v[184:187], v[216:219], v[88:91]
	v_mfma_f32_16x16x32_bf16 v[84:87], v[192:195], v[216:219], v[84:87]
	v_mfma_f32_16x16x32_bf16 v[72:75], v[184:187], v[224:227], v[72:75]
	v_mfma_f32_16x16x32_bf16 v[68:71], v[192:195], v[224:227], v[68:71]
	s_barrier
; #define PG8_STAGE(bufoff, gbase, voff) do { _Pragma("unroll") for (int _i = 0; _i < 2; ++_i) \
;         __builtin_amdgcn_global_load_lds((const unsigned*)((const char*)(gbase) + (voff)[_i]), (PG8_LAS unsigned*)(lds + (bufoff) + ldsw + _i * 8192), 16, 0, 0); } while (0)
; #define PG8_LDA(dst, b, h) do { _Pragma("unroll") for (int m = 0; m < 4; ++m) _Pragma("unroll") for (int k = 0; k < 2; ++k) dst[m][k] = *(const PG8_LAS bf16x8*)(lds + PG8_SA(b, h) + aoff + m * 2048 + k * 1024); } while (0)
; #define PG8_MMA(ai, bj, At, Bt) do { __builtin_amdgcn_s_setprio(1); _Pragma("unroll") for (int m = 0; m < 4; ++m) _Pragma("unroll") for (int n = 0; n < 2; ++n) _Pragma("unroll") for (int k = 0; k < 2; ++k) \
;         acc[ai][bj][m][n] = __builtin_amdgcn_mfma_f32_16x16x32_bf16(Bt[n][k], At[m][k], acc[ai][bj][m][n], 0, 0, 0); __builtin_amdgcn_s_setprio(0); } while (0)
; #define PG8_WAIT_V(n) asm volatile("s_waitcnt vmcnt(" #n ")" ::: "memory")
; #define PG8_WAIT_L(n) asm volatile("s_waitcnt lgkmcnt(" #n ")" ::: "memory")
; #define PG8_BAR __builtin_amdgcn_s_barrier()
; #define PG8_SCHED __builtin_amdgcn_sched_barrier(0)
; template <class Epi, class Sched, bool ALIGN_EPI = false, bool SP2 = false>
; __device__ __forceinline__ void gemm_phase(PG8_LAS unsigned char* lds, const Gemm g, const Sched& S, const Epi& E) {
;     ...
;             PG8_LDA(At, 1, 1); PG8_STAGE(PG8_SB(1, 0), b3, voffB); PG8_STAGE(PG8_SB(1, 1), b3 + hstep, voffB); PG8_STAGE(PG8_SA(1, 0), a3, voffA);
;             PG8_WAIT_V(8); PG8_WAIT_L(0); PG8_BAR; PG8_MMA(1, 0, At, B0); PG8_MMA(1, 1, At, B1); PG8_BAR; PG8_SCHED;
	s_add_i32 s26, s55, s24
	v_lshl_add_u64 v[144:145], v[144:145], 0, s[10:11]
	s_mov_b32 m0, s26
	ds_read_b128 v[196:199], v155 offset:49152
	ds_read_b128 v[200:203], v155 offset:50176
	ds_read_b128 v[204:207], v155 offset:51200
	ds_read_b128 v[208:211], v155 offset:52224
	ds_read_b128 v[212:215], v155 offset:53248
	ds_read_b128 v[216:219], v155 offset:54272
	ds_read_b128 v[220:223], v155 offset:55296
	ds_read_b128 v[224:227], v155 offset:56320
	global_load_lds_dwordx4 v[144:145], off
	s_add_i32 m0, s26, 0x2000
	s_add_u32 s26, s40, 0x80080
	v_lshl_add_u64 v[144:145], v[228:229], 0, s[10:11]
	s_addc_u32 s27, s41, 0
	s_add_i32 s40, s56, s24
	global_load_lds_dwordx4 v[144:145], off
	v_lshl_add_u64 v[144:145], s[26:27], 0, v[174:175]
	s_mov_b32 m0, s40
	s_nop 0
	global_load_lds_dwordx4 v[144:145], off
	v_lshl_add_u64 v[144:145], s[26:27], 0, v[132:133]
	s_add_i32 m0, s40, 0x2000
	s_nop 0
	global_load_lds_dwordx4 v[144:145], off
	v_lshl_add_u64 v[144:145], v[230:231], 0, s[10:11]
	s_mov_b32 m0, s20
	s_nop 0
	global_load_lds_dwordx4 v[144:145], off
	v_lshl_add_u64 v[144:145], v[232:233], 0, s[10:11]
	s_mov_b32 m0, s45
	s_nop 0
	global_load_lds_dwordx4 v[144:145], off
	s_waitcnt vmcnt(8)
	s_waitcnt lgkmcnt(0)
	s_barrier
	s_waitcnt lgkmcnt(0)
	v_mfma_f32_16x16x32_bf16 v[64:67], v[148:151], v[196:199], v[64:67]
	v_mfma_f32_16x16x32_bf16 v[60:63], v[160:163], v[196:199], v[60:63]
	v_mfma_f32_16x16x32_bf16 v[52:55], v[148:151], v[204:207], v[52:55]
	v_mfma_f32_16x16x32_bf16 v[44:47], v[160:163], v[204:207], v[44:47]
	v_mfma_f32_16x16x32_bf16 v[36:39], v[148:151], v[212:215], v[36:39]
	v_mfma_f32_16x16x32_bf16 v[28:31], v[160:163], v[212:215], v[28:31]
	v_mfma_f32_16x16x32_bf16 v[20:23], v[148:151], v[220:223], v[20:23]
	v_mfma_f32_16x16x32_bf16 v[12:15], v[160:163], v[220:223], v[12:15]
	v_mfma_f32_16x16x32_bf16 v[64:67], v[156:159], v[200:203], v[64:67]
	v_mfma_f32_16x16x32_bf16 v[60:63], v[164:167], v[200:203], v[60:63]
	v_mfma_f32_16x16x32_bf16 v[52:55], v[156:159], v[208:211], v[52:55]
	v_mfma_f32_16x16x32_bf16 v[44:47], v[164:167], v[208:211], v[44:47]
	v_mfma_f32_16x16x32_bf16 v[36:39], v[156:159], v[216:219], v[36:39]
	v_mfma_f32_16x16x32_bf16 v[28:31], v[164:167], v[216:219], v[28:31]
	v_mfma_f32_16x16x32_bf16 v[20:23], v[156:159], v[224:227], v[20:23]
	v_mfma_f32_16x16x32_bf16 v[12:15], v[164:167], v[224:227], v[12:15]
	v_mfma_f32_16x16x32_bf16 v[56:59], v[168:171], v[196:199], v[56:59]
	v_mfma_f32_16x16x32_bf16 v[48:51], v[188:191], v[196:199], v[48:51]
	v_mfma_f32_16x16x32_bf16 v[40:43], v[168:171], v[204:207], v[40:43]
	v_mfma_f32_16x16x32_bf16 v[32:35], v[188:191], v[204:207], v[32:35]
	v_mfma_f32_16x16x32_bf16 v[24:27], v[168:171], v[212:215], v[24:27]
	v_mfma_f32_16x16x32_bf16 v[16:19], v[188:191], v[212:215], v[16:19]
	v_mfma_f32_16x16x32_bf16 v[8:11], v[168:171], v[220:223], v[8:11]
	v_mfma_f32_16x16x32_bf16 v[4:7], v[188:191], v[220:223], v[4:7]
	v_mfma_f32_16x16x32_bf16 v[56:59], v[184:187], v[200:203], v[56:59]
	v_mfma_f32_16x16x32_bf16 v[48:51], v[192:195], v[200:203], v[48:51]
	v_mfma_f32_16x16x32_bf16 v[40:43], v[184:187], v[208:211], v[40:43]
	v_mfma_f32_16x16x32_bf16 v[32:35], v[192:195], v[208:211], v[32:35]
	v_mfma_f32_16x16x32_bf16 v[24:27], v[184:187], v[216:219], v[24:27]
	v_mfma_f32_16x16x32_bf16 v[16:19], v[192:195], v[216:219], v[16:19]
	v_mfma_f32_16x16x32_bf16 v[8:11], v[184:187], v[224:227], v[8:11]
	v_mfma_f32_16x16x32_bf16 v[4:7], v[192:195], v[224:227], v[4:7]
	s_barrier
	s_add_i32 s54, s54, 2
	s_add_u32 s52, s52, 0x100
	s_addc_u32 s53, s53, 0
	s_add_u32 s38, s38, 0x100
	s_addc_u32 s39, s39, 0
	s_cmp_gt_u32 s54, 29
	s_cbranch_scc0 .LBB0_86
	s_and_b64 vcc, exec, s[16:17]
	s_cbranch_vccz .LBB0_89
	s_barrier

; #define PG8_STAGE(bufoff, gbase, voff) do { _Pragma("unroll") for (int _i = 0; _i < 2; ++_i) \
;         __builtin_amdgcn_global_load_lds((const unsigned*)((const char*)(gbase) + (voff)[_i]), (PG8_LAS unsigned*)(lds + (bufoff) + ldsw + _i * 8192), 16, 0, 0); } while (0)
; #define PG8_LDA(dst, b, h) do { _Pragma("unroll") for (int m = 0; m < 4; ++m) _Pragma("unroll") for (int k = 0; k < 2; ++k) dst[m][k] = *(const PG8_LAS bf16x8*)(lds + PG8_SA(b, h) + aoff + m * 2048 + k * 1024); } while (0)
; #define PG8_LDB(dst, b, h) do { _Pragma("unroll") for (int n = 0; n < 2; ++n) _Pragma("unroll") for (int k = 0; k < 2; ++k) dst[n][k] = *(const PG8_LAS bf16x8*)(lds + PG8_SB(b, h) + boff + n * 2048 + k * 1024); } while (0)
; #define PG8_SCHED __builtin_amdgcn_sched_barrier(0)
; template <class Epi, class Sched, bool ALIGN_EPI = false, bool SP2 = false>
; __device__ __forceinline__ void gemm_phase(PG8_LAS unsigned char* lds, const Gemm g, const Sched& S, const Epi& E) {
;     ...
;         const bool has_next = S.next(ui + 1, nxt);
;         const char* nA = has_next ? (const char*)g.A + (size_t)nxt.pm * tstep : cA; const char* nB = has_next ? (const char*)g.Bt + (size_t)nxt.pn * tstep : cB;
;         for (int t = 0; t < nt; t += 2) {
;             const bool last = (t == nt - 2);
;             const char* a1 = cA + (size_t)(t + 1) * kstep;
;             const char* a2 = last ? nA : cA + (size_t)(t + 2) * kstep; const char* b2 = last ? nB : cB + (size_t)(t + 2) * kstep;
;             const char* a3 = a2 + kstep; const char* b3 = b2 + kstep;
;             if (last && has_next) S.a_ready(nxt);
;             if constexpr (SP2) {
;             PG8_LDB(B0, 0, 0); PG8_LDB(B1, 0, 1); PG8_SCHED; PG8_LDA(At, 0, 0); PG8_STAGE(PG8_SA(1, 1), a1 + hstep, voffA);
;     ...
;         for (int a = 0; a < 2; ++a)
; #pragma unroll
;             for (int b = 0; b < 2; ++b)
; #pragma unroll
;                 for (int m = 0; m < 4; ++m)
; #pragma unroll
;                     for (int n = 0; n < 2; ++n) acc[a][b][m][n] = (f32x4){0.f, 0.f, 0.f, 0.f};
.LBB0_406:
	s_ashr_i32 s51, s50, 31
	s_lshl_b64 s[16:17], s[50:51], 20
	s_add_u32 s52, s19, s16
	s_addc_u32 s53, s20, s17
	s_and_b64 s[16:17], s[40:41], exec
	s_cselect_b32 s23, s53, s15
	s_cselect_b32 s24, s52, s14
	s_ashr_i32 s49, s48, 31
	s_lshl_b64 s[16:17], s[48:49], 20
	s_add_u32 s54, s26, s16
	s_addc_u32 s55, s27, s17
	s_and_b64 s[16:17], s[40:41], exec
	s_cselect_b32 s25, s55, s1
	s_cselect_b32 s49, s54, s0
	s_add_u32 s51, s0, 0x100
	s_addc_u32 s57, s1, 0
	s_add_u32 s0, s14, 0x80080
	v_mov_b32_e32 v4, 0
	s_addc_u32 s1, s15, 0
	s_mov_b32 s58, -2
	v_mov_b32_e32 v5, v4
	v_mov_b32_e32 v6, v4
	v_mov_b32_e32 v7, v4
	v_mov_b32_e32 v8, v4
	v_mov_b32_e32 v9, v4
	v_mov_b32_e32 v10, v4
	v_mov_b32_e32 v11, v4
	v_mov_b32_e32 v12, v4
	v_mov_b32_e32 v13, v4
	v_mov_b32_e32 v14, v4
	v_mov_b32_e32 v15, v4
	v_mov_b32_e32 v16, v4
	v_mov_b32_e32 v17, v4
	v_mov_b32_e32 v18, v4
	v_mov_b32_e32 v19, v4
	v_mov_b32_e32 v20, v4
	v_mov_b32_e32 v21, v4
	v_mov_b32_e32 v22, v4
	v_mov_b32_e32 v23, v4
	v_mov_b32_e32 v24, v4
	v_mov_b32_e32 v25, v4
	v_mov_b32_e32 v26, v4
	v_mov_b32_e32 v27, v4
	s_waitcnt vmcnt(0)
	v_mov_b32_e32 v28, v4
	v_mov_b32_e32 v29, v4
	v_mov_b32_e32 v30, v4
	v_mov_b32_e32 v31, v4
	v_mov_b32_e32 v32, v4
	v_mov_b32_e32 v33, v4
	v_mov_b32_e32 v34, v4
	v_mov_b32_e32 v35, v4
	v_mov_b32_e32 v68, v4
	v_mov_b32_e32 v69, v4
	v_mov_b32_e32 v70, v4
	v_mov_b32_e32 v71, v4
	v_mov_b32_e32 v72, v4
	v_mov_b32_e32 v73, v4
	v_mov_b32_e32 v74, v4
	v_mov_b32_e32 v75, v4
	v_mov_b32_e32 v76, v4
	v_mov_b32_e32 v77, v4
	v_mov_b32_e32 v78, v4
	v_mov_b32_e32 v79, v4
	v_mov_b32_e32 v80, v4
	v_mov_b32_e32 v81, v4
	v_mov_b32_e32 v82, v4
	v_mov_b32_e32 v83, v4
	v_mov_b32_e32 v84, v4
	v_mov_b32_e32 v85, v4
	v_mov_b32_e32 v86, v4
	v_mov_b32_e32 v87, v4
	v_mov_b32_e32 v88, v4
	v_mov_b32_e32 v89, v4
	v_mov_b32_e32 v90, v4
	v_mov_b32_e32 v91, v4
	v_mov_b32_e32 v92, v4
	v_mov_b32_e32 v93, v4
	v_mov_b32_e32 v94, v4
	v_mov_b32_e32 v95, v4
	v_mov_b32_e32 v96, v4
	v_mov_b32_e32 v97, v4
	v_mov_b32_e32 v98, v4
	v_mov_b32_e32 v99, v4
	v_mov_b32_e32 v36, v4
	v_mov_b32_e32 v37, v4
	v_mov_b32_e32 v38, v4
	v_mov_b32_e32 v39, v4
	v_mov_b32_e32 v40, v4
	v_mov_b32_e32 v41, v4
	v_mov_b32_e32 v42, v4
	v_mov_b32_e32 v43, v4
	v_mov_b32_e32 v44, v4
	v_mov_b32_e32 v45, v4
	v_mov_b32_e32 v46, v4
	v_mov_b32_e32 v47, v4
	v_mov_b32_e32 v48, v4
	v_mov_b32_e32 v49, v4
	v_mov_b32_e32 v50, v4
	v_mov_b32_e32 v51, v4
	v_mov_b32_e32 v52, v4
	v_mov_b32_e32 v53, v4
	v_mov_b32_e32 v54, v4
	v_mov_b32_e32 v55, v4
	v_mov_b32_e32 v56, v4
	v_mov_b32_e32 v57, v4
	v_mov_b32_e32 v58, v4
	v_mov_b32_e32 v59, v4
	v_mov_b32_e32 v60, v4
	v_mov_b32_e32 v61, v4
	v_mov_b32_e32 v62, v4
	v_mov_b32_e32 v63, v4
	v_mov_b32_e32 v64, v4
	v_mov_b32_e32 v65, v4
	v_mov_b32_e32 v66, v4
	v_mov_b32_e32 v67, v4
	v_mov_b32_e32 v108, v4
	v_mov_b32_e32 v109, v4
	v_mov_b32_e32 v110, v4
	v_mov_b32_e32 v111, v4
	v_mov_b32_e32 v112, v4
	v_mov_b32_e32 v113, v4
	v_mov_b32_e32 v114, v4
	v_mov_b32_e32 v115, v4
	v_mov_b32_e32 v116, v4
	v_mov_b32_e32 v117, v4
	v_mov_b32_e32 v118, v4
	v_mov_b32_e32 v119, v4
	v_mov_b32_e32 v120, v4
	v_mov_b32_e32 v121, v4
	v_mov_b32_e32 v122, v4
	v_mov_b32_e32 v123, v4
	v_mov_b32_e32 v124, v4
	v_mov_b32_e32 v125, v4
	v_mov_b32_e32 v126, v4
	v_mov_b32_e32 v127, v4
	v_mov_b32_e32 v128, v4
	v_mov_b32_e32 v129, v4
	v_mov_b32_e32 v130, v4
	v_mov_b32_e32 v131, v4
	v_mov_b32_e32 v132, v4
	v_mov_b32_e32 v133, v4
	v_mov_b32_e32 v134, v4
	v_mov_b32_e32 v135, v4
	v_mov_b32_e32 v136, v4
	v_mov_b32_e32 v137, v4
	v_mov_b32_e32 v138, v4
	v_mov_b32_e32 v139, v4
	v_readfirstlane_b32 s101, v172
	s_nop 3
	s_cmp_ge_u32 s101, 0x100
	s_cbranch_scc1 .Lprio_hi_407
	s_setprio 1
	s_branch .Lprio_done_407
.Lprio_hi_407:
	s_setprio 0
.Lprio_done_407:
.LBB0_407:
	s_add_u32 s14, s0, 0xfff80080
	s_addc_u32 s15, s1, -1
	s_add_i32 s59, 0, 0x10000
	s_cmp_eq_u32 s58, 28
	s_cselect_b32 s17, s23, s15
	s_cselect_b32 s16, s24, s14
	s_cselect_b32 s15, s25, s57
	s_cselect_b32 s14, s49, s51
	s_add_i32 s62, 0, 0x14000
	v_add_u32_e32 v154, s59, v171
	v_add_u32_e32 v185, s62, v171
	ds_read_b128 v[100:103], v154
	ds_read_b128 v[104:107], v154 offset:1024
	ds_read_b128 v[140:143], v154 offset:2048
	ds_read_b128 v[154:157], v154 offset:3072
	ds_read_b128 v[158:161], v185
	ds_read_b128 v[162:165], v185 offset:1024
	ds_read_b128 v[166:169], v185 offset:2048
	ds_read_b128 v[186:189], v185 offset:3072
	v_lshl_add_u64 v[222:223], s[0:1], 0, v[152:153]
	s_add_i32 m0, s29, 0xc000
	ds_read_b128 v[190:193], v184
	ds_read_b128 v[194:197], v184 offset:1024
	ds_read_b128 v[198:201], v184 offset:2048
	ds_read_b128 v[202:205], v184 offset:3072
	ds_read_b128 v[206:209], v184 offset:4096
	ds_read_b128 v[210:213], v184 offset:5120
	ds_read_b128 v[214:217], v184 offset:6144
	ds_read_b128 v[218:221], v184 offset:7168
	global_load_lds_dwordx4 v[222:223], off
	v_lshl_add_u64 v[222:223], s[0:1], 0, v[150:151]
	s_add_i32 m0, s29, 0xe000
	s_nop 0
	global_load_lds_dwordx4 v[222:223], off
	s_waitcnt vmcnt(8)
	s_waitcnt lgkmcnt(0)
	s_barrier
; #define PG8_STAGE(bufoff, gbase, voff) do { _Pragma("unroll") for (int _i = 0; _i < 2; ++_i) \
;         __builtin_amdgcn_global_load_lds((const unsigned*)((const char*)(gbase) + (voff)[_i]), (PG8_LAS unsigned*)(lds + (bufoff) + ldsw + _i * 8192), 16, 0, 0); } while (0)
; #define PG8_LDA(dst, b, h) do { _Pragma("unroll") for (int m = 0; m < 4; ++m) _Pragma("unroll") for (int k = 0; k < 2; ++k) dst[m][k] = *(const PG8_LAS bf16x8*)(lds + PG8_SA(b, h) + aoff + m * 2048 + k * 1024); } while (0)
; #define PG8_MMA(ai, bj, At, Bt) do { __builtin_amdgcn_s_setprio(1); _Pragma("unroll") for (int m = 0; m < 4; ++m) _Pragma("unroll") for (int n = 0; n < 2; ++n) _Pragma("unroll") for (int k = 0; k < 2; ++k) \
;         acc[ai][bj][m][n] = __builtin_amdgcn_mfma_f32_16x16x32_bf16(Bt[n][k], At[m][k], acc[ai][bj][m][n], 0, 0, 0); __builtin_amdgcn_s_setprio(0); } while (0)
; #define PG8_WAIT_V(n) asm volatile("s_waitcnt vmcnt(" #n ")" ::: "memory")
; #define PG8_WAIT_L(n) asm volatile("s_waitcnt lgkmcnt(" #n ")" ::: "memory")
; #define PG8_BAR __builtin_amdgcn_s_barrier()
; #define PG8_SCHED __builtin_amdgcn_sched_barrier(0)
; template <class Epi, class Sched, bool ALIGN_EPI = false, bool SP2 = false>
; __device__ __forceinline__ void gemm_phase(PG8_LAS unsigned char* lds, const Gemm g, const Sched& S, const Epi& E) {
;     ...
;             PG8_WAIT_V(8); PG8_WAIT_L(0); PG8_BAR; PG8_MMA(0, 0, At, B0); PG8_MMA(0, 1, At, B1); PG8_BAR; PG8_SCHED;
;             PG8_LDA(At, 0, 1); PG8_STAGE(PG8_SB(0, 0), b2, voffB); PG8_STAGE(PG8_SB(0, 1), b2 + hstep, voffB); PG8_STAGE(PG8_SA(0, 0), a2, voffA);
;             PG8_WAIT_V(8); PG8_WAIT_L(0); PG8_BAR; PG8_MMA(1, 0, At, B0); PG8_MMA(1, 1, At, B1); PG8_BAR; PG8_SCHED;
	s_waitcnt lgkmcnt(0)
	v_mfma_f32_16x16x32_bf16 v[136:139], v[100:103], v[190:193], v[136:139]
	v_mfma_f32_16x16x32_bf16 v[132:135], v[140:143], v[190:193], v[132:135]
	v_mfma_f32_16x16x32_bf16 v[128:131], v[100:103], v[198:201], v[128:131]
	v_mfma_f32_16x16x32_bf16 v[124:127], v[140:143], v[198:201], v[124:127]
	v_mfma_f32_16x16x32_bf16 v[120:123], v[100:103], v[206:209], v[120:123]
	v_mfma_f32_16x16x32_bf16 v[116:119], v[140:143], v[206:209], v[116:119]
	v_mfma_f32_16x16x32_bf16 v[112:115], v[100:103], v[214:217], v[112:115]
	v_mfma_f32_16x16x32_bf16 v[108:111], v[140:143], v[214:217], v[108:111]
	v_mfma_f32_16x16x32_bf16 v[136:139], v[104:107], v[194:197], v[136:139]
	v_mfma_f32_16x16x32_bf16 v[132:135], v[154:157], v[194:197], v[132:135]
	v_mfma_f32_16x16x32_bf16 v[128:131], v[104:107], v[202:205], v[128:131]
	v_mfma_f32_16x16x32_bf16 v[124:127], v[154:157], v[202:205], v[124:127]
	v_mfma_f32_16x16x32_bf16 v[120:123], v[104:107], v[210:213], v[120:123]
	v_mfma_f32_16x16x32_bf16 v[116:119], v[154:157], v[210:213], v[116:119]
	v_mfma_f32_16x16x32_bf16 v[112:115], v[104:107], v[218:221], v[112:115]
	v_mfma_f32_16x16x32_bf16 v[108:111], v[154:157], v[218:221], v[108:111]
	v_mfma_f32_16x16x32_bf16 v[64:67], v[158:161], v[190:193], v[64:67]
	v_mfma_f32_16x16x32_bf16 v[60:63], v[166:169], v[190:193], v[60:63]
	v_mfma_f32_16x16x32_bf16 v[56:59], v[158:161], v[198:201], v[56:59]
	v_mfma_f32_16x16x32_bf16 v[52:55], v[166:169], v[198:201], v[52:55]
	v_mfma_f32_16x16x32_bf16 v[48:51], v[158:161], v[206:209], v[48:51]
	v_mfma_f32_16x16x32_bf16 v[44:47], v[166:169], v[206:209], v[44:47]
	v_mfma_f32_16x16x32_bf16 v[40:43], v[158:161], v[214:217], v[40:43]
	v_mfma_f32_16x16x32_bf16 v[36:39], v[166:169], v[214:217], v[36:39]
	v_mfma_f32_16x16x32_bf16 v[64:67], v[162:165], v[194:197], v[64:67]
	v_mfma_f32_16x16x32_bf16 v[60:63], v[186:189], v[194:197], v[60:63]
	v_mfma_f32_16x16x32_bf16 v[56:59], v[162:165], v[202:205], v[56:59]
	v_mfma_f32_16x16x32_bf16 v[52:55], v[186:189], v[202:205], v[52:55]
	v_mfma_f32_16x16x32_bf16 v[48:51], v[162:165], v[210:213], v[48:51]
	v_mfma_f32_16x16x32_bf16 v[44:47], v[186:189], v[210:213], v[44:47]
	v_mfma_f32_16x16x32_bf16 v[40:43], v[162:165], v[218:221], v[40:43]
	v_mfma_f32_16x16x32_bf16 v[36:39], v[186:189], v[218:221], v[36:39]
	s_barrier
	s_add_i32 s59, s59, s28
	v_lshl_add_u64 v[222:223], s[14:15], 0, v[174:175]
	s_mov_b32 m0, s59
	ds_read_b128 v[190:193], v184 offset:16384
	ds_read_b128 v[194:197], v184 offset:17408
	ds_read_b128 v[198:201], v184 offset:18432
	ds_read_b128 v[202:205], v184 offset:19456
	ds_read_b128 v[206:209], v184 offset:20480
	ds_read_b128 v[210:213], v184 offset:21504
	ds_read_b128 v[214:217], v184 offset:22528
	ds_read_b128 v[218:221], v184 offset:23552
	global_load_lds_dwordx4 v[222:223], off
	s_add_i32 m0, s59, 0x2000
	s_add_u32 s60, s14, 0x80000
	v_lshl_add_u64 v[224:225], s[14:15], 0, v[144:145]
	s_addc_u32 s61, s15, 0
	s_add_i32 s59, s62, s28
	global_load_lds_dwordx4 v[224:225], off
	v_lshl_add_u64 v[226:227], s[60:61], 0, v[174:175]
	s_mov_b32 m0, s59
	v_lshl_add_u64 v[228:229], s[16:17], 0, v[146:147]
	global_load_lds_dwordx4 v[226:227], off
	v_lshl_add_u64 v[226:227], s[60:61], 0, v[144:145]
	s_add_i32 m0, s59, 0x2000
	s_nop 0
	global_load_lds_dwordx4 v[226:227], off
	v_lshl_add_u64 v[226:227], s[16:17], 0, v[148:149]
	s_mov_b32 m0, s29
	s_nop 0
	global_load_lds_dwordx4 v[226:227], off
	s_mov_b32 m0, s30
	s_nop 0
	global_load_lds_dwordx4 v[228:229], off
	s_waitcnt vmcnt(8)
	s_waitcnt lgkmcnt(0)
	s_barrier
	s_waitcnt lgkmcnt(0)
	v_mfma_f32_16x16x32_bf16 v[96:99], v[100:103], v[190:193], v[96:99]
	v_mfma_f32_16x16x32_bf16 v[92:95], v[140:143], v[190:193], v[92:95]
	v_mfma_f32_16x16x32_bf16 v[88:91], v[100:103], v[198:201], v[88:91]
	v_mfma_f32_16x16x32_bf16 v[84:87], v[140:143], v[198:201], v[84:87]
	v_mfma_f32_16x16x32_bf16 v[80:83], v[100:103], v[206:209], v[80:83]
	v_mfma_f32_16x16x32_bf16 v[76:79], v[140:143], v[206:209], v[76:79]
	v_mfma_f32_16x16x32_bf16 v[72:75], v[100:103], v[214:217], v[72:75]
	v_mfma_f32_16x16x32_bf16 v[68:71], v[140:143], v[214:217], v[68:71]
	v_mfma_f32_16x16x32_bf16 v[96:99], v[104:107], v[194:197], v[96:99]
	v_mfma_f32_16x16x32_bf16 v[92:95], v[154:157], v[194:197], v[92:95]
	v_mfma_f32_16x16x32_bf16 v[88:91], v[104:107], v[202:205], v[88:91]
	v_mfma_f32_16x16x32_bf16 v[84:87], v[154:157], v[202:205], v[84:87]
	v_mfma_f32_16x16x32_bf16 v[80:83], v[104:107], v[210:213], v[80:83]
	v_mfma_f32_16x16x32_bf16 v[76:79], v[154:157], v[210:213], v[76:79]
	v_mfma_f32_16x16x32_bf16 v[72:75], v[104:107], v[218:221], v[72:75]
	v_mfma_f32_16x16x32_bf16 v[68:71], v[154:157], v[218:221], v[68:71]
	v_mfma_f32_16x16x32_bf16 v[32:35], v[158:161], v[190:193], v[32:35]
	v_mfma_f32_16x16x32_bf16 v[28:31], v[166:169], v[190:193], v[28:31]
	v_mfma_f32_16x16x32_bf16 v[24:27], v[158:161], v[198:201], v[24:27]
	v_mfma_f32_16x16x32_bf16 v[20:23], v[166:169], v[198:201], v[20:23]
	v_mfma_f32_16x16x32_bf16 v[16:19], v[158:161], v[206:209], v[16:19]
	v_mfma_f32_16x16x32_bf16 v[12:15], v[166:169], v[206:209], v[12:15]
	v_mfma_f32_16x16x32_bf16 v[8:11], v[158:161], v[214:217], v[8:11]
	v_mfma_f32_16x16x32_bf16 v[4:7], v[166:169], v[214:217], v[4:7]
	v_mfma_f32_16x16x32_bf16 v[32:35], v[162:165], v[194:197], v[32:35]
	v_mfma_f32_16x16x32_bf16 v[28:31], v[186:189], v[194:197], v[28:31]
	v_mfma_f32_16x16x32_bf16 v[24:27], v[162:165], v[202:205], v[24:27]
	v_mfma_f32_16x16x32_bf16 v[20:23], v[186:189], v[202:205], v[20:23]
	v_mfma_f32_16x16x32_bf16 v[16:19], v[162:165], v[210:213], v[16:19]
	v_mfma_f32_16x16x32_bf16 v[12:15], v[186:189], v[210:213], v[12:15]
	v_mfma_f32_16x16x32_bf16 v[8:11], v[162:165], v[218:221], v[8:11]
	v_mfma_f32_16x16x32_bf16 v[4:7], v[186:189], v[218:221], v[4:7]
	s_barrier
; #define PG8_STAGE(bufoff, gbase, voff) do { _Pragma("unroll") for (int _i = 0; _i < 2; ++_i) \
;         __builtin_amdgcn_global_load_lds((const unsigned*)((const char*)(gbase) + (voff)[_i]), (PG8_LAS unsigned*)(lds + (bufoff) + ldsw + _i * 8192), 16, 0, 0); } while (0)
; #define PG8_LDA(dst, b, h) do { _Pragma("unroll") for (int m = 0; m < 4; ++m) _Pragma("unroll") for (int k = 0; k < 2; ++k) dst[m][k] = *(const PG8_LAS bf16x8*)(lds + PG8_SA(b, h) + aoff + m * 2048 + k * 1024); } while (0)
; #define PG8_LDB(dst, b, h) do { _Pragma("unroll") for (int n = 0; n < 2; ++n) _Pragma("unroll") for (int k = 0; k < 2; ++k) dst[n][k] = *(const PG8_LAS bf16x8*)(lds + PG8_SB(b, h) + boff + n * 2048 + k * 1024); } while (0)
; #define PG8_MMA(ai, bj, At, Bt) do { __builtin_amdgcn_s_setprio(1); _Pragma("unroll") for (int m = 0; m < 4; ++m) _Pragma("unroll") for (int n = 0; n < 2; ++n) _Pragma("unroll") for (int k = 0; k < 2; ++k) \
;         acc[ai][bj][m][n] = __builtin_amdgcn_mfma_f32_16x16x32_bf16(Bt[n][k], At[m][k], acc[ai][bj][m][n], 0, 0, 0); __builtin_amdgcn_s_setprio(0); } while (0)
; #define PG8_WAIT_V(n) asm volatile("s_waitcnt vmcnt(" #n ")" ::: "memory")
; #define PG8_WAIT_L(n) asm volatile("s_waitcnt lgkmcnt(" #n ")" ::: "memory")
; #define PG8_BAR __builtin_amdgcn_s_barrier()
; #define PG8_SCHED __builtin_amdgcn_sched_barrier(0)
; template <class Epi, class Sched, bool ALIGN_EPI = false, bool SP2 = false>
; __device__ __forceinline__ void gemm_phase(PG8_LAS unsigned char* lds, const Gemm g, const Sched& S, const Epi& E) {
;     ...
;             PG8_LDB(B0, 1, 0); PG8_LDB(B1, 1, 1); PG8_SCHED; PG8_LDA(At, 1, 0); PG8_STAGE(PG8_SA(0, 1), a2 + hstep, voffA);
;             PG8_WAIT_V(8); PG8_WAIT_L(0); PG8_BAR; PG8_MMA(0, 0, At, B0); PG8_MMA(0, 1, At, B1); PG8_BAR; PG8_SCHED;
	s_add_i32 s59, 0, 0x18000
	s_add_i32 s60, 0, 0x1c000
	v_add_u32_e32 v154, s59, v171
	v_add_u32_e32 v185, s60, v171
	ds_read_b128 v[100:103], v154
	ds_read_b128 v[104:107], v154 offset:1024
	ds_read_b128 v[140:143], v154 offset:2048
	ds_read_b128 v[154:157], v154 offset:3072
	ds_read_b128 v[158:161], v185
	ds_read_b128 v[162:165], v185 offset:1024
	ds_read_b128 v[166:169], v185 offset:2048
	ds_read_b128 v[186:189], v185 offset:3072
	s_add_u32 s16, s16, 0x80000
	s_addc_u32 s17, s17, 0
	s_mov_b32 m0, s31
	v_lshl_add_u64 v[230:231], s[16:17], 0, v[148:149]
	ds_read_b128 v[190:193], v184 offset:32768
	ds_read_b128 v[194:197], v184 offset:33792
	ds_read_b128 v[198:201], v184 offset:34816
	ds_read_b128 v[202:205], v184 offset:35840
	ds_read_b128 v[206:209], v184 offset:36864
	ds_read_b128 v[210:213], v184 offset:37888
	ds_read_b128 v[214:217], v184 offset:38912
	ds_read_b128 v[218:221], v184 offset:39936
	global_load_lds_dwordx4 v[230:231], off
	v_lshl_add_u64 v[230:231], s[16:17], 0, v[146:147]
	s_mov_b32 m0, s34
	s_nop 0
	global_load_lds_dwordx4 v[230:231], off
	s_waitcnt vmcnt(8)
	s_waitcnt lgkmcnt(0)
	s_barrier
	s_waitcnt lgkmcnt(0)
	v_mfma_f32_16x16x32_bf16 v[136:139], v[100:103], v[190:193], v[136:139]
	v_mfma_f32_16x16x32_bf16 v[132:135], v[140:143], v[190:193], v[132:135]
	v_mfma_f32_16x16x32_bf16 v[128:131], v[100:103], v[198:201], v[128:131]
	v_mfma_f32_16x16x32_bf16 v[124:127], v[140:143], v[198:201], v[124:127]
	v_mfma_f32_16x16x32_bf16 v[120:123], v[100:103], v[206:209], v[120:123]
	v_mfma_f32_16x16x32_bf16 v[116:119], v[140:143], v[206:209], v[116:119]
	v_mfma_f32_16x16x32_bf16 v[112:115], v[100:103], v[214:217], v[112:115]
	v_mfma_f32_16x16x32_bf16 v[108:111], v[140:143], v[214:217], v[108:111]
	v_mfma_f32_16x16x32_bf16 v[136:139], v[104:107], v[194:197], v[136:139]
	v_mfma_f32_16x16x32_bf16 v[132:135], v[154:157], v[194:197], v[132:135]
	v_mfma_f32_16x16x32_bf16 v[128:131], v[104:107], v[202:205], v[128:131]
	v_mfma_f32_16x16x32_bf16 v[124:127], v[154:157], v[202:205], v[124:127]
	v_mfma_f32_16x16x32_bf16 v[120:123], v[104:107], v[210:213], v[120:123]
	v_mfma_f32_16x16x32_bf16 v[116:119], v[154:157], v[210:213], v[116:119]
	v_mfma_f32_16x16x32_bf16 v[112:115], v[104:107], v[218:221], v[112:115]
	v_mfma_f32_16x16x32_bf16 v[108:111], v[154:157], v[218:221], v[108:111]
	v_mfma_f32_16x16x32_bf16 v[64:67], v[158:161], v[190:193], v[64:67]
	v_mfma_f32_16x16x32_bf16 v[60:63], v[166:169], v[190:193], v[60:63]
	v_mfma_f32_16x16x32_bf16 v[56:59], v[158:161], v[198:201], v[56:59]
	v_mfma_f32_16x16x32_bf16 v[52:55], v[166:169], v[198:201], v[52:55]
	v_mfma_f32_16x16x32_bf16 v[48:51], v[158:161], v[206:209], v[48:51]
	v_mfma_f32_16x16x32_bf16 v[44:47], v[166:169], v[206:209], v[44:47]
	v_mfma_f32_16x16x32_bf16 v[40:43], v[158:161], v[214:217], v[40:43]
	v_mfma_f32_16x16x32_bf16 v[36:39], v[166:169], v[214:217], v[36:39]
	v_mfma_f32_16x16x32_bf16 v[64:67], v[162:165], v[194:197], v[64:67]
	v_mfma_f32_16x16x32_bf16 v[60:63], v[186:189], v[194:197], v[60:63]
	v_mfma_f32_16x16x32_bf16 v[56:59], v[162:165], v[202:205], v[56:59]
	v_mfma_f32_16x16x32_bf16 v[52:55], v[186:189], v[202:205], v[52:55]
	v_mfma_f32_16x16x32_bf16 v[48:51], v[162:165], v[210:213], v[48:51]
	v_mfma_f32_16x16x32_bf16 v[44:47], v[186:189], v[210:213], v[44:47]
	v_mfma_f32_16x16x32_bf16 v[40:43], v[162:165], v[218:221], v[40:43]
	v_mfma_f32_16x16x32_bf16 v[36:39], v[186:189], v[218:221], v[36:39]
	s_barrier
; #define PG8_STAGE(bufoff, gbase, voff) do { _Pragma("unroll") for (int _i = 0; _i < 2; ++_i) \
;         __builtin_amdgcn_global_load_lds((const unsigned*)((const char*)(gbase) + (voff)[_i]), (PG8_LAS unsigned*)(lds + (bufoff) + ldsw + _i * 8192), 16, 0, 0); } while (0)
; #define PG8_LDA(dst, b, h) do { _Pragma("unroll") for (int m = 0; m < 4; ++m) _Pragma("unroll") for (int k = 0; k < 2; ++k) dst[m][k] = *(const PG8_LAS bf16x8*)(lds + PG8_SA(b, h) + aoff + m * 2048 + k * 1024); } while (0)
; #define PG8_MMA(ai, bj, At, Bt) do { __builtin_amdgcn_s_setprio(1); _Pragma("unroll") for (int m = 0; m < 4; ++m) _Pragma("unroll") for (int n = 0; n < 2; ++n) _Pragma("unroll") for (int k = 0; k < 2; ++k) \
;         acc[ai][bj][m][n] = __builtin_amdgcn_mfma_f32_16x16x32_bf16(Bt[n][k], At[m][k], acc[ai][bj][m][n], 0, 0, 0); __builtin_amdgcn_s_setprio(0); } while (0)
; #define PG8_WAIT_V(n) asm volatile("s_waitcnt vmcnt(" #n ")" ::: "memory")
; #define PG8_WAIT_L(n) asm volatile("s_waitcnt lgkmcnt(" #n ")" ::: "memory")
; #define PG8_BAR __builtin_amdgcn_s_barrier()
; #define PG8_SCHED __builtin_amdgcn_sched_barrier(0)
; template <class Epi, class Sched, bool ALIGN_EPI = false, bool SP2 = false>
; __device__ __forceinline__ void gemm_phase(PG8_LAS unsigned char* lds, const Gemm g, const Sched& S, const Epi& E) {
;     ...
;             PG8_LDA(At, 1, 1); PG8_STAGE(PG8_SB(1, 0), b3, voffB); PG8_STAGE(PG8_SB(1, 1), b3 + hstep, voffB); PG8_STAGE(PG8_SA(1, 0), a3, voffA);
;             PG8_WAIT_V(8); PG8_WAIT_L(0); PG8_BAR; PG8_MMA(1, 0, At, B0); PG8_MMA(1, 1, At, B1); PG8_BAR; PG8_SCHED;
	s_add_i32 s16, s59, s28
	v_lshl_add_u64 v[222:223], v[222:223], 0, s[10:11]
	s_mov_b32 m0, s16
	ds_read_b128 v[190:193], v184 offset:49152
	ds_read_b128 v[194:197], v184 offset:50176
	ds_read_b128 v[198:201], v184 offset:51200
	ds_read_b128 v[202:205], v184 offset:52224
	ds_read_b128 v[206:209], v184 offset:53248
	ds_read_b128 v[210:213], v184 offset:54272
	ds_read_b128 v[214:217], v184 offset:55296
	ds_read_b128 v[218:221], v184 offset:56320
	global_load_lds_dwordx4 v[222:223], off
	s_add_i32 m0, s16, 0x2000
	s_add_u32 s14, s14, 0x80080
	v_lshl_add_u64 v[222:223], v[224:225], 0, s[10:11]
	s_addc_u32 s15, s15, 0
	s_add_i32 s16, s60, s28
	global_load_lds_dwordx4 v[222:223], off
	v_lshl_add_u64 v[222:223], s[14:15], 0, v[174:175]
	s_mov_b32 m0, s16
	s_nop 0
	global_load_lds_dwordx4 v[222:223], off
	v_lshl_add_u64 v[222:223], s[14:15], 0, v[144:145]
	s_add_i32 m0, s16, 0x2000
	s_nop 0
	global_load_lds_dwordx4 v[222:223], off
	v_lshl_add_u64 v[222:223], v[226:227], 0, s[10:11]
	s_mov_b32 m0, s35
	s_nop 0
	global_load_lds_dwordx4 v[222:223], off
	v_lshl_add_u64 v[222:223], v[228:229], 0, s[10:11]
	s_mov_b32 m0, s38
	s_nop 0
	global_load_lds_dwordx4 v[222:223], off
	s_waitcnt vmcnt(8)
	s_waitcnt lgkmcnt(0)
	s_barrier
	s_waitcnt lgkmcnt(0)
	v_mfma_f32_16x16x32_bf16 v[96:99], v[100:103], v[190:193], v[96:99]
	v_mfma_f32_16x16x32_bf16 v[92:95], v[140:143], v[190:193], v[92:95]
	v_mfma_f32_16x16x32_bf16 v[88:91], v[100:103], v[198:201], v[88:91]
	v_mfma_f32_16x16x32_bf16 v[84:87], v[140:143], v[198:201], v[84:87]
	v_mfma_f32_16x16x32_bf16 v[80:83], v[100:103], v[206:209], v[80:83]
	v_mfma_f32_16x16x32_bf16 v[76:79], v[140:143], v[206:209], v[76:79]
	v_mfma_f32_16x16x32_bf16 v[72:75], v[100:103], v[214:217], v[72:75]
	v_mfma_f32_16x16x32_bf16 v[68:71], v[140:143], v[214:217], v[68:71]
	v_mfma_f32_16x16x32_bf16 v[96:99], v[104:107], v[194:197], v[96:99]
	v_mfma_f32_16x16x32_bf16 v[92:95], v[154:157], v[194:197], v[92:95]
	v_mfma_f32_16x16x32_bf16 v[88:91], v[104:107], v[202:205], v[88:91]
	v_mfma_f32_16x16x32_bf16 v[84:87], v[154:157], v[202:205], v[84:87]
	v_mfma_f32_16x16x32_bf16 v[80:83], v[104:107], v[210:213], v[80:83]
	v_mfma_f32_16x16x32_bf16 v[76:79], v[154:157], v[210:213], v[76:79]
	v_mfma_f32_16x16x32_bf16 v[72:75], v[104:107], v[218:221], v[72:75]
	v_mfma_f32_16x16x32_bf16 v[68:71], v[154:157], v[218:221], v[68:71]
	v_mfma_f32_16x16x32_bf16 v[32:35], v[158:161], v[190:193], v[32:35]
	v_mfma_f32_16x16x32_bf16 v[28:31], v[166:169], v[190:193], v[28:31]
	v_mfma_f32_16x16x32_bf16 v[24:27], v[158:161], v[198:201], v[24:27]
	v_mfma_f32_16x16x32_bf16 v[20:23], v[166:169], v[198:201], v[20:23]
	v_mfma_f32_16x16x32_bf16 v[16:19], v[158:161], v[206:209], v[16:19]
	v_mfma_f32_16x16x32_bf16 v[12:15], v[166:169], v[206:209], v[12:15]
	v_mfma_f32_16x16x32_bf16 v[8:11], v[158:161], v[214:217], v[8:11]
	v_mfma_f32_16x16x32_bf16 v[4:7], v[166:169], v[214:217], v[4:7]
	v_mfma_f32_16x16x32_bf16 v[32:35], v[162:165], v[194:197], v[32:35]
	v_mfma_f32_16x16x32_bf16 v[28:31], v[186:189], v[194:197], v[28:31]
	v_mfma_f32_16x16x32_bf16 v[24:27], v[162:165], v[202:205], v[24:27]
	v_mfma_f32_16x16x32_bf16 v[20:23], v[186:189], v[202:205], v[20:23]
	v_mfma_f32_16x16x32_bf16 v[16:19], v[162:165], v[210:213], v[16:19]
	v_mfma_f32_16x16x32_bf16 v[12:15], v[186:189], v[210:213], v[12:15]
	v_mfma_f32_16x16x32_bf16 v[8:11], v[162:165], v[218:221], v[8:11]
	v_mfma_f32_16x16x32_bf16 v[4:7], v[186:189], v[218:221], v[4:7]
	s_barrier
	s_add_i32 s58, s58, 2
	s_add_u32 s51, s51, 0x100
	s_addc_u32 s57, s57, 0
	s_add_u32 s0, s0, 0x100
	s_addc_u32 s1, s1, 0
	s_cmp_gt_u32 s58, 29
	s_cbranch_scc0 .LBB0_407
	s_and_b64 vcc, exec, s[46:47]
	s_cbranch_vccz .LBB0_410
	s_barrier

; #define PG8_STAGE(bufoff, gbase, voff) do { _Pragma("unroll") for (int _i = 0; _i < 2; ++_i) \
;         __builtin_amdgcn_global_load_lds((const unsigned*)((const char*)(gbase) + (voff)[_i]), (PG8_LAS unsigned*)(lds + (bufoff) + ldsw + _i * 8192), 16, 0, 0); } while (0)
; #define PG8_LDA(dst, b, h) do { _Pragma("unroll") for (int m = 0; m < 4; ++m) _Pragma("unroll") for (int k = 0; k < 2; ++k) dst[m][k] = *(const PG8_LAS bf16x8*)(lds + PG8_SA(b, h) + aoff + m * 2048 + k * 1024); } while (0)
; #define PG8_LDB(dst, b, h) do { _Pragma("unroll") for (int n = 0; n < 2; ++n) _Pragma("unroll") for (int k = 0; k < 2; ++k) dst[n][k] = *(const PG8_LAS bf16x8*)(lds + PG8_SB(b, h) + boff + n * 2048 + k * 1024); } while (0)
; #define PG8_SCHED __builtin_amdgcn_sched_barrier(0)
; template <class Epi, class Sched, bool ALIGN_EPI = false, bool SP2 = false>
; __device__ __forceinline__ void gemm_phase(PG8_LAS unsigned char* lds, const Gemm g, const Sched& S, const Epi& E) {
;     ...
;         const bool has_next = S.next(ui + 1, nxt);
;         const char* nA = has_next ? (const char*)g.A + (size_t)nxt.pm * tstep : cA; const char* nB = has_next ? (const char*)g.Bt + (size_t)nxt.pn * tstep : cB;
;         for (int t = 0; t < nt; t += 2) {
;             const bool last = (t == nt - 2);
;             const char* a1 = cA + (size_t)(t + 1) * kstep;
;             const char* a2 = last ? nA : cA + (size_t)(t + 2) * kstep; const char* b2 = last ? nB : cB + (size_t)(t + 2) * kstep;
;             const char* a3 = a2 + kstep; const char* b3 = b2 + kstep;
;             if (last && has_next) S.a_ready(nxt);
;             if constexpr (SP2) {
;             PG8_LDB(B0, 0, 0); PG8_LDB(B1, 0, 1); PG8_SCHED; PG8_LDA(At, 0, 0); PG8_STAGE(PG8_SA(1, 1), a1 + hstep, voffA);
;     ...
;         for (int a = 0; a < 2; ++a)
; #pragma unroll
;             for (int b = 0; b < 2; ++b)
; #pragma unroll
;                 for (int m = 0; m < 4; ++m)
; #pragma unroll
;                     for (int n = 0; n < 2; ++n) acc[a][b][m][n] = (f32x4){0.f, 0.f, 0.f, 0.f};
.LBB0_484:
	s_ashr_i32 s53, s52, 31
	s_lshl_b64 s[16:17], s[52:53], 21
	s_add_u32 s54, s19, s16
	s_addc_u32 s55, s20, s17
	s_and_b64 s[16:17], s[40:41], exec
	s_cselect_b32 s23, s55, s15
	s_cselect_b32 s24, s54, s14
	s_ashr_i32 s51, s50, 31
	s_lshl_b64 s[16:17], s[50:51], 21
	s_add_u32 s56, s26, s16
	s_addc_u32 s57, s27, s17
	s_and_b64 s[16:17], s[40:41], exec
	s_cselect_b32 s25, s57, s1
	s_cselect_b32 s51, s56, s0
	s_add_u32 s53, s0, 0x100
	s_addc_u32 s59, s1, 0
	s_add_u32 s0, s14, 0x100080
	v_mov_b32_e32 v4, 0
	s_addc_u32 s1, s15, 0
	s_mov_b32 s60, -2
	v_mov_b32_e32 v5, v4
	v_mov_b32_e32 v6, v4
	v_mov_b32_e32 v7, v4
	v_mov_b32_e32 v8, v4
	v_mov_b32_e32 v9, v4
	v_mov_b32_e32 v10, v4
	v_mov_b32_e32 v11, v4
	v_mov_b32_e32 v12, v4
	v_mov_b32_e32 v13, v4
	v_mov_b32_e32 v14, v4
	v_mov_b32_e32 v15, v4
	v_mov_b32_e32 v16, v4
	v_mov_b32_e32 v17, v4
	v_mov_b32_e32 v18, v4
	v_mov_b32_e32 v19, v4
	v_mov_b32_e32 v20, v4
	v_mov_b32_e32 v21, v4
	v_mov_b32_e32 v22, v4
	v_mov_b32_e32 v23, v4
	v_mov_b32_e32 v24, v4
	v_mov_b32_e32 v25, v4
	v_mov_b32_e32 v26, v4
	v_mov_b32_e32 v27, v4
	s_waitcnt vmcnt(0)
	v_mov_b32_e32 v28, v4
	v_mov_b32_e32 v29, v4
	v_mov_b32_e32 v30, v4
	v_mov_b32_e32 v31, v4
	v_mov_b32_e32 v32, v4
	v_mov_b32_e32 v33, v4
	v_mov_b32_e32 v34, v4
	v_mov_b32_e32 v35, v4
	v_mov_b32_e32 v68, v4
	v_mov_b32_e32 v69, v4
	v_mov_b32_e32 v70, v4
	v_mov_b32_e32 v71, v4
	v_mov_b32_e32 v72, v4
	v_mov_b32_e32 v73, v4
	v_mov_b32_e32 v74, v4
	v_mov_b32_e32 v75, v4
	v_mov_b32_e32 v76, v4
	v_mov_b32_e32 v77, v4
	v_mov_b32_e32 v78, v4
	v_mov_b32_e32 v79, v4
	v_mov_b32_e32 v80, v4
	v_mov_b32_e32 v81, v4
	v_mov_b32_e32 v82, v4
	v_mov_b32_e32 v83, v4
	v_mov_b32_e32 v84, v4
	v_mov_b32_e32 v85, v4
	v_mov_b32_e32 v86, v4
	v_mov_b32_e32 v87, v4
	v_mov_b32_e32 v88, v4
	v_mov_b32_e32 v89, v4
	v_mov_b32_e32 v90, v4
	v_mov_b32_e32 v91, v4
	v_mov_b32_e32 v92, v4
	v_mov_b32_e32 v93, v4
	v_mov_b32_e32 v94, v4
	v_mov_b32_e32 v95, v4
	v_mov_b32_e32 v96, v4
	v_mov_b32_e32 v97, v4
	v_mov_b32_e32 v98, v4
	v_mov_b32_e32 v99, v4
	v_mov_b32_e32 v36, v4
	v_mov_b32_e32 v37, v4
	v_mov_b32_e32 v38, v4
	v_mov_b32_e32 v39, v4
	v_mov_b32_e32 v40, v4
	v_mov_b32_e32 v41, v4
	v_mov_b32_e32 v42, v4
	v_mov_b32_e32 v43, v4
	v_mov_b32_e32 v44, v4
	v_mov_b32_e32 v45, v4
	v_mov_b32_e32 v46, v4
	v_mov_b32_e32 v47, v4
	v_mov_b32_e32 v48, v4
	v_mov_b32_e32 v49, v4
	v_mov_b32_e32 v50, v4
	v_mov_b32_e32 v51, v4
	v_mov_b32_e32 v52, v4
	v_mov_b32_e32 v53, v4
	v_mov_b32_e32 v54, v4
	v_mov_b32_e32 v55, v4
	v_mov_b32_e32 v56, v4
	v_mov_b32_e32 v57, v4
	v_mov_b32_e32 v58, v4
	v_mov_b32_e32 v59, v4
	v_mov_b32_e32 v60, v4
	v_mov_b32_e32 v61, v4
	v_mov_b32_e32 v62, v4
	v_mov_b32_e32 v63, v4
	v_mov_b32_e32 v64, v4
	v_mov_b32_e32 v65, v4
	v_mov_b32_e32 v66, v4
	v_mov_b32_e32 v67, v4
	v_mov_b32_e32 v108, v4
	v_mov_b32_e32 v109, v4
	v_mov_b32_e32 v110, v4
	v_mov_b32_e32 v111, v4
	v_mov_b32_e32 v112, v4
	v_mov_b32_e32 v113, v4
	v_mov_b32_e32 v114, v4
	v_mov_b32_e32 v115, v4
	v_mov_b32_e32 v116, v4
	v_mov_b32_e32 v117, v4
	v_mov_b32_e32 v118, v4
	v_mov_b32_e32 v119, v4
	v_mov_b32_e32 v120, v4
	v_mov_b32_e32 v121, v4
	v_mov_b32_e32 v122, v4
	v_mov_b32_e32 v123, v4
	v_mov_b32_e32 v124, v4
	v_mov_b32_e32 v125, v4
	v_mov_b32_e32 v126, v4
	v_mov_b32_e32 v127, v4
	v_mov_b32_e32 v128, v4
	v_mov_b32_e32 v129, v4
	v_mov_b32_e32 v130, v4
	v_mov_b32_e32 v131, v4
	v_mov_b32_e32 v132, v4
	v_mov_b32_e32 v133, v4
	v_mov_b32_e32 v134, v4
	v_mov_b32_e32 v135, v4
	v_mov_b32_e32 v136, v4
	v_mov_b32_e32 v137, v4
	v_mov_b32_e32 v138, v4
	v_mov_b32_e32 v139, v4
	v_readfirstlane_b32 s101, v172
	s_nop 3
	s_cmp_ge_u32 s101, 0x100
	s_cbranch_scc1 .Lprio_hi_485
	s_setprio 1
	s_branch .Lprio_done_485
.Lprio_hi_485:
	s_setprio 0
.Lprio_done_485:
.LBB0_485:
	s_add_u32 s14, s0, 0xfff00080
	s_addc_u32 s15, s1, -1
	s_add_i32 s61, 0, 0x10000
	s_cmp_eq_u32 s60, 60
	s_cselect_b32 s17, s23, s15
	s_cselect_b32 s16, s24, s14
	s_cselect_b32 s15, s25, s59
	s_cselect_b32 s14, s51, s53
	s_add_i32 s64, 0, 0x14000
	v_add_u32_e32 v144, s61, v188
	v_add_u32_e32 v170, s64, v188
	ds_read_b128 v[100:103], v144
	ds_read_b128 v[104:107], v144 offset:1024
	ds_read_b128 v[140:143], v144 offset:2048
	ds_read_b128 v[144:147], v144 offset:3072
	ds_read_b128 v[158:161], v170
	ds_read_b128 v[162:165], v170 offset:1024
	ds_read_b128 v[166:169], v170 offset:2048
	ds_read_b128 v[184:187], v170 offset:3072
	v_lshl_add_u64 v[170:171], s[0:1], 0, v[156:157]
	s_add_i32 m0, s29, 0xc000
	ds_read_b128 v[192:195], v190
	ds_read_b128 v[196:199], v190 offset:1024
	ds_read_b128 v[200:203], v190 offset:2048
	ds_read_b128 v[204:207], v190 offset:3072
	ds_read_b128 v[208:211], v190 offset:4096
	ds_read_b128 v[212:215], v190 offset:5120
	ds_read_b128 v[216:219], v190 offset:6144
	ds_read_b128 v[220:223], v190 offset:7168
	global_load_lds_dwordx4 v[170:171], off
	v_lshl_add_u64 v[170:171], s[0:1], 0, v[154:155]
	s_add_i32 m0, s29, 0xe000
	s_nop 0
	global_load_lds_dwordx4 v[170:171], off
	s_waitcnt vmcnt(8)
	s_waitcnt lgkmcnt(0)
	s_barrier
; #define PG8_STAGE(bufoff, gbase, voff) do { _Pragma("unroll") for (int _i = 0; _i < 2; ++_i) \
;         __builtin_amdgcn_global_load_lds((const unsigned*)((const char*)(gbase) + (voff)[_i]), (PG8_LAS unsigned*)(lds + (bufoff) + ldsw + _i * 8192), 16, 0, 0); } while (0)
; #define PG8_LDA(dst, b, h) do { _Pragma("unroll") for (int m = 0; m < 4; ++m) _Pragma("unroll") for (int k = 0; k < 2; ++k) dst[m][k] = *(const PG8_LAS bf16x8*)(lds + PG8_SA(b, h) + aoff + m * 2048 + k * 1024); } while (0)
; #define PG8_MMA(ai, bj, At, Bt) do { __builtin_amdgcn_s_setprio(1); _Pragma("unroll") for (int m = 0; m < 4; ++m) _Pragma("unroll") for (int n = 0; n < 2; ++n) _Pragma("unroll") for (int k = 0; k < 2; ++k) \
;         acc[ai][bj][m][n] = __builtin_amdgcn_mfma_f32_16x16x32_bf16(Bt[n][k], At[m][k], acc[ai][bj][m][n], 0, 0, 0); __builtin_amdgcn_s_setprio(0); } while (0)
; #define PG8_WAIT_V(n) asm volatile("s_waitcnt vmcnt(" #n ")" ::: "memory")
; #define PG8_WAIT_L(n) asm volatile("s_waitcnt lgkmcnt(" #n ")" ::: "memory")
; #define PG8_BAR __builtin_amdgcn_s_barrier()
; #define PG8_SCHED __builtin_amdgcn_sched_barrier(0)
; template <class Epi, class Sched, bool ALIGN_EPI = false, bool SP2 = false>
; __device__ __forceinline__ void gemm_phase(PG8_LAS unsigned char* lds, const Gemm g, const Sched& S, const Epi& E) {
;     ...
;             PG8_WAIT_V(8); PG8_WAIT_L(0); PG8_BAR; PG8_MMA(0, 0, At, B0); PG8_MMA(0, 1, At, B1); PG8_BAR; PG8_SCHED;
;             PG8_LDA(At, 0, 1); PG8_STAGE(PG8_SB(0, 0), b2, voffB); PG8_STAGE(PG8_SB(0, 1), b2 + hstep, voffB); PG8_STAGE(PG8_SA(0, 0), a2, voffA);
;             PG8_WAIT_V(8); PG8_WAIT_L(0); PG8_BAR; PG8_MMA(1, 0, At, B0); PG8_MMA(1, 1, At, B1); PG8_BAR; PG8_SCHED;
	s_waitcnt lgkmcnt(0)
	v_mfma_f32_16x16x32_bf16 v[136:139], v[100:103], v[192:195], v[136:139]
	v_mfma_f32_16x16x32_bf16 v[132:135], v[140:143], v[192:195], v[132:135]
	v_mfma_f32_16x16x32_bf16 v[128:131], v[100:103], v[200:203], v[128:131]
	v_mfma_f32_16x16x32_bf16 v[124:127], v[140:143], v[200:203], v[124:127]
	v_mfma_f32_16x16x32_bf16 v[120:123], v[100:103], v[208:211], v[120:123]
	v_mfma_f32_16x16x32_bf16 v[116:119], v[140:143], v[208:211], v[116:119]
	v_mfma_f32_16x16x32_bf16 v[112:115], v[100:103], v[216:219], v[112:115]
	v_mfma_f32_16x16x32_bf16 v[108:111], v[140:143], v[216:219], v[108:111]
	v_mfma_f32_16x16x32_bf16 v[136:139], v[104:107], v[196:199], v[136:139]
	v_mfma_f32_16x16x32_bf16 v[132:135], v[144:147], v[196:199], v[132:135]
	v_mfma_f32_16x16x32_bf16 v[128:131], v[104:107], v[204:207], v[128:131]
	v_mfma_f32_16x16x32_bf16 v[124:127], v[144:147], v[204:207], v[124:127]
	v_mfma_f32_16x16x32_bf16 v[120:123], v[104:107], v[212:215], v[120:123]
	v_mfma_f32_16x16x32_bf16 v[116:119], v[144:147], v[212:215], v[116:119]
	v_mfma_f32_16x16x32_bf16 v[112:115], v[104:107], v[220:223], v[112:115]
	v_mfma_f32_16x16x32_bf16 v[108:111], v[144:147], v[220:223], v[108:111]
	v_mfma_f32_16x16x32_bf16 v[64:67], v[158:161], v[192:195], v[64:67]
	v_mfma_f32_16x16x32_bf16 v[60:63], v[166:169], v[192:195], v[60:63]
	v_mfma_f32_16x16x32_bf16 v[56:59], v[158:161], v[200:203], v[56:59]
	v_mfma_f32_16x16x32_bf16 v[52:55], v[166:169], v[200:203], v[52:55]
	v_mfma_f32_16x16x32_bf16 v[48:51], v[158:161], v[208:211], v[48:51]
	v_mfma_f32_16x16x32_bf16 v[44:47], v[166:169], v[208:211], v[44:47]
	v_mfma_f32_16x16x32_bf16 v[40:43], v[158:161], v[216:219], v[40:43]
	v_mfma_f32_16x16x32_bf16 v[36:39], v[166:169], v[216:219], v[36:39]
	v_mfma_f32_16x16x32_bf16 v[64:67], v[162:165], v[196:199], v[64:67]
	v_mfma_f32_16x16x32_bf16 v[60:63], v[184:187], v[196:199], v[60:63]
	v_mfma_f32_16x16x32_bf16 v[56:59], v[162:165], v[204:207], v[56:59]
	v_mfma_f32_16x16x32_bf16 v[52:55], v[184:187], v[204:207], v[52:55]
	v_mfma_f32_16x16x32_bf16 v[48:51], v[162:165], v[212:215], v[48:51]
	v_mfma_f32_16x16x32_bf16 v[44:47], v[184:187], v[212:215], v[44:47]
	v_mfma_f32_16x16x32_bf16 v[40:43], v[162:165], v[220:223], v[40:43]
	v_mfma_f32_16x16x32_bf16 v[36:39], v[184:187], v[220:223], v[36:39]
	s_barrier
	s_add_i32 s61, s61, s28
	v_lshl_add_u64 v[170:171], s[14:15], 0, v[174:175]
	s_mov_b32 m0, s61
	ds_read_b128 v[192:195], v190 offset:16384
	ds_read_b128 v[196:199], v190 offset:17408
	ds_read_b128 v[200:203], v190 offset:18432
	ds_read_b128 v[204:207], v190 offset:19456
	ds_read_b128 v[208:211], v190 offset:20480
	ds_read_b128 v[212:215], v190 offset:21504
	ds_read_b128 v[216:219], v190 offset:22528
	ds_read_b128 v[220:223], v190 offset:23552
	global_load_lds_dwordx4 v[170:171], off
	s_add_i32 m0, s61, 0x2000
	s_add_u32 s62, s14, 0x100000
	v_lshl_add_u64 v[224:225], s[14:15], 0, v[148:149]
	s_addc_u32 s63, s15, 0
	s_add_i32 s61, s64, s28
	global_load_lds_dwordx4 v[224:225], off
	v_lshl_add_u64 v[226:227], s[62:63], 0, v[174:175]
	s_mov_b32 m0, s61
	v_lshl_add_u64 v[228:229], s[16:17], 0, v[150:151]
	global_load_lds_dwordx4 v[226:227], off
	v_lshl_add_u64 v[226:227], s[62:63], 0, v[148:149]
	s_add_i32 m0, s61, 0x2000
	s_nop 0
	global_load_lds_dwordx4 v[226:227], off
	v_lshl_add_u64 v[226:227], s[16:17], 0, v[152:153]
	s_mov_b32 m0, s29
	s_nop 0
	global_load_lds_dwordx4 v[226:227], off
	s_mov_b32 m0, s30
	s_nop 0
	global_load_lds_dwordx4 v[228:229], off
	s_waitcnt vmcnt(8)
	s_waitcnt lgkmcnt(0)
	s_barrier
	s_waitcnt lgkmcnt(0)
	v_mfma_f32_16x16x32_bf16 v[96:99], v[100:103], v[192:195], v[96:99]
	v_mfma_f32_16x16x32_bf16 v[92:95], v[140:143], v[192:195], v[92:95]
	v_mfma_f32_16x16x32_bf16 v[88:91], v[100:103], v[200:203], v[88:91]
	v_mfma_f32_16x16x32_bf16 v[84:87], v[140:143], v[200:203], v[84:87]
	v_mfma_f32_16x16x32_bf16 v[80:83], v[100:103], v[208:211], v[80:83]
	v_mfma_f32_16x16x32_bf16 v[76:79], v[140:143], v[208:211], v[76:79]
	v_mfma_f32_16x16x32_bf16 v[72:75], v[100:103], v[216:219], v[72:75]
	v_mfma_f32_16x16x32_bf16 v[68:71], v[140:143], v[216:219], v[68:71]
	v_mfma_f32_16x16x32_bf16 v[96:99], v[104:107], v[196:199], v[96:99]
	v_mfma_f32_16x16x32_bf16 v[92:95], v[144:147], v[196:199], v[92:95]
	v_mfma_f32_16x16x32_bf16 v[88:91], v[104:107], v[204:207], v[88:91]
	v_mfma_f32_16x16x32_bf16 v[84:87], v[144:147], v[204:207], v[84:87]
	v_mfma_f32_16x16x32_bf16 v[80:83], v[104:107], v[212:215], v[80:83]
	v_mfma_f32_16x16x32_bf16 v[76:79], v[144:147], v[212:215], v[76:79]
	v_mfma_f32_16x16x32_bf16 v[72:75], v[104:107], v[220:223], v[72:75]
	v_mfma_f32_16x16x32_bf16 v[68:71], v[144:147], v[220:223], v[68:71]
	v_mfma_f32_16x16x32_bf16 v[32:35], v[158:161], v[192:195], v[32:35]
	v_mfma_f32_16x16x32_bf16 v[28:31], v[166:169], v[192:195], v[28:31]
	v_mfma_f32_16x16x32_bf16 v[24:27], v[158:161], v[200:203], v[24:27]
	v_mfma_f32_16x16x32_bf16 v[20:23], v[166:169], v[200:203], v[20:23]
	v_mfma_f32_16x16x32_bf16 v[16:19], v[158:161], v[208:211], v[16:19]
	v_mfma_f32_16x16x32_bf16 v[12:15], v[166:169], v[208:211], v[12:15]
	v_mfma_f32_16x16x32_bf16 v[8:11], v[158:161], v[216:219], v[8:11]
	v_mfma_f32_16x16x32_bf16 v[4:7], v[166:169], v[216:219], v[4:7]
	v_mfma_f32_16x16x32_bf16 v[32:35], v[162:165], v[196:199], v[32:35]
	v_mfma_f32_16x16x32_bf16 v[28:31], v[184:187], v[196:199], v[28:31]
	v_mfma_f32_16x16x32_bf16 v[24:27], v[162:165], v[204:207], v[24:27]
	v_mfma_f32_16x16x32_bf16 v[20:23], v[184:187], v[204:207], v[20:23]
	v_mfma_f32_16x16x32_bf16 v[16:19], v[162:165], v[212:215], v[16:19]
	v_mfma_f32_16x16x32_bf16 v[12:15], v[184:187], v[212:215], v[12:15]
	v_mfma_f32_16x16x32_bf16 v[8:11], v[162:165], v[220:223], v[8:11]
	v_mfma_f32_16x16x32_bf16 v[4:7], v[184:187], v[220:223], v[4:7]
	s_barrier
; #define PG8_STAGE(bufoff, gbase, voff) do { _Pragma("unroll") for (int _i = 0; _i < 2; ++_i) \
;         __builtin_amdgcn_global_load_lds((const unsigned*)((const char*)(gbase) + (voff)[_i]), (PG8_LAS unsigned*)(lds + (bufoff) + ldsw + _i * 8192), 16, 0, 0); } while (0)
; #define PG8_LDA(dst, b, h) do { _Pragma("unroll") for (int m = 0; m < 4; ++m) _Pragma("unroll") for (int k = 0; k < 2; ++k) dst[m][k] = *(const PG8_LAS bf16x8*)(lds + PG8_SA(b, h) + aoff + m * 2048 + k * 1024); } while (0)
; #define PG8_LDB(dst, b, h) do { _Pragma("unroll") for (int n = 0; n < 2; ++n) _Pragma("unroll") for (int k = 0; k < 2; ++k) dst[n][k] = *(const PG8_LAS bf16x8*)(lds + PG8_SB(b, h) + boff + n * 2048 + k * 1024); } while (0)
; #define PG8_MMA(ai, bj, At, Bt) do { __builtin_amdgcn_s_setprio(1); _Pragma("unroll") for (int m = 0; m < 4; ++m) _Pragma("unroll") for (int n = 0; n < 2; ++n) _Pragma("unroll") for (int k = 0; k < 2; ++k) \
;         acc[ai][bj][m][n] = __builtin_amdgcn_mfma_f32_16x16x32_bf16(Bt[n][k], At[m][k], acc[ai][bj][m][n], 0, 0, 0); __builtin_amdgcn_s_setprio(0); } while (0)
; #define PG8_WAIT_V(n) asm volatile("s_waitcnt vmcnt(" #n ")" ::: "memory")
; #define PG8_WAIT_L(n) asm volatile("s_waitcnt lgkmcnt(" #n ")" ::: "memory")
; #define PG8_BAR __builtin_amdgcn_s_barrier()
; #define PG8_SCHED __builtin_amdgcn_sched_barrier(0)
; template <class Epi, class Sched, bool ALIGN_EPI = false, bool SP2 = false>
; __device__ __forceinline__ void gemm_phase(PG8_LAS unsigned char* lds, const Gemm g, const Sched& S, const Epi& E) {
;     ...
;             PG8_LDB(B0, 1, 0); PG8_LDB(B1, 1, 1); PG8_SCHED; PG8_LDA(At, 1, 0); PG8_STAGE(PG8_SA(0, 1), a2 + hstep, voffA);
;             PG8_WAIT_V(8); PG8_WAIT_L(0); PG8_BAR; PG8_MMA(0, 0, At, B0); PG8_MMA(0, 1, At, B1); PG8_BAR; PG8_SCHED;
	s_add_i32 s61, 0, 0x18000
	s_add_i32 s62, 0, 0x1c000
	v_add_u32_e32 v144, s61, v188
	v_add_u32_e32 v184, s62, v188
	ds_read_b128 v[100:103], v144
	ds_read_b128 v[104:107], v144 offset:1024
	ds_read_b128 v[140:143], v144 offset:2048
	ds_read_b128 v[144:147], v144 offset:3072
	ds_read_b128 v[158:161], v184
	ds_read_b128 v[162:165], v184 offset:1024
	ds_read_b128 v[166:169], v184 offset:2048
	ds_read_b128 v[184:187], v184 offset:3072
	s_add_u32 s16, s16, 0x100000
	s_addc_u32 s17, s17, 0
	s_mov_b32 m0, s31
	v_lshl_add_u64 v[230:231], s[16:17], 0, v[152:153]
	ds_read_b128 v[192:195], v190 offset:32768
	ds_read_b128 v[196:199], v190 offset:33792
	ds_read_b128 v[200:203], v190 offset:34816
	ds_read_b128 v[204:207], v190 offset:35840
	ds_read_b128 v[208:211], v190 offset:36864
	ds_read_b128 v[212:215], v190 offset:37888
	ds_read_b128 v[216:219], v190 offset:38912
	ds_read_b128 v[220:223], v190 offset:39936
	global_load_lds_dwordx4 v[230:231], off
	v_lshl_add_u64 v[230:231], s[16:17], 0, v[150:151]
	s_mov_b32 m0, s34
	s_nop 0
	global_load_lds_dwordx4 v[230:231], off
	s_waitcnt vmcnt(8)
	s_waitcnt lgkmcnt(0)
	s_barrier
	s_waitcnt lgkmcnt(0)
	v_mfma_f32_16x16x32_bf16 v[136:139], v[100:103], v[192:195], v[136:139]
	v_mfma_f32_16x16x32_bf16 v[132:135], v[140:143], v[192:195], v[132:135]
	v_mfma_f32_16x16x32_bf16 v[128:131], v[100:103], v[200:203], v[128:131]
	v_mfma_f32_16x16x32_bf16 v[124:127], v[140:143], v[200:203], v[124:127]
	v_mfma_f32_16x16x32_bf16 v[120:123], v[100:103], v[208:211], v[120:123]
	v_mfma_f32_16x16x32_bf16 v[116:119], v[140:143], v[208:211], v[116:119]
	v_mfma_f32_16x16x32_bf16 v[112:115], v[100:103], v[216:219], v[112:115]
	v_mfma_f32_16x16x32_bf16 v[108:111], v[140:143], v[216:219], v[108:111]
	v_mfma_f32_16x16x32_bf16 v[136:139], v[104:107], v[196:199], v[136:139]
	v_mfma_f32_16x16x32_bf16 v[132:135], v[144:147], v[196:199], v[132:135]
	v_mfma_f32_16x16x32_bf16 v[128:131], v[104:107], v[204:207], v[128:131]
	v_mfma_f32_16x16x32_bf16 v[124:127], v[144:147], v[204:207], v[124:127]
	v_mfma_f32_16x16x32_bf16 v[120:123], v[104:107], v[212:215], v[120:123]
	v_mfma_f32_16x16x32_bf16 v[116:119], v[144:147], v[212:215], v[116:119]
	v_mfma_f32_16x16x32_bf16 v[112:115], v[104:107], v[220:223], v[112:115]
	v_mfma_f32_16x16x32_bf16 v[108:111], v[144:147], v[220:223], v[108:111]
	v_mfma_f32_16x16x32_bf16 v[64:67], v[158:161], v[192:195], v[64:67]
	v_mfma_f32_16x16x32_bf16 v[60:63], v[166:169], v[192:195], v[60:63]
	v_mfma_f32_16x16x32_bf16 v[56:59], v[158:161], v[200:203], v[56:59]
	v_mfma_f32_16x16x32_bf16 v[52:55], v[166:169], v[200:203], v[52:55]
	v_mfma_f32_16x16x32_bf16 v[48:51], v[158:161], v[208:211], v[48:51]
	v_mfma_f32_16x16x32_bf16 v[44:47], v[166:169], v[208:211], v[44:47]
	v_mfma_f32_16x16x32_bf16 v[40:43], v[158:161], v[216:219], v[40:43]
	v_mfma_f32_16x16x32_bf16 v[36:39], v[166:169], v[216:219], v[36:39]
	v_mfma_f32_16x16x32_bf16 v[64:67], v[162:165], v[196:199], v[64:67]
	v_mfma_f32_16x16x32_bf16 v[60:63], v[184:187], v[196:199], v[60:63]
	v_mfma_f32_16x16x32_bf16 v[56:59], v[162:165], v[204:207], v[56:59]
	v_mfma_f32_16x16x32_bf16 v[52:55], v[184:187], v[204:207], v[52:55]
	v_mfma_f32_16x16x32_bf16 v[48:51], v[162:165], v[212:215], v[48:51]
	v_mfma_f32_16x16x32_bf16 v[44:47], v[184:187], v[212:215], v[44:47]
	v_mfma_f32_16x16x32_bf16 v[40:43], v[162:165], v[220:223], v[40:43]
	v_mfma_f32_16x16x32_bf16 v[36:39], v[184:187], v[220:223], v[36:39]
	s_barrier
; #define PG8_STAGE(bufoff, gbase, voff) do { _Pragma("unroll") for (int _i = 0; _i < 2; ++_i) \
;         __builtin_amdgcn_global_load_lds((const unsigned*)((const char*)(gbase) + (voff)[_i]), (PG8_LAS unsigned*)(lds + (bufoff) + ldsw + _i * 8192), 16, 0, 0); } while (0)
; #define PG8_LDA(dst, b, h) do { _Pragma("unroll") for (int m = 0; m < 4; ++m) _Pragma("unroll") for (int k = 0; k < 2; ++k) dst[m][k] = *(const PG8_LAS bf16x8*)(lds + PG8_SA(b, h) + aoff + m * 2048 + k * 1024); } while (0)
; #define PG8_MMA(ai, bj, At, Bt) do { __builtin_amdgcn_s_setprio(1); _Pragma("unroll") for (int m = 0; m < 4; ++m) _Pragma("unroll") for (int n = 0; n < 2; ++n) _Pragma("unroll") for (int k = 0; k < 2; ++k) \
;         acc[ai][bj][m][n] = __builtin_amdgcn_mfma_f32_16x16x32_bf16(Bt[n][k], At[m][k], acc[ai][bj][m][n], 0, 0, 0); __builtin_amdgcn_s_setprio(0); } while (0)
; #define PG8_WAIT_V(n) asm volatile("s_waitcnt vmcnt(" #n ")" ::: "memory")
; #define PG8_WAIT_L(n) asm volatile("s_waitcnt lgkmcnt(" #n ")" ::: "memory")
; #define PG8_BAR __builtin_amdgcn_s_barrier()
; #define PG8_SCHED __builtin_amdgcn_sched_barrier(0)
; template <class Epi, class Sched, bool ALIGN_EPI = false, bool SP2 = false>
; __device__ __forceinline__ void gemm_phase(PG8_LAS unsigned char* lds, const Gemm g, const Sched& S, const Epi& E) {
;     ...
;             PG8_LDA(At, 1, 1); PG8_STAGE(PG8_SB(1, 0), b3, voffB); PG8_STAGE(PG8_SB(1, 1), b3 + hstep, voffB); PG8_STAGE(PG8_SA(1, 0), a3, voffA);
;             PG8_WAIT_V(8); PG8_WAIT_L(0); PG8_BAR; PG8_MMA(1, 0, At, B0); PG8_MMA(1, 1, At, B1); PG8_BAR; PG8_SCHED;
	s_add_i32 s16, s61, s28
	v_lshl_add_u64 v[170:171], v[170:171], 0, s[10:11]
	s_mov_b32 m0, s16
	ds_read_b128 v[192:195], v190 offset:49152
	ds_read_b128 v[196:199], v190 offset:50176
	ds_read_b128 v[200:203], v190 offset:51200
	ds_read_b128 v[204:207], v190 offset:52224
	ds_read_b128 v[208:211], v190 offset:53248
	ds_read_b128 v[212:215], v190 offset:54272
	ds_read_b128 v[216:219], v190 offset:55296
	ds_read_b128 v[220:223], v190 offset:56320
	global_load_lds_dwordx4 v[170:171], off
	s_add_i32 m0, s16, 0x2000
	s_add_u32 s14, s14, 0x100080
	v_lshl_add_u64 v[170:171], v[224:225], 0, s[10:11]
	s_addc_u32 s15, s15, 0
	s_add_i32 s16, s62, s28
	global_load_lds_dwordx4 v[170:171], off
	v_lshl_add_u64 v[170:171], s[14:15], 0, v[174:175]
	s_mov_b32 m0, s16
	s_nop 0
	global_load_lds_dwordx4 v[170:171], off
	v_lshl_add_u64 v[170:171], s[14:15], 0, v[148:149]
	s_add_i32 m0, s16, 0x2000
	s_nop 0
	global_load_lds_dwordx4 v[170:171], off
	v_lshl_add_u64 v[170:171], v[226:227], 0, s[10:11]
	s_mov_b32 m0, s35
	s_nop 0
	global_load_lds_dwordx4 v[170:171], off
	v_lshl_add_u64 v[170:171], v[228:229], 0, s[10:11]
	s_mov_b32 m0, s38
	s_nop 0
	global_load_lds_dwordx4 v[170:171], off
	s_waitcnt vmcnt(8)
	s_waitcnt lgkmcnt(0)
	s_barrier
	s_waitcnt lgkmcnt(0)
	v_mfma_f32_16x16x32_bf16 v[96:99], v[100:103], v[192:195], v[96:99]
	v_mfma_f32_16x16x32_bf16 v[92:95], v[140:143], v[192:195], v[92:95]
	v_mfma_f32_16x16x32_bf16 v[88:91], v[100:103], v[200:203], v[88:91]
	v_mfma_f32_16x16x32_bf16 v[84:87], v[140:143], v[200:203], v[84:87]
	v_mfma_f32_16x16x32_bf16 v[80:83], v[100:103], v[208:211], v[80:83]
	v_mfma_f32_16x16x32_bf16 v[76:79], v[140:143], v[208:211], v[76:79]
	v_mfma_f32_16x16x32_bf16 v[72:75], v[100:103], v[216:219], v[72:75]
	v_mfma_f32_16x16x32_bf16 v[68:71], v[140:143], v[216:219], v[68:71]
	v_mfma_f32_16x16x32_bf16 v[96:99], v[104:107], v[196:199], v[96:99]
	v_mfma_f32_16x16x32_bf16 v[92:95], v[144:147], v[196:199], v[92:95]
	v_mfma_f32_16x16x32_bf16 v[88:91], v[104:107], v[204:207], v[88:91]
	v_mfma_f32_16x16x32_bf16 v[84:87], v[144:147], v[204:207], v[84:87]
	v_mfma_f32_16x16x32_bf16 v[80:83], v[104:107], v[212:215], v[80:83]
	v_mfma_f32_16x16x32_bf16 v[76:79], v[144:147], v[212:215], v[76:79]
	v_mfma_f32_16x16x32_bf16 v[72:75], v[104:107], v[220:223], v[72:75]
	v_mfma_f32_16x16x32_bf16 v[68:71], v[144:147], v[220:223], v[68:71]
	v_mfma_f32_16x16x32_bf16 v[32:35], v[158:161], v[192:195], v[32:35]
	v_mfma_f32_16x16x32_bf16 v[28:31], v[166:169], v[192:195], v[28:31]
	v_mfma_f32_16x16x32_bf16 v[24:27], v[158:161], v[200:203], v[24:27]
	v_mfma_f32_16x16x32_bf16 v[20:23], v[166:169], v[200:203], v[20:23]
	v_mfma_f32_16x16x32_bf16 v[16:19], v[158:161], v[208:211], v[16:19]
	v_mfma_f32_16x16x32_bf16 v[12:15], v[166:169], v[208:211], v[12:15]
	v_mfma_f32_16x16x32_bf16 v[8:11], v[158:161], v[216:219], v[8:11]
	v_mfma_f32_16x16x32_bf16 v[4:7], v[166:169], v[216:219], v[4:7]
	v_mfma_f32_16x16x32_bf16 v[32:35], v[162:165], v[196:199], v[32:35]
	v_mfma_f32_16x16x32_bf16 v[28:31], v[184:187], v[196:199], v[28:31]
	v_mfma_f32_16x16x32_bf16 v[24:27], v[162:165], v[204:207], v[24:27]
	v_mfma_f32_16x16x32_bf16 v[20:23], v[184:187], v[204:207], v[20:23]
	v_mfma_f32_16x16x32_bf16 v[16:19], v[162:165], v[212:215], v[16:19]
	v_mfma_f32_16x16x32_bf16 v[12:15], v[184:187], v[212:215], v[12:15]
	v_mfma_f32_16x16x32_bf16 v[8:11], v[162:165], v[220:223], v[8:11]
	v_mfma_f32_16x16x32_bf16 v[4:7], v[184:187], v[220:223], v[4:7]
	s_barrier
	s_add_i32 s60, s60, 2
	s_add_u32 s53, s53, 0x100
	s_addc_u32 s59, s59, 0
	s_add_u32 s0, s0, 0x100
	s_addc_u32 s1, s1, 0
	s_cmp_gt_u32 s60, 61
	s_cbranch_scc0 .LBB0_485
	s_and_b64 vcc, exec, s[48:49]
	s_cbranch_vccz .LBB0_488
	s_barrier

; #define PG8_STAGE(bufoff, gbase, voff) do { _Pragma("unroll") for (int _i = 0; _i < 2; ++_i) \
;         __builtin_amdgcn_global_load_lds((const unsigned*)((const char*)(gbase) + (voff)[_i]), (PG8_LAS unsigned*)(lds + (bufoff) + ldsw + _i * 8192), 16, 0, 0); } while (0)
; #define PG8_LDA(dst, b, h) do { _Pragma("unroll") for (int m = 0; m < 4; ++m) _Pragma("unroll") for (int k = 0; k < 2; ++k) dst[m][k] = *(const PG8_LAS bf16x8*)(lds + PG8_SA(b, h) + aoff + m * 2048 + k * 1024); } while (0)
; #define PG8_LDB(dst, b, h) do { _Pragma("unroll") for (int n = 0; n < 2; ++n) _Pragma("unroll") for (int k = 0; k < 2; ++k) dst[n][k] = *(const PG8_LAS bf16x8*)(lds + PG8_SB(b, h) + boff + n * 2048 + k * 1024); } while (0)
; #define PG8_SCHED __builtin_amdgcn_sched_barrier(0)
; template <class Epi, class Sched, bool ALIGN_EPI = false, bool SP2 = false>
; __device__ __forceinline__ void gemm_phase(PG8_LAS unsigned char* lds, const Gemm g, const Sched& S, const Epi& E) {
;     ...
;         const bool has_next = S.next(ui + 1, nxt);
;         const char* nA = has_next ? (const char*)g.A + (size_t)nxt.pm * tstep : cA; const char* nB = has_next ? (const char*)g.Bt + (size_t)nxt.pn * tstep : cB;
;         for (int t = 0; t < nt; t += 2) {
;             const bool last = (t == nt - 2);
;             const char* a1 = cA + (size_t)(t + 1) * kstep;
;             const char* a2 = last ? nA : cA + (size_t)(t + 2) * kstep; const char* b2 = last ? nB : cB + (size_t)(t + 2) * kstep;
;             const char* a3 = a2 + kstep; const char* b3 = b2 + kstep;
;             if (last && has_next) S.a_ready(nxt);
;             if constexpr (SP2) {
;             PG8_LDB(B0, 0, 0); PG8_LDB(B1, 0, 1); PG8_SCHED; PG8_LDA(At, 0, 0); PG8_STAGE(PG8_SA(1, 1), a1 + hstep, voffA);
;     ...
;         for (int a = 0; a < 2; ++a)
; #pragma unroll
;             for (int b = 0; b < 2; ++b)
; #pragma unroll
;                 for (int m = 0; m < 4; ++m)
; #pragma unroll
;                     for (int n = 0; n < 2; ++n) acc[a][b][m][n] = (f32x4){0.f, 0.f, 0.f, 0.f};
.LBB0_562:
	s_ashr_i32 s39, s38, 31
	s_lshl_b64 s[26:27], s[38:39], 20
	s_add_u32 s44, s22, s26
	s_addc_u32 s45, s23, s27
	s_and_b64 s[26:27], s[42:43], exec
	s_cselect_b32 s39, s45, s19
	s_cselect_b32 s59, s44, s18
	s_ashr_i32 s37, s36, 31
	s_lshl_b64 s[26:27], s[36:37], 20
	s_add_u32 s46, s24, s26
	s_addc_u32 s47, s25, s27
	s_and_b64 s[26:27], s[42:43], exec
	s_cselect_b32 s37, s47, s1
	s_cselect_b32 s60, s46, s0
	s_add_u32 s61, s0, 0x100
	s_addc_u32 s62, s1, 0
	s_add_u32 s0, s18, 0x80080
	v_mov_b32_e32 v4, 0
	s_addc_u32 s1, s19, 0
	s_mov_b32 s63, -2
	s_waitcnt lgkmcnt(0)
	v_mov_b32_e32 v5, v4
	v_mov_b32_e32 v6, v4
	v_mov_b32_e32 v7, v4
	v_mov_b32_e32 v8, v4
	v_mov_b32_e32 v9, v4
	v_mov_b32_e32 v10, v4
	v_mov_b32_e32 v11, v4
	v_mov_b32_e32 v20, v4
	v_mov_b32_e32 v21, v4
	v_mov_b32_e32 v22, v4
	v_mov_b32_e32 v23, v4
	v_mov_b32_e32 v24, v4
	v_mov_b32_e32 v25, v4
	v_mov_b32_e32 v26, v4
	v_mov_b32_e32 v27, v4
	s_waitcnt vmcnt(0)
	v_mov_b32_e32 v36, v4
	v_mov_b32_e32 v37, v4
	v_mov_b32_e32 v38, v4
	v_mov_b32_e32 v39, v4
	v_mov_b32_e32 v40, v4
	v_mov_b32_e32 v41, v4
	v_mov_b32_e32 v42, v4
	v_mov_b32_e32 v43, v4
	v_mov_b32_e32 v52, v4
	v_mov_b32_e32 v53, v4
	v_mov_b32_e32 v54, v4
	v_mov_b32_e32 v55, v4
	v_mov_b32_e32 v56, v4
	v_mov_b32_e32 v57, v4
	v_mov_b32_e32 v58, v4
	v_mov_b32_e32 v59, v4
	v_mov_b32_e32 v12, v4
	v_mov_b32_e32 v13, v4
	v_mov_b32_e32 v14, v4
	v_mov_b32_e32 v15, v4
	v_mov_b32_e32 v16, v4
	v_mov_b32_e32 v17, v4
	v_mov_b32_e32 v18, v4
	v_mov_b32_e32 v19, v4
	v_mov_b32_e32 v28, v4
	v_mov_b32_e32 v29, v4
	v_mov_b32_e32 v30, v4
	v_mov_b32_e32 v31, v4
	v_mov_b32_e32 v32, v4
	v_mov_b32_e32 v33, v4
	v_mov_b32_e32 v34, v4
	v_mov_b32_e32 v35, v4
	v_mov_b32_e32 v44, v4
	v_mov_b32_e32 v45, v4
	v_mov_b32_e32 v46, v4
	v_mov_b32_e32 v47, v4
	v_mov_b32_e32 v48, v4
	v_mov_b32_e32 v49, v4
	v_mov_b32_e32 v50, v4
	v_mov_b32_e32 v51, v4
	v_mov_b32_e32 v60, v4
	v_mov_b32_e32 v61, v4
	v_mov_b32_e32 v62, v4
	v_mov_b32_e32 v63, v4
	v_mov_b32_e32 v64, v4
	v_mov_b32_e32 v65, v4
	v_mov_b32_e32 v66, v4
	v_mov_b32_e32 v67, v4
	v_mov_b32_e32 v68, v4
	v_mov_b32_e32 v69, v4
	v_mov_b32_e32 v70, v4
	v_mov_b32_e32 v71, v4
	v_mov_b32_e32 v72, v4
	v_mov_b32_e32 v73, v4
	v_mov_b32_e32 v74, v4
	v_mov_b32_e32 v75, v4
	v_mov_b32_e32 v84, v4
	v_mov_b32_e32 v85, v4
	v_mov_b32_e32 v86, v4
	v_mov_b32_e32 v87, v4
	v_mov_b32_e32 v88, v4
	v_mov_b32_e32 v89, v4
	v_mov_b32_e32 v90, v4
	v_mov_b32_e32 v91, v4
	v_mov_b32_e32 v100, v4
	v_mov_b32_e32 v101, v4
	v_mov_b32_e32 v102, v4
	v_mov_b32_e32 v103, v4
	v_mov_b32_e32 v104, v4
	v_mov_b32_e32 v105, v4
	v_mov_b32_e32 v106, v4
	v_mov_b32_e32 v107, v4
	v_mov_b32_e32 v116, v4
	v_mov_b32_e32 v117, v4
	v_mov_b32_e32 v118, v4
	v_mov_b32_e32 v119, v4
	v_mov_b32_e32 v120, v4
	v_mov_b32_e32 v121, v4
	v_mov_b32_e32 v122, v4
	v_mov_b32_e32 v123, v4
	v_mov_b32_e32 v76, v4
	v_mov_b32_e32 v77, v4
	v_mov_b32_e32 v78, v4
	v_mov_b32_e32 v79, v4
	v_mov_b32_e32 v80, v4
	v_mov_b32_e32 v81, v4
	v_mov_b32_e32 v82, v4
	v_mov_b32_e32 v83, v4
	v_mov_b32_e32 v92, v4
	v_mov_b32_e32 v93, v4
	v_mov_b32_e32 v94, v4
	v_mov_b32_e32 v95, v4
	v_mov_b32_e32 v96, v4
	v_mov_b32_e32 v97, v4
	v_mov_b32_e32 v98, v4
	v_mov_b32_e32 v99, v4
	v_mov_b32_e32 v108, v4
	v_mov_b32_e32 v109, v4
	v_mov_b32_e32 v110, v4
	v_mov_b32_e32 v111, v4
	v_mov_b32_e32 v112, v4
	v_mov_b32_e32 v113, v4
	v_mov_b32_e32 v114, v4
	v_mov_b32_e32 v115, v4
	v_mov_b32_e32 v124, v4
	v_mov_b32_e32 v125, v4
	v_mov_b32_e32 v126, v4
	v_mov_b32_e32 v127, v4
	v_mov_b32_e32 v128, v4
	v_mov_b32_e32 v129, v4
	v_mov_b32_e32 v130, v4
	v_mov_b32_e32 v131, v4
	v_readfirstlane_b32 s101, v172
	s_nop 3
	s_cmp_ge_u32 s101, 0x100
	s_cbranch_scc1 .Lprio_hi_563
	s_setprio 1
	s_branch .Lprio_done_563
.Lprio_hi_563:
	s_setprio 0
.Lprio_done_563:
.LBB0_563:
	s_add_u32 s18, s0, 0xfff80080
	s_addc_u32 s19, s1, -1
	s_add_i32 s64, 0, 0x10000
	s_cmp_eq_u32 s63, 28
	s_cselect_b32 s27, s39, s19
	s_cselect_b32 s26, s59, s18
	s_cselect_b32 s19, s37, s62
	s_cselect_b32 s18, s60, s61
	s_add_i32 s66, 0, 0x14000
	v_add_u32_e32 v144, s64, v167
	v_add_u32_e32 v170, s66, v167
	ds_read_b128 v[132:135], v144
	ds_read_b128 v[136:139], v144 offset:1024
	ds_read_b128 v[140:143], v144 offset:2048
	ds_read_b128 v[144:147], v144 offset:3072
	ds_read_b128 v[158:161], v170
	ds_read_b128 v[162:165], v170 offset:1024
	ds_read_b128 v[184:187], v170 offset:2048
	ds_read_b128 v[188:191], v170 offset:3072
	v_lshl_add_u64 v[170:171], s[0:1], 0, v[156:157]
	s_add_i32 m0, s49, 0xc000
	ds_read_b128 v[192:195], v169
	ds_read_b128 v[196:199], v169 offset:1024
	ds_read_b128 v[200:203], v169 offset:2048
	ds_read_b128 v[204:207], v169 offset:3072
	ds_read_b128 v[208:211], v169 offset:4096
	ds_read_b128 v[212:215], v169 offset:5120
	ds_read_b128 v[216:219], v169 offset:6144
	ds_read_b128 v[220:223], v169 offset:7168
	global_load_lds_dwordx4 v[170:171], off
	v_lshl_add_u64 v[170:171], s[0:1], 0, v[154:155]
	s_add_i32 m0, s49, 0xe000
	s_nop 0
	global_load_lds_dwordx4 v[170:171], off
	s_waitcnt vmcnt(8)
	s_waitcnt lgkmcnt(0)
	s_barrier
; #define PG8_STAGE(bufoff, gbase, voff) do { _Pragma("unroll") for (int _i = 0; _i < 2; ++_i) \
;         __builtin_amdgcn_global_load_lds((const unsigned*)((const char*)(gbase) + (voff)[_i]), (PG8_LAS unsigned*)(lds + (bufoff) + ldsw + _i * 8192), 16, 0, 0); } while (0)
; #define PG8_LDA(dst, b, h) do { _Pragma("unroll") for (int m = 0; m < 4; ++m) _Pragma("unroll") for (int k = 0; k < 2; ++k) dst[m][k] = *(const PG8_LAS bf16x8*)(lds + PG8_SA(b, h) + aoff + m * 2048 + k * 1024); } while (0)
; #define PG8_MMA(ai, bj, At, Bt) do { __builtin_amdgcn_s_setprio(1); _Pragma("unroll") for (int m = 0; m < 4; ++m) _Pragma("unroll") for (int n = 0; n < 2; ++n) _Pragma("unroll") for (int k = 0; k < 2; ++k) \
;         acc[ai][bj][m][n] = __builtin_amdgcn_mfma_f32_16x16x32_bf16(Bt[n][k], At[m][k], acc[ai][bj][m][n], 0, 0, 0); __builtin_amdgcn_s_setprio(0); } while (0)
; #define PG8_WAIT_V(n) asm volatile("s_waitcnt vmcnt(" #n ")" ::: "memory")
; #define PG8_WAIT_L(n) asm volatile("s_waitcnt lgkmcnt(" #n ")" ::: "memory")
; #define PG8_BAR __builtin_amdgcn_s_barrier()
; #define PG8_SCHED __builtin_amdgcn_sched_barrier(0)
; template <class Epi, class Sched, bool ALIGN_EPI = false, bool SP2 = false>
; __device__ __forceinline__ void gemm_phase(PG8_LAS unsigned char* lds, const Gemm g, const Sched& S, const Epi& E) {
;     ...
;             PG8_WAIT_V(8); PG8_WAIT_L(0); PG8_BAR; PG8_MMA(0, 0, At, B0); PG8_MMA(0, 1, At, B1); PG8_BAR; PG8_SCHED;
;             PG8_LDA(At, 0, 1); PG8_STAGE(PG8_SB(0, 0), b2, voffB); PG8_STAGE(PG8_SB(0, 1), b2 + hstep, voffB); PG8_STAGE(PG8_SA(0, 0), a2, voffA);
;             PG8_WAIT_V(8); PG8_WAIT_L(0); PG8_BAR; PG8_MMA(1, 0, At, B0); PG8_MMA(1, 1, At, B1); PG8_BAR; PG8_SCHED;
	s_waitcnt lgkmcnt(0)
	v_mfma_f32_16x16x32_bf16 v[128:131], v[132:135], v[192:195], v[128:131]
	v_mfma_f32_16x16x32_bf16 v[124:127], v[140:143], v[192:195], v[124:127]
	v_mfma_f32_16x16x32_bf16 v[112:115], v[132:135], v[200:203], v[112:115]
	v_mfma_f32_16x16x32_bf16 v[108:111], v[140:143], v[200:203], v[108:111]
	v_mfma_f32_16x16x32_bf16 v[96:99], v[132:135], v[208:211], v[96:99]
	v_mfma_f32_16x16x32_bf16 v[92:95], v[140:143], v[208:211], v[92:95]
	v_mfma_f32_16x16x32_bf16 v[80:83], v[132:135], v[216:219], v[80:83]
	v_mfma_f32_16x16x32_bf16 v[76:79], v[140:143], v[216:219], v[76:79]
	v_mfma_f32_16x16x32_bf16 v[128:131], v[136:139], v[196:199], v[128:131]
	v_mfma_f32_16x16x32_bf16 v[124:127], v[144:147], v[196:199], v[124:127]
	v_mfma_f32_16x16x32_bf16 v[112:115], v[136:139], v[204:207], v[112:115]
	v_mfma_f32_16x16x32_bf16 v[108:111], v[144:147], v[204:207], v[108:111]
	v_mfma_f32_16x16x32_bf16 v[96:99], v[136:139], v[212:215], v[96:99]
	v_mfma_f32_16x16x32_bf16 v[92:95], v[144:147], v[212:215], v[92:95]
	v_mfma_f32_16x16x32_bf16 v[80:83], v[136:139], v[220:223], v[80:83]
	v_mfma_f32_16x16x32_bf16 v[76:79], v[144:147], v[220:223], v[76:79]
	v_mfma_f32_16x16x32_bf16 v[120:123], v[158:161], v[192:195], v[120:123]
	v_mfma_f32_16x16x32_bf16 v[116:119], v[184:187], v[192:195], v[116:119]
	v_mfma_f32_16x16x32_bf16 v[104:107], v[158:161], v[200:203], v[104:107]
	v_mfma_f32_16x16x32_bf16 v[100:103], v[184:187], v[200:203], v[100:103]
	v_mfma_f32_16x16x32_bf16 v[88:91], v[158:161], v[208:211], v[88:91]
	v_mfma_f32_16x16x32_bf16 v[84:87], v[184:187], v[208:211], v[84:87]
	v_mfma_f32_16x16x32_bf16 v[72:75], v[158:161], v[216:219], v[72:75]
	v_mfma_f32_16x16x32_bf16 v[68:71], v[184:187], v[216:219], v[68:71]
	v_mfma_f32_16x16x32_bf16 v[120:123], v[162:165], v[196:199], v[120:123]
	v_mfma_f32_16x16x32_bf16 v[116:119], v[188:191], v[196:199], v[116:119]
	v_mfma_f32_16x16x32_bf16 v[104:107], v[162:165], v[204:207], v[104:107]
	v_mfma_f32_16x16x32_bf16 v[100:103], v[188:191], v[204:207], v[100:103]
	v_mfma_f32_16x16x32_bf16 v[88:91], v[162:165], v[212:215], v[88:91]
	v_mfma_f32_16x16x32_bf16 v[84:87], v[188:191], v[212:215], v[84:87]
	v_mfma_f32_16x16x32_bf16 v[72:75], v[162:165], v[220:223], v[72:75]
	v_mfma_f32_16x16x32_bf16 v[68:71], v[188:191], v[220:223], v[68:71]
	s_barrier
	s_add_i32 s64, s64, s48
	v_lshl_add_u64 v[170:171], s[18:19], 0, v[174:175]
	s_mov_b32 m0, s64
	ds_read_b128 v[192:195], v169 offset:16384
	ds_read_b128 v[196:199], v169 offset:17408
	ds_read_b128 v[200:203], v169 offset:18432
	ds_read_b128 v[204:207], v169 offset:19456
	ds_read_b128 v[208:211], v169 offset:20480
	ds_read_b128 v[212:215], v169 offset:21504
	ds_read_b128 v[216:219], v169 offset:22528
	ds_read_b128 v[220:223], v169 offset:23552
	global_load_lds_dwordx4 v[170:171], off
	s_add_i32 m0, s64, 0x2000
	s_add_u32 s64, s18, 0x80000
	v_lshl_add_u64 v[224:225], s[18:19], 0, v[148:149]
	s_addc_u32 s65, s19, 0
	s_add_i32 s66, s66, s48
	global_load_lds_dwordx4 v[224:225], off
	v_lshl_add_u64 v[226:227], s[64:65], 0, v[174:175]
	s_mov_b32 m0, s66
	v_lshl_add_u64 v[228:229], s[26:27], 0, v[150:151]
	global_load_lds_dwordx4 v[226:227], off
	v_lshl_add_u64 v[226:227], s[64:65], 0, v[148:149]
	s_add_i32 m0, s66, 0x2000
	s_nop 0
	global_load_lds_dwordx4 v[226:227], off
	v_lshl_add_u64 v[226:227], s[26:27], 0, v[152:153]
	s_mov_b32 m0, s49
	s_nop 0
	global_load_lds_dwordx4 v[226:227], off
	s_mov_b32 m0, s50
	s_nop 0
	global_load_lds_dwordx4 v[228:229], off
	s_waitcnt vmcnt(8)
	s_waitcnt lgkmcnt(0)
	s_barrier
	s_waitcnt lgkmcnt(0)
	v_mfma_f32_16x16x32_bf16 v[64:67], v[132:135], v[192:195], v[64:67]
	v_mfma_f32_16x16x32_bf16 v[60:63], v[140:143], v[192:195], v[60:63]
	v_mfma_f32_16x16x32_bf16 v[48:51], v[132:135], v[200:203], v[48:51]
	v_mfma_f32_16x16x32_bf16 v[44:47], v[140:143], v[200:203], v[44:47]
	v_mfma_f32_16x16x32_bf16 v[32:35], v[132:135], v[208:211], v[32:35]
	v_mfma_f32_16x16x32_bf16 v[28:31], v[140:143], v[208:211], v[28:31]
	v_mfma_f32_16x16x32_bf16 v[16:19], v[132:135], v[216:219], v[16:19]
	v_mfma_f32_16x16x32_bf16 v[12:15], v[140:143], v[216:219], v[12:15]
	v_mfma_f32_16x16x32_bf16 v[64:67], v[136:139], v[196:199], v[64:67]
	v_mfma_f32_16x16x32_bf16 v[60:63], v[144:147], v[196:199], v[60:63]
	v_mfma_f32_16x16x32_bf16 v[48:51], v[136:139], v[204:207], v[48:51]
	v_mfma_f32_16x16x32_bf16 v[44:47], v[144:147], v[204:207], v[44:47]
	v_mfma_f32_16x16x32_bf16 v[32:35], v[136:139], v[212:215], v[32:35]
	v_mfma_f32_16x16x32_bf16 v[28:31], v[144:147], v[212:215], v[28:31]
	v_mfma_f32_16x16x32_bf16 v[16:19], v[136:139], v[220:223], v[16:19]
	v_mfma_f32_16x16x32_bf16 v[12:15], v[144:147], v[220:223], v[12:15]
	v_mfma_f32_16x16x32_bf16 v[56:59], v[158:161], v[192:195], v[56:59]
	v_mfma_f32_16x16x32_bf16 v[52:55], v[184:187], v[192:195], v[52:55]
	v_mfma_f32_16x16x32_bf16 v[40:43], v[158:161], v[200:203], v[40:43]
	v_mfma_f32_16x16x32_bf16 v[36:39], v[184:187], v[200:203], v[36:39]
	v_mfma_f32_16x16x32_bf16 v[24:27], v[158:161], v[208:211], v[24:27]
	v_mfma_f32_16x16x32_bf16 v[20:23], v[184:187], v[208:211], v[20:23]
	v_mfma_f32_16x16x32_bf16 v[8:11], v[158:161], v[216:219], v[8:11]
	v_mfma_f32_16x16x32_bf16 v[4:7], v[184:187], v[216:219], v[4:7]
	v_mfma_f32_16x16x32_bf16 v[56:59], v[162:165], v[196:199], v[56:59]
	v_mfma_f32_16x16x32_bf16 v[52:55], v[188:191], v[196:199], v[52:55]
	v_mfma_f32_16x16x32_bf16 v[40:43], v[162:165], v[204:207], v[40:43]
	v_mfma_f32_16x16x32_bf16 v[36:39], v[188:191], v[204:207], v[36:39]
	v_mfma_f32_16x16x32_bf16 v[24:27], v[162:165], v[212:215], v[24:27]
	v_mfma_f32_16x16x32_bf16 v[20:23], v[188:191], v[212:215], v[20:23]
	v_mfma_f32_16x16x32_bf16 v[8:11], v[162:165], v[220:223], v[8:11]
	v_mfma_f32_16x16x32_bf16 v[4:7], v[188:191], v[220:223], v[4:7]
	s_barrier
; #define PG8_STAGE(bufoff, gbase, voff) do { _Pragma("unroll") for (int _i = 0; _i < 2; ++_i) \
;         __builtin_amdgcn_global_load_lds((const unsigned*)((const char*)(gbase) + (voff)[_i]), (PG8_LAS unsigned*)(lds + (bufoff) + ldsw + _i * 8192), 16, 0, 0); } while (0)
; #define PG8_LDA(dst, b, h) do { _Pragma("unroll") for (int m = 0; m < 4; ++m) _Pragma("unroll") for (int k = 0; k < 2; ++k) dst[m][k] = *(const PG8_LAS bf16x8*)(lds + PG8_SA(b, h) + aoff + m * 2048 + k * 1024); } while (0)
; #define PG8_LDB(dst, b, h) do { _Pragma("unroll") for (int n = 0; n < 2; ++n) _Pragma("unroll") for (int k = 0; k < 2; ++k) dst[n][k] = *(const PG8_LAS bf16x8*)(lds + PG8_SB(b, h) + boff + n * 2048 + k * 1024); } while (0)
; #define PG8_MMA(ai, bj, At, Bt) do { __builtin_amdgcn_s_setprio(1); _Pragma("unroll") for (int m = 0; m < 4; ++m) _Pragma("unroll") for (int n = 0; n < 2; ++n) _Pragma("unroll") for (int k = 0; k < 2; ++k) \
;         acc[ai][bj][m][n] = __builtin_amdgcn_mfma_f32_16x16x32_bf16(Bt[n][k], At[m][k], acc[ai][bj][m][n], 0, 0, 0); __builtin_amdgcn_s_setprio(0); } while (0)
; #define PG8_WAIT_V(n) asm volatile("s_waitcnt vmcnt(" #n ")" ::: "memory")
; #define PG8_WAIT_L(n) asm volatile("s_waitcnt lgkmcnt(" #n ")" ::: "memory")
; #define PG8_BAR __builtin_amdgcn_s_barrier()
; #define PG8_SCHED __builtin_amdgcn_sched_barrier(0)
; template <class Epi, class Sched, bool ALIGN_EPI = false, bool SP2 = false>
; __device__ __forceinline__ void gemm_phase(PG8_LAS unsigned char* lds, const Gemm g, const Sched& S, const Epi& E) {
;     ...
;             PG8_LDB(B0, 1, 0); PG8_LDB(B1, 1, 1); PG8_SCHED; PG8_LDA(At, 1, 0); PG8_STAGE(PG8_SA(0, 1), a2 + hstep, voffA);
;             PG8_WAIT_V(8); PG8_WAIT_L(0); PG8_BAR; PG8_MMA(0, 0, At, B0); PG8_MMA(0, 1, At, B1); PG8_BAR; PG8_SCHED;
	s_add_i32 s64, 0, 0x18000
	s_add_i32 s65, 0, 0x1c000
	v_add_u32_e32 v144, s64, v167
	v_add_u32_e32 v179, s65, v167
	ds_read_b128 v[132:135], v144
	ds_read_b128 v[136:139], v144 offset:1024
	ds_read_b128 v[140:143], v144 offset:2048
	ds_read_b128 v[144:147], v144 offset:3072
	ds_read_b128 v[158:161], v179
	ds_read_b128 v[162:165], v179 offset:1024
	ds_read_b128 v[184:187], v179 offset:2048
	ds_read_b128 v[188:191], v179 offset:3072
	s_add_u32 s26, s26, 0x80000
	s_addc_u32 s27, s27, 0
	s_mov_b32 m0, s51
	v_lshl_add_u64 v[230:231], s[26:27], 0, v[152:153]
	ds_read_b128 v[192:195], v169 offset:32768
	ds_read_b128 v[196:199], v169 offset:33792
	ds_read_b128 v[200:203], v169 offset:34816
	ds_read_b128 v[204:207], v169 offset:35840
	ds_read_b128 v[208:211], v169 offset:36864
	ds_read_b128 v[212:215], v169 offset:37888
	ds_read_b128 v[216:219], v169 offset:38912
	ds_read_b128 v[220:223], v169 offset:39936
	global_load_lds_dwordx4 v[230:231], off
	v_lshl_add_u64 v[230:231], s[26:27], 0, v[150:151]
	s_mov_b32 m0, s52
	s_nop 0
	global_load_lds_dwordx4 v[230:231], off
	s_waitcnt vmcnt(8)
	s_waitcnt lgkmcnt(0)
	s_barrier
	s_waitcnt lgkmcnt(0)
	v_mfma_f32_16x16x32_bf16 v[128:131], v[132:135], v[192:195], v[128:131]
	v_mfma_f32_16x16x32_bf16 v[124:127], v[140:143], v[192:195], v[124:127]
	v_mfma_f32_16x16x32_bf16 v[112:115], v[132:135], v[200:203], v[112:115]
	v_mfma_f32_16x16x32_bf16 v[108:111], v[140:143], v[200:203], v[108:111]
	v_mfma_f32_16x16x32_bf16 v[96:99], v[132:135], v[208:211], v[96:99]
	v_mfma_f32_16x16x32_bf16 v[92:95], v[140:143], v[208:211], v[92:95]
	v_mfma_f32_16x16x32_bf16 v[80:83], v[132:135], v[216:219], v[80:83]
	v_mfma_f32_16x16x32_bf16 v[76:79], v[140:143], v[216:219], v[76:79]
	v_mfma_f32_16x16x32_bf16 v[128:131], v[136:139], v[196:199], v[128:131]
	v_mfma_f32_16x16x32_bf16 v[124:127], v[144:147], v[196:199], v[124:127]
	v_mfma_f32_16x16x32_bf16 v[112:115], v[136:139], v[204:207], v[112:115]
	v_mfma_f32_16x16x32_bf16 v[108:111], v[144:147], v[204:207], v[108:111]
	v_mfma_f32_16x16x32_bf16 v[96:99], v[136:139], v[212:215], v[96:99]
	v_mfma_f32_16x16x32_bf16 v[92:95], v[144:147], v[212:215], v[92:95]
	v_mfma_f32_16x16x32_bf16 v[80:83], v[136:139], v[220:223], v[80:83]
	v_mfma_f32_16x16x32_bf16 v[76:79], v[144:147], v[220:223], v[76:79]
	v_mfma_f32_16x16x32_bf16 v[120:123], v[158:161], v[192:195], v[120:123]
	v_mfma_f32_16x16x32_bf16 v[116:119], v[184:187], v[192:195], v[116:119]
	v_mfma_f32_16x16x32_bf16 v[104:107], v[158:161], v[200:203], v[104:107]
	v_mfma_f32_16x16x32_bf16 v[100:103], v[184:187], v[200:203], v[100:103]
	v_mfma_f32_16x16x32_bf16 v[88:91], v[158:161], v[208:211], v[88:91]
	v_mfma_f32_16x16x32_bf16 v[84:87], v[184:187], v[208:211], v[84:87]
	v_mfma_f32_16x16x32_bf16 v[72:75], v[158:161], v[216:219], v[72:75]
	v_mfma_f32_16x16x32_bf16 v[68:71], v[184:187], v[216:219], v[68:71]
	v_mfma_f32_16x16x32_bf16 v[120:123], v[162:165], v[196:199], v[120:123]
	v_mfma_f32_16x16x32_bf16 v[116:119], v[188:191], v[196:199], v[116:119]
	v_mfma_f32_16x16x32_bf16 v[104:107], v[162:165], v[204:207], v[104:107]
	v_mfma_f32_16x16x32_bf16 v[100:103], v[188:191], v[204:207], v[100:103]
	v_mfma_f32_16x16x32_bf16 v[88:91], v[162:165], v[212:215], v[88:91]
	v_mfma_f32_16x16x32_bf16 v[84:87], v[188:191], v[212:215], v[84:87]
	v_mfma_f32_16x16x32_bf16 v[72:75], v[162:165], v[220:223], v[72:75]
	v_mfma_f32_16x16x32_bf16 v[68:71], v[188:191], v[220:223], v[68:71]
	s_barrier
; #define PG8_STAGE(bufoff, gbase, voff) do { _Pragma("unroll") for (int _i = 0; _i < 2; ++_i) \
;         __builtin_amdgcn_global_load_lds((const unsigned*)((const char*)(gbase) + (voff)[_i]), (PG8_LAS unsigned*)(lds + (bufoff) + ldsw + _i * 8192), 16, 0, 0); } while (0)
; #define PG8_LDA(dst, b, h) do { _Pragma("unroll") for (int m = 0; m < 4; ++m) _Pragma("unroll") for (int k = 0; k < 2; ++k) dst[m][k] = *(const PG8_LAS bf16x8*)(lds + PG8_SA(b, h) + aoff + m * 2048 + k * 1024); } while (0)
; #define PG8_MMA(ai, bj, At, Bt) do { __builtin_amdgcn_s_setprio(1); _Pragma("unroll") for (int m = 0; m < 4; ++m) _Pragma("unroll") for (int n = 0; n < 2; ++n) _Pragma("unroll") for (int k = 0; k < 2; ++k) \
;         acc[ai][bj][m][n] = __builtin_amdgcn_mfma_f32_16x16x32_bf16(Bt[n][k], At[m][k], acc[ai][bj][m][n], 0, 0, 0); __builtin_amdgcn_s_setprio(0); } while (0)
; #define PG8_WAIT_V(n) asm volatile("s_waitcnt vmcnt(" #n ")" ::: "memory")
; #define PG8_WAIT_L(n) asm volatile("s_waitcnt lgkmcnt(" #n ")" ::: "memory")
; #define PG8_BAR __builtin_amdgcn_s_barrier()
; #define PG8_SCHED __builtin_amdgcn_sched_barrier(0)
; template <class Epi, class Sched, bool ALIGN_EPI = false, bool SP2 = false>
; __device__ __forceinline__ void gemm_phase(PG8_LAS unsigned char* lds, const Gemm g, const Sched& S, const Epi& E) {
;     ...
;             PG8_LDA(At, 1, 1); PG8_STAGE(PG8_SB(1, 0), b3, voffB); PG8_STAGE(PG8_SB(1, 1), b3 + hstep, voffB); PG8_STAGE(PG8_SA(1, 0), a3, voffA);
;             PG8_WAIT_V(8); PG8_WAIT_L(0); PG8_BAR; PG8_MMA(1, 0, At, B0); PG8_MMA(1, 1, At, B1); PG8_BAR; PG8_SCHED;
	s_add_i32 s26, s64, s48
	v_lshl_add_u64 v[170:171], v[170:171], 0, s[10:11]
	s_mov_b32 m0, s26
	ds_read_b128 v[192:195], v169 offset:49152
	ds_read_b128 v[196:199], v169 offset:50176
	ds_read_b128 v[200:203], v169 offset:51200
	ds_read_b128 v[204:207], v169 offset:52224
	ds_read_b128 v[208:211], v169 offset:53248
	ds_read_b128 v[212:215], v169 offset:54272
	ds_read_b128 v[216:219], v169 offset:55296
	ds_read_b128 v[220:223], v169 offset:56320
	global_load_lds_dwordx4 v[170:171], off
	s_add_i32 m0, s26, 0x2000
	s_add_u32 s18, s18, 0x80080
	v_lshl_add_u64 v[170:171], v[224:225], 0, s[10:11]
	s_addc_u32 s19, s19, 0
	s_add_i32 s26, s65, s48
	global_load_lds_dwordx4 v[170:171], off
	v_lshl_add_u64 v[170:171], s[18:19], 0, v[174:175]
	s_mov_b32 m0, s26
	s_nop 0
	global_load_lds_dwordx4 v[170:171], off
	v_lshl_add_u64 v[170:171], s[18:19], 0, v[148:149]
	s_add_i32 m0, s26, 0x2000
	s_nop 0
	global_load_lds_dwordx4 v[170:171], off
	v_lshl_add_u64 v[170:171], v[226:227], 0, s[10:11]
	s_mov_b32 m0, s54
	s_nop 0
	global_load_lds_dwordx4 v[170:171], off
	v_lshl_add_u64 v[170:171], v[228:229], 0, s[10:11]
	s_mov_b32 m0, s55
	s_nop 0
	global_load_lds_dwordx4 v[170:171], off
	s_waitcnt vmcnt(8)
	s_waitcnt lgkmcnt(0)
	s_barrier
	s_waitcnt lgkmcnt(0)
	v_mfma_f32_16x16x32_bf16 v[64:67], v[132:135], v[192:195], v[64:67]
	v_mfma_f32_16x16x32_bf16 v[60:63], v[140:143], v[192:195], v[60:63]
	v_mfma_f32_16x16x32_bf16 v[48:51], v[132:135], v[200:203], v[48:51]
	v_mfma_f32_16x16x32_bf16 v[44:47], v[140:143], v[200:203], v[44:47]
	v_mfma_f32_16x16x32_bf16 v[32:35], v[132:135], v[208:211], v[32:35]
	v_mfma_f32_16x16x32_bf16 v[28:31], v[140:143], v[208:211], v[28:31]
	v_mfma_f32_16x16x32_bf16 v[16:19], v[132:135], v[216:219], v[16:19]
	v_mfma_f32_16x16x32_bf16 v[12:15], v[140:143], v[216:219], v[12:15]
	v_mfma_f32_16x16x32_bf16 v[64:67], v[136:139], v[196:199], v[64:67]
	v_mfma_f32_16x16x32_bf16 v[60:63], v[144:147], v[196:199], v[60:63]
	v_mfma_f32_16x16x32_bf16 v[48:51], v[136:139], v[204:207], v[48:51]
	v_mfma_f32_16x16x32_bf16 v[44:47], v[144:147], v[204:207], v[44:47]
	v_mfma_f32_16x16x32_bf16 v[32:35], v[136:139], v[212:215], v[32:35]
	v_mfma_f32_16x16x32_bf16 v[28:31], v[144:147], v[212:215], v[28:31]
	v_mfma_f32_16x16x32_bf16 v[16:19], v[136:139], v[220:223], v[16:19]
	v_mfma_f32_16x16x32_bf16 v[12:15], v[144:147], v[220:223], v[12:15]
	v_mfma_f32_16x16x32_bf16 v[56:59], v[158:161], v[192:195], v[56:59]
	v_mfma_f32_16x16x32_bf16 v[52:55], v[184:187], v[192:195], v[52:55]
	v_mfma_f32_16x16x32_bf16 v[40:43], v[158:161], v[200:203], v[40:43]
	v_mfma_f32_16x16x32_bf16 v[36:39], v[184:187], v[200:203], v[36:39]
	v_mfma_f32_16x16x32_bf16 v[24:27], v[158:161], v[208:211], v[24:27]
	v_mfma_f32_16x16x32_bf16 v[20:23], v[184:187], v[208:211], v[20:23]
	v_mfma_f32_16x16x32_bf16 v[8:11], v[158:161], v[216:219], v[8:11]
	v_mfma_f32_16x16x32_bf16 v[4:7], v[184:187], v[216:219], v[4:7]
	v_mfma_f32_16x16x32_bf16 v[56:59], v[162:165], v[196:199], v[56:59]
	v_mfma_f32_16x16x32_bf16 v[52:55], v[188:191], v[196:199], v[52:55]
	v_mfma_f32_16x16x32_bf16 v[40:43], v[162:165], v[204:207], v[40:43]
	v_mfma_f32_16x16x32_bf16 v[36:39], v[188:191], v[204:207], v[36:39]
	v_mfma_f32_16x16x32_bf16 v[24:27], v[162:165], v[212:215], v[24:27]
	v_mfma_f32_16x16x32_bf16 v[20:23], v[188:191], v[212:215], v[20:23]
	v_mfma_f32_16x16x32_bf16 v[8:11], v[162:165], v[220:223], v[8:11]
	v_mfma_f32_16x16x32_bf16 v[4:7], v[188:191], v[220:223], v[4:7]
	s_barrier
	s_add_i32 s63, s63, 2
	s_add_u32 s61, s61, 0x100
	s_addc_u32 s62, s62, 0
	s_add_u32 s0, s0, 0x100
	s_addc_u32 s1, s1, 0
	s_cmp_gt_u32 s63, 29
	s_cbranch_scc0 .LBB0_563
	s_and_b64 vcc, exec, s[34:35]
	s_cbranch_vccz .LBB0_566
	s_barrier

; #define PG8_STAGE(bufoff, gbase, voff) do { _Pragma("unroll") for (int _i = 0; _i < 2; ++_i) \
;         __builtin_amdgcn_global_load_lds((const unsigned*)((const char*)(gbase) + (voff)[_i]), (PG8_LAS unsigned*)(lds + (bufoff) + ldsw + _i * 8192), 16, 0, 0); } while (0)
; #define PG8_LDA(dst, b, h) do { _Pragma("unroll") for (int m = 0; m < 4; ++m) _Pragma("unroll") for (int k = 0; k < 2; ++k) dst[m][k] = *(const PG8_LAS bf16x8*)(lds + PG8_SA(b, h) + aoff + m * 2048 + k * 1024); } while (0)
; #define PG8_LDB(dst, b, h) do { _Pragma("unroll") for (int n = 0; n < 2; ++n) _Pragma("unroll") for (int k = 0; k < 2; ++k) dst[n][k] = *(const PG8_LAS bf16x8*)(lds + PG8_SB(b, h) + boff + n * 2048 + k * 1024); } while (0)
; #define PG8_SCHED __builtin_amdgcn_sched_barrier(0)
; template <class Epi, class Sched, bool ALIGN_EPI = false, bool SP2 = false>
; __device__ __forceinline__ void gemm_phase(PG8_LAS unsigned char* lds, const Gemm g, const Sched& S, const Epi& E) {
;     ...
;         const bool has_next = S.next(ui + 1, nxt);
;         const char* nA = has_next ? (const char*)g.A + (size_t)nxt.pm * tstep : cA; const char* nB = has_next ? (const char*)g.Bt + (size_t)nxt.pn * tstep : cB;
;         for (int t = 0; t < nt; t += 2) {
;             const bool last = (t == nt - 2);
;             const char* a1 = cA + (size_t)(t + 1) * kstep;
;             const char* a2 = last ? nA : cA + (size_t)(t + 2) * kstep; const char* b2 = last ? nB : cB + (size_t)(t + 2) * kstep;
;             const char* a3 = a2 + kstep; const char* b3 = b2 + kstep;
;             if (last && has_next) S.a_ready(nxt);
;             if constexpr (SP2) {
;             PG8_LDB(B0, 0, 0); PG8_LDB(B1, 0, 1); PG8_SCHED; PG8_LDA(At, 0, 0); PG8_STAGE(PG8_SA(1, 1), a1 + hstep, voffA);
;     ...
;         for (int a = 0; a < 2; ++a)
; #pragma unroll
;             for (int b = 0; b < 2; ++b)
; #pragma unroll
;                 for (int m = 0; m < 4; ++m)
; #pragma unroll
;                     for (int n = 0; n < 2; ++n) acc[a][b][m][n] = (f32x4){0.f, 0.f, 0.f, 0.f};
.LBB0_659:
	s_ashr_i32 s65, s64, 31
	s_lshl_b64 s[16:17], s[64:65], 20
	s_add_u32 s66, s19, s16
	s_addc_u32 s67, s20, s17
	s_and_b64 s[16:17], s[40:41], exec
	s_cselect_b32 s23, s67, s15
	s_cselect_b32 s24, s66, s14
	s_ashr_i32 s63, s62, 31
	s_lshl_b64 s[16:17], s[62:63], 20
	s_add_u32 s68, s26, s16
	s_addc_u32 s69, s27, s17
	s_and_b64 s[16:17], s[40:41], exec
	s_cselect_b32 s25, s69, s1
	s_cselect_b32 s42, s68, s0
	s_add_u32 s43, s0, 0x100
	s_addc_u32 s44, s1, 0
	s_add_u32 s0, s14, 0x80080
	v_mov_b32_e32 v4, 0
	s_addc_u32 s1, s15, 0
	s_mov_b32 s45, -2
	v_mov_b32_e32 v5, v4
	v_mov_b32_e32 v6, v4
	v_mov_b32_e32 v7, v4
	v_mov_b32_e32 v8, v4
	v_mov_b32_e32 v9, v4
	v_mov_b32_e32 v10, v4
	v_mov_b32_e32 v11, v4
	v_mov_b32_e32 v12, v4
	v_mov_b32_e32 v13, v4
	v_mov_b32_e32 v14, v4
	v_mov_b32_e32 v15, v4
	v_mov_b32_e32 v16, v4
	v_mov_b32_e32 v17, v4
	v_mov_b32_e32 v18, v4
	v_mov_b32_e32 v19, v4
	v_mov_b32_e32 v20, v4
	v_mov_b32_e32 v21, v4
	v_mov_b32_e32 v22, v4
	v_mov_b32_e32 v23, v4
	v_mov_b32_e32 v24, v4
	v_mov_b32_e32 v25, v4
	v_mov_b32_e32 v26, v4
	v_mov_b32_e32 v27, v4
	s_waitcnt vmcnt(0)
	v_mov_b32_e32 v28, v4
	v_mov_b32_e32 v29, v4
	v_mov_b32_e32 v30, v4
	v_mov_b32_e32 v31, v4
	v_mov_b32_e32 v32, v4
	v_mov_b32_e32 v33, v4
	v_mov_b32_e32 v34, v4
	v_mov_b32_e32 v35, v4
	v_mov_b32_e32 v88, v4
	v_mov_b32_e32 v89, v4
	v_mov_b32_e32 v90, v4
	v_mov_b32_e32 v91, v4
	v_mov_b32_e32 v92, v4
	v_mov_b32_e32 v93, v4
	v_mov_b32_e32 v94, v4
	v_mov_b32_e32 v95, v4
	v_mov_b32_e32 v52, v4
	v_mov_b32_e32 v53, v4
	v_mov_b32_e32 v54, v4
	v_mov_b32_e32 v55, v4
	v_mov_b32_e32 v56, v4
	v_mov_b32_e32 v57, v4
	v_mov_b32_e32 v58, v4
	v_mov_b32_e32 v59, v4
	v_mov_b32_e32 v60, v4
	v_mov_b32_e32 v61, v4
	v_mov_b32_e32 v62, v4
	v_mov_b32_e32 v63, v4
	v_mov_b32_e32 v64, v4
	v_mov_b32_e32 v65, v4
	v_mov_b32_e32 v66, v4
	v_mov_b32_e32 v67, v4
	v_mov_b32_e32 v68, v4
	v_mov_b32_e32 v69, v4
	v_mov_b32_e32 v70, v4
	v_mov_b32_e32 v71, v4
	v_mov_b32_e32 v72, v4
	v_mov_b32_e32 v73, v4
	v_mov_b32_e32 v74, v4
	v_mov_b32_e32 v75, v4
	v_mov_b32_e32 v100, v4
	v_mov_b32_e32 v101, v4
	v_mov_b32_e32 v102, v4
	v_mov_b32_e32 v103, v4
	v_mov_b32_e32 v104, v4
	v_mov_b32_e32 v105, v4
	v_mov_b32_e32 v106, v4
	v_mov_b32_e32 v107, v4
	v_mov_b32_e32 v108, v4
	v_mov_b32_e32 v109, v4
	v_mov_b32_e32 v110, v4
	v_mov_b32_e32 v111, v4
	v_mov_b32_e32 v112, v4
	v_mov_b32_e32 v113, v4
	v_mov_b32_e32 v114, v4
	v_mov_b32_e32 v115, v4
	v_mov_b32_e32 v116, v4
	v_mov_b32_e32 v117, v4
	v_mov_b32_e32 v118, v4
	v_mov_b32_e32 v119, v4
	v_mov_b32_e32 v120, v4
	v_mov_b32_e32 v121, v4
	v_mov_b32_e32 v122, v4
	v_mov_b32_e32 v123, v4
	v_mov_b32_e32 v140, v4
	v_mov_b32_e32 v141, v4
	v_mov_b32_e32 v142, v4
	v_mov_b32_e32 v143, v4
	v_mov_b32_e32 v144, v4
	v_mov_b32_e32 v145, v4
	v_mov_b32_e32 v146, v4
	v_mov_b32_e32 v147, v4
	v_mov_b32_e32 v156, v4
	v_mov_b32_e32 v157, v4
	v_mov_b32_e32 v158, v4
	v_mov_b32_e32 v159, v4
	v_mov_b32_e32 v160, v4
	v_mov_b32_e32 v161, v4
	v_mov_b32_e32 v162, v4
	v_mov_b32_e32 v163, v4
	v_mov_b32_e32 v124, v4
	v_mov_b32_e32 v125, v4
	v_mov_b32_e32 v126, v4
	v_mov_b32_e32 v127, v4
	v_mov_b32_e32 v128, v4
	v_mov_b32_e32 v129, v4
	v_mov_b32_e32 v130, v4
	v_mov_b32_e32 v131, v4
	v_mov_b32_e32 v132, v4
	v_mov_b32_e32 v133, v4
	v_mov_b32_e32 v134, v4
	v_mov_b32_e32 v135, v4
	v_mov_b32_e32 v136, v4
	v_mov_b32_e32 v137, v4
	v_mov_b32_e32 v138, v4
	v_mov_b32_e32 v139, v4
	v_mov_b32_e32 v148, v4
	v_mov_b32_e32 v149, v4
	v_mov_b32_e32 v150, v4
	v_mov_b32_e32 v151, v4
	v_mov_b32_e32 v152, v4
	v_mov_b32_e32 v153, v4
	v_mov_b32_e32 v154, v4
	v_mov_b32_e32 v155, v4
	v_readfirstlane_b32 s101, v172
	s_nop 3
	s_cmp_ge_u32 s101, 0x100
	s_cbranch_scc1 .Lprio_hi_660
	s_setprio 1
	s_branch .Lprio_done_660
.Lprio_hi_660:
	s_setprio 0
.Lprio_done_660:
.LBB0_660:
	s_add_u32 s14, s0, 0xfff80080
	s_addc_u32 s15, s1, -1
	s_add_i32 s46, 0, 0x10000
	s_cmp_eq_u32 s45, 28
	s_cselect_b32 s17, s23, s15
	s_cselect_b32 s16, s24, s14
	s_cselect_b32 s15, s25, s44
	s_cselect_b32 s14, s42, s43
	s_add_i32 s63, 0, 0x14000
	v_add_u32_e32 v48, s46, v243
	v_add_u32_e32 v96, s63, v243
	ds_read_b128 v[36:39], v48
	ds_read_b128 v[40:43], v48 offset:1024
	ds_read_b128 v[44:47], v48 offset:2048
	ds_read_b128 v[48:51], v48 offset:3072
	ds_read_b128 v[76:79], v96
	ds_read_b128 v[80:83], v96 offset:1024
	ds_read_b128 v[84:87], v96 offset:2048
	ds_read_b128 v[96:99], v96 offset:3072
	v_lshl_add_u64 v[224:225], s[0:1], 0, v[198:199]
	s_add_i32 m0, s29, 0xc000
	ds_read_b128 v[164:167], v249
	ds_read_b128 v[168:171], v249 offset:1024
	ds_read_b128 v[200:203], v249 offset:2048
	ds_read_b128 v[204:207], v249 offset:3072
	ds_read_b128 v[208:211], v249 offset:4096
	ds_read_b128 v[212:215], v249 offset:5120
	ds_read_b128 v[216:219], v249 offset:6144
	ds_read_b128 v[220:223], v249 offset:7168
	global_load_lds_dwordx4 v[224:225], off
	v_lshl_add_u64 v[224:225], s[0:1], 0, v[196:197]
	s_add_i32 m0, s29, 0xe000
	s_nop 0
	global_load_lds_dwordx4 v[224:225], off
	s_waitcnt vmcnt(8)
	s_waitcnt lgkmcnt(0)
	s_barrier
; #define PG8_STAGE(bufoff, gbase, voff) do { _Pragma("unroll") for (int _i = 0; _i < 2; ++_i) \
;         __builtin_amdgcn_global_load_lds((const unsigned*)((const char*)(gbase) + (voff)[_i]), (PG8_LAS unsigned*)(lds + (bufoff) + ldsw + _i * 8192), 16, 0, 0); } while (0)
; #define PG8_LDA(dst, b, h) do { _Pragma("unroll") for (int m = 0; m < 4; ++m) _Pragma("unroll") for (int k = 0; k < 2; ++k) dst[m][k] = *(const PG8_LAS bf16x8*)(lds + PG8_SA(b, h) + aoff + m * 2048 + k * 1024); } while (0)
; #define PG8_MMA(ai, bj, At, Bt) do { __builtin_amdgcn_s_setprio(1); _Pragma("unroll") for (int m = 0; m < 4; ++m) _Pragma("unroll") for (int n = 0; n < 2; ++n) _Pragma("unroll") for (int k = 0; k < 2; ++k) \
;         acc[ai][bj][m][n] = __builtin_amdgcn_mfma_f32_16x16x32_bf16(Bt[n][k], At[m][k], acc[ai][bj][m][n], 0, 0, 0); __builtin_amdgcn_s_setprio(0); } while (0)
; #define PG8_WAIT_V(n) asm volatile("s_waitcnt vmcnt(" #n ")" ::: "memory")
; #define PG8_WAIT_L(n) asm volatile("s_waitcnt lgkmcnt(" #n ")" ::: "memory")
; #define PG8_BAR __builtin_amdgcn_s_barrier()
; #define PG8_SCHED __builtin_amdgcn_sched_barrier(0)
; template <class Epi, class Sched, bool ALIGN_EPI = false, bool SP2 = false>
; __device__ __forceinline__ void gemm_phase(PG8_LAS unsigned char* lds, const Gemm g, const Sched& S, const Epi& E) {
;     ...
;             PG8_WAIT_V(8); PG8_WAIT_L(0); PG8_BAR; PG8_MMA(0, 0, At, B0); PG8_MMA(0, 1, At, B1); PG8_BAR; PG8_SCHED;
;             PG8_LDA(At, 0, 1); PG8_STAGE(PG8_SB(0, 0), b2, voffB); PG8_STAGE(PG8_SB(0, 1), b2 + hstep, voffB); PG8_STAGE(PG8_SA(0, 0), a2, voffA);
;             PG8_WAIT_V(8); PG8_WAIT_L(0); PG8_BAR; PG8_MMA(1, 0, At, B0); PG8_MMA(1, 1, At, B1); PG8_BAR; PG8_SCHED;
	s_waitcnt lgkmcnt(0)
	v_mfma_f32_16x16x32_bf16 v[152:155], v[36:39], v[164:167], v[152:155]
	v_mfma_f32_16x16x32_bf16 v[148:151], v[44:47], v[164:167], v[148:151]
	v_mfma_f32_16x16x32_bf16 v[136:139], v[36:39], v[200:203], v[136:139]
	v_mfma_f32_16x16x32_bf16 v[132:135], v[44:47], v[200:203], v[132:135]
	v_mfma_f32_16x16x32_bf16 v[128:131], v[36:39], v[208:211], v[128:131]
	v_mfma_f32_16x16x32_bf16 v[124:127], v[44:47], v[208:211], v[124:127]
	v_mfma_f32_16x16x32_bf16 v[160:163], v[36:39], v[216:219], v[160:163]
	v_mfma_f32_16x16x32_bf16 v[156:159], v[44:47], v[216:219], v[156:159]
	v_mfma_f32_16x16x32_bf16 v[152:155], v[40:43], v[168:171], v[152:155]
	v_mfma_f32_16x16x32_bf16 v[148:151], v[48:51], v[168:171], v[148:151]
	v_mfma_f32_16x16x32_bf16 v[136:139], v[40:43], v[204:207], v[136:139]
	v_mfma_f32_16x16x32_bf16 v[132:135], v[48:51], v[204:207], v[132:135]
	v_mfma_f32_16x16x32_bf16 v[128:131], v[40:43], v[212:215], v[128:131]
	v_mfma_f32_16x16x32_bf16 v[124:127], v[48:51], v[212:215], v[124:127]
	v_mfma_f32_16x16x32_bf16 v[160:163], v[40:43], v[220:223], v[160:163]
	v_mfma_f32_16x16x32_bf16 v[156:159], v[48:51], v[220:223], v[156:159]
	v_mfma_f32_16x16x32_bf16 v[144:147], v[76:79], v[164:167], v[144:147]
	v_mfma_f32_16x16x32_bf16 v[140:143], v[84:87], v[164:167], v[140:143]
	v_mfma_f32_16x16x32_bf16 v[120:123], v[76:79], v[200:203], v[120:123]
	v_mfma_f32_16x16x32_bf16 v[116:119], v[84:87], v[200:203], v[116:119]
	v_mfma_f32_16x16x32_bf16 v[112:115], v[76:79], v[208:211], v[112:115]
	v_mfma_f32_16x16x32_bf16 v[108:111], v[84:87], v[208:211], v[108:111]
	v_mfma_f32_16x16x32_bf16 v[104:107], v[76:79], v[216:219], v[104:107]
	v_mfma_f32_16x16x32_bf16 v[100:103], v[84:87], v[216:219], v[100:103]
	v_mfma_f32_16x16x32_bf16 v[144:147], v[80:83], v[168:171], v[144:147]
	v_mfma_f32_16x16x32_bf16 v[140:143], v[96:99], v[168:171], v[140:143]
	v_mfma_f32_16x16x32_bf16 v[120:123], v[80:83], v[204:207], v[120:123]
	v_mfma_f32_16x16x32_bf16 v[116:119], v[96:99], v[204:207], v[116:119]
	v_mfma_f32_16x16x32_bf16 v[112:115], v[80:83], v[212:215], v[112:115]
	v_mfma_f32_16x16x32_bf16 v[108:111], v[96:99], v[212:215], v[108:111]
	v_mfma_f32_16x16x32_bf16 v[104:107], v[80:83], v[220:223], v[104:107]
	v_mfma_f32_16x16x32_bf16 v[100:103], v[96:99], v[220:223], v[100:103]
	s_barrier
	s_add_i32 s46, s46, s28
	v_lshl_add_u64 v[232:233], s[14:15], 0, v[188:189]
	s_mov_b32 m0, s46
	ds_read_b128 v[164:167], v249 offset:16384
	ds_read_b128 v[168:171], v249 offset:17408
	ds_read_b128 v[200:203], v249 offset:18432
	ds_read_b128 v[204:207], v249 offset:19456
	ds_read_b128 v[208:211], v249 offset:20480
	ds_read_b128 v[212:215], v249 offset:21504
	ds_read_b128 v[216:219], v249 offset:22528
	ds_read_b128 v[220:223], v249 offset:23552
	global_load_lds_dwordx4 v[232:233], off
	s_add_i32 m0, s46, 0x2000
	s_add_u32 s46, s14, 0x80000
	v_lshl_add_u64 v[234:235], s[14:15], 0, v[184:185]
	s_addc_u32 s47, s15, 0
	s_add_i32 s63, s63, s28
	global_load_lds_dwordx4 v[234:235], off
	v_lshl_add_u64 v[224:225], s[46:47], 0, v[188:189]
	s_mov_b32 m0, s63
	v_lshl_add_u64 v[236:237], s[16:17], 0, v[190:191]
	global_load_lds_dwordx4 v[224:225], off
	v_lshl_add_u64 v[224:225], s[46:47], 0, v[184:185]
	s_add_i32 m0, s63, 0x2000
	v_lshl_add_u64 v[250:251], s[16:17], 0, v[186:187]
	global_load_lds_dwordx4 v[224:225], off
	s_mov_b32 m0, s29
	s_nop 0
	global_load_lds_dwordx4 v[236:237], off
	s_mov_b32 m0, s30
	s_nop 0
	global_load_lds_dwordx4 v[250:251], off
	s_waitcnt vmcnt(8)
	s_waitcnt lgkmcnt(0)
	s_barrier
	s_waitcnt lgkmcnt(0)
	v_mfma_f32_16x16x32_bf16 v[72:75], v[36:39], v[164:167], v[72:75]
	v_mfma_f32_16x16x32_bf16 v[68:71], v[44:47], v[164:167], v[68:71]
	v_mfma_f32_16x16x32_bf16 v[64:67], v[36:39], v[200:203], v[64:67]
	v_mfma_f32_16x16x32_bf16 v[60:63], v[44:47], v[200:203], v[60:63]
	v_mfma_f32_16x16x32_bf16 v[56:59], v[36:39], v[208:211], v[56:59]
	v_mfma_f32_16x16x32_bf16 v[52:55], v[44:47], v[208:211], v[52:55]
	v_mfma_f32_16x16x32_bf16 v[36:39], v[36:39], v[216:219], v[92:95]
	v_mfma_f32_16x16x32_bf16 v[72:75], v[40:43], v[168:171], v[72:75]
	v_mfma_f32_16x16x32_bf16 v[68:71], v[48:51], v[168:171], v[68:71]
	v_mfma_f32_16x16x32_bf16 v[64:67], v[40:43], v[204:207], v[64:67]
	v_mfma_f32_16x16x32_bf16 v[60:63], v[48:51], v[204:207], v[60:63]
	v_mfma_f32_16x16x32_bf16 v[56:59], v[40:43], v[212:215], v[56:59]
	v_mfma_f32_16x16x32_bf16 v[52:55], v[48:51], v[212:215], v[52:55]
	v_mfma_f32_16x16x32_bf16 v[36:39], v[40:43], v[220:223], v[36:39]
	v_mfma_f32_16x16x32_bf16 v[40:43], v[44:47], v[216:219], v[88:91]
	v_mfma_f32_16x16x32_bf16 v[40:43], v[48:51], v[220:223], v[40:43]
	v_mfma_f32_16x16x32_bf16 v[32:35], v[76:79], v[164:167], v[32:35]
	v_mfma_f32_16x16x32_bf16 v[28:31], v[84:87], v[164:167], v[28:31]
	v_mfma_f32_16x16x32_bf16 v[24:27], v[76:79], v[200:203], v[24:27]
	v_mfma_f32_16x16x32_bf16 v[20:23], v[84:87], v[200:203], v[20:23]
	v_mfma_f32_16x16x32_bf16 v[16:19], v[76:79], v[208:211], v[16:19]
	v_mfma_f32_16x16x32_bf16 v[12:15], v[84:87], v[208:211], v[12:15]
	v_mfma_f32_16x16x32_bf16 v[8:11], v[76:79], v[216:219], v[8:11]
	v_mfma_f32_16x16x32_bf16 v[4:7], v[84:87], v[216:219], v[4:7]
	v_mfma_f32_16x16x32_bf16 v[32:35], v[80:83], v[168:171], v[32:35]
	v_mfma_f32_16x16x32_bf16 v[28:31], v[96:99], v[168:171], v[28:31]
	v_mfma_f32_16x16x32_bf16 v[24:27], v[80:83], v[204:207], v[24:27]
	v_mfma_f32_16x16x32_bf16 v[20:23], v[96:99], v[204:207], v[20:23]
	v_mfma_f32_16x16x32_bf16 v[16:19], v[80:83], v[212:215], v[16:19]
	v_mfma_f32_16x16x32_bf16 v[12:15], v[96:99], v[212:215], v[12:15]
	v_mfma_f32_16x16x32_bf16 v[8:11], v[80:83], v[220:223], v[8:11]
	v_mfma_f32_16x16x32_bf16 v[4:7], v[96:99], v[220:223], v[4:7]
	s_barrier
; #define PG8_STAGE(bufoff, gbase, voff) do { _Pragma("unroll") for (int _i = 0; _i < 2; ++_i) \
;         __builtin_amdgcn_global_load_lds((const unsigned*)((const char*)(gbase) + (voff)[_i]), (PG8_LAS unsigned*)(lds + (bufoff) + ldsw + _i * 8192), 16, 0, 0); } while (0)
; #define PG8_LDA(dst, b, h) do { _Pragma("unroll") for (int m = 0; m < 4; ++m) _Pragma("unroll") for (int k = 0; k < 2; ++k) dst[m][k] = *(const PG8_LAS bf16x8*)(lds + PG8_SA(b, h) + aoff + m * 2048 + k * 1024); } while (0)
; #define PG8_LDB(dst, b, h) do { _Pragma("unroll") for (int n = 0; n < 2; ++n) _Pragma("unroll") for (int k = 0; k < 2; ++k) dst[n][k] = *(const PG8_LAS bf16x8*)(lds + PG8_SB(b, h) + boff + n * 2048 + k * 1024); } while (0)
; #define PG8_MMA(ai, bj, At, Bt) do { __builtin_amdgcn_s_setprio(1); _Pragma("unroll") for (int m = 0; m < 4; ++m) _Pragma("unroll") for (int n = 0; n < 2; ++n) _Pragma("unroll") for (int k = 0; k < 2; ++k) \
;         acc[ai][bj][m][n] = __builtin_amdgcn_mfma_f32_16x16x32_bf16(Bt[n][k], At[m][k], acc[ai][bj][m][n], 0, 0, 0); __builtin_amdgcn_s_setprio(0); } while (0)
; #define PG8_WAIT_V(n) asm volatile("s_waitcnt vmcnt(" #n ")" ::: "memory")
; #define PG8_WAIT_L(n) asm volatile("s_waitcnt lgkmcnt(" #n ")" ::: "memory")
; #define PG8_BAR __builtin_amdgcn_s_barrier()
; #define PG8_SCHED __builtin_amdgcn_sched_barrier(0)
; template <class Epi, class Sched, bool ALIGN_EPI = false, bool SP2 = false>
; __device__ __forceinline__ void gemm_phase(PG8_LAS unsigned char* lds, const Gemm g, const Sched& S, const Epi& E) {
;     ...
;             PG8_WAIT_V(8); PG8_WAIT_L(0); PG8_BAR; PG8_MMA(1, 0, At, B0); PG8_MMA(1, 1, At, B1); PG8_BAR; PG8_SCHED;
;             PG8_LDB(B0, 1, 0); PG8_LDB(B1, 1, 1); PG8_SCHED; PG8_LDA(At, 1, 0); PG8_STAGE(PG8_SA(0, 1), a2 + hstep, voffA);
;             PG8_WAIT_V(8); PG8_WAIT_L(0); PG8_BAR; PG8_MMA(0, 0, At, B0); PG8_MMA(0, 1, At, B1); PG8_BAR; PG8_SCHED;
;             PG8_LDA(At, 1, 1); PG8_STAGE(PG8_SB(1, 0), b3, voffB); PG8_STAGE(PG8_SB(1, 1), b3 + hstep, voffB); PG8_STAGE(PG8_SA(1, 0), a3, voffA);
;             PG8_WAIT_V(8); PG8_WAIT_L(0); PG8_BAR; PG8_MMA(1, 0, At, B0); PG8_MMA(1, 1, At, B1); PG8_BAR; PG8_SCHED;
	s_add_i32 s46, 0, 0x18000
	s_add_i32 s47, 0, 0x1c000
	v_add_u32_e32 v80, s46, v243
	v_add_u32_e32 v88, s47, v243
	ds_read_b128 v[44:47], v80
	ds_read_b128 v[48:51], v80 offset:1024
	ds_read_b128 v[76:79], v80 offset:2048
	ds_read_b128 v[80:83], v80 offset:3072
	ds_read_b128 v[84:87], v88
	ds_read_b128 v[96:99], v88 offset:1024
	ds_read_b128 v[164:167], v88 offset:2048
	ds_read_b128 v[168:171], v88 offset:3072
	s_add_u32 s16, s16, 0x80000
	s_addc_u32 s17, s17, 0
	s_mov_b32 m0, s31
	v_lshl_add_u64 v[224:225], s[16:17], 0, v[190:191]
	ds_read_b128 v[88:91], v249 offset:32768
	ds_read_b128 v[92:95], v249 offset:33792
	ds_read_b128 v[200:203], v249 offset:34816
	ds_read_b128 v[204:207], v249 offset:35840
	ds_read_b128 v[208:211], v249 offset:36864
	ds_read_b128 v[212:215], v249 offset:37888
	ds_read_b128 v[216:219], v249 offset:38912
	ds_read_b128 v[220:223], v249 offset:39936
	global_load_lds_dwordx4 v[224:225], off
	v_lshl_add_u64 v[224:225], s[16:17], 0, v[186:187]
	s_mov_b32 m0, s34
	s_nop 0
	global_load_lds_dwordx4 v[224:225], off
	s_waitcnt vmcnt(8)
	s_waitcnt lgkmcnt(0)
	s_barrier
	s_waitcnt lgkmcnt(0)
	v_mfma_f32_16x16x32_bf16 v[152:155], v[44:47], v[88:91], v[152:155]
	v_mfma_f32_16x16x32_bf16 v[148:151], v[76:79], v[88:91], v[148:151]
	v_mfma_f32_16x16x32_bf16 v[136:139], v[44:47], v[200:203], v[136:139]
	v_mfma_f32_16x16x32_bf16 v[132:135], v[76:79], v[200:203], v[132:135]
	v_mfma_f32_16x16x32_bf16 v[128:131], v[44:47], v[208:211], v[128:131]
	v_mfma_f32_16x16x32_bf16 v[124:127], v[76:79], v[208:211], v[124:127]
	v_mfma_f32_16x16x32_bf16 v[160:163], v[44:47], v[216:219], v[160:163]
	v_mfma_f32_16x16x32_bf16 v[156:159], v[76:79], v[216:219], v[156:159]
	v_mfma_f32_16x16x32_bf16 v[152:155], v[48:51], v[92:95], v[152:155]
	v_mfma_f32_16x16x32_bf16 v[148:151], v[80:83], v[92:95], v[148:151]
	v_mfma_f32_16x16x32_bf16 v[136:139], v[48:51], v[204:207], v[136:139]
	v_mfma_f32_16x16x32_bf16 v[132:135], v[80:83], v[204:207], v[132:135]
	v_mfma_f32_16x16x32_bf16 v[128:131], v[48:51], v[212:215], v[128:131]
	v_mfma_f32_16x16x32_bf16 v[124:127], v[80:83], v[212:215], v[124:127]
	v_mfma_f32_16x16x32_bf16 v[160:163], v[48:51], v[220:223], v[160:163]
	v_mfma_f32_16x16x32_bf16 v[156:159], v[80:83], v[220:223], v[156:159]
	v_mfma_f32_16x16x32_bf16 v[144:147], v[84:87], v[88:91], v[144:147]
	v_mfma_f32_16x16x32_bf16 v[88:91], v[164:167], v[88:91], v[140:143]
	v_mfma_f32_16x16x32_bf16 v[140:143], v[168:171], v[92:95], v[88:91]
	v_mfma_f32_16x16x32_bf16 v[88:91], v[84:87], v[200:203], v[120:123]
	v_mfma_f32_16x16x32_bf16 v[120:123], v[96:99], v[204:207], v[88:91]
	v_mfma_f32_16x16x32_bf16 v[88:91], v[164:167], v[200:203], v[116:119]
	v_mfma_f32_16x16x32_bf16 v[116:119], v[168:171], v[204:207], v[88:91]
	v_mfma_f32_16x16x32_bf16 v[88:91], v[84:87], v[208:211], v[112:115]
	v_mfma_f32_16x16x32_bf16 v[112:115], v[96:99], v[212:215], v[88:91]
	v_mfma_f32_16x16x32_bf16 v[88:91], v[164:167], v[208:211], v[108:111]
	v_mfma_f32_16x16x32_bf16 v[108:111], v[168:171], v[212:215], v[88:91]
	v_mfma_f32_16x16x32_bf16 v[88:91], v[84:87], v[216:219], v[104:107]
	v_mfma_f32_16x16x32_bf16 v[104:107], v[96:99], v[220:223], v[88:91]
	v_mfma_f32_16x16x32_bf16 v[88:91], v[164:167], v[216:219], v[100:103]
	v_mfma_f32_16x16x32_bf16 v[144:147], v[96:99], v[92:95], v[144:147]
	v_mfma_f32_16x16x32_bf16 v[100:103], v[168:171], v[220:223], v[88:91]
	s_barrier
	s_add_i32 s16, s46, s28
	s_nop 2
	v_lshl_add_u64 v[88:89], v[232:233], 0, s[10:11]
	s_mov_b32 m0, s16
	ds_read_b128 v[200:203], v249 offset:49152
	ds_read_b128 v[204:207], v249 offset:50176
	ds_read_b128 v[208:211], v249 offset:51200
	ds_read_b128 v[212:215], v249 offset:52224
	ds_read_b128 v[216:219], v249 offset:53248
	ds_read_b128 v[220:223], v249 offset:54272
	ds_read_b128 v[224:227], v249 offset:55296
	ds_read_b128 v[228:231], v249 offset:56320
	global_load_lds_dwordx4 v[88:89], off
	s_add_i32 m0, s16, 0x2000
	s_add_u32 s14, s14, 0x80080
	v_lshl_add_u64 v[88:89], v[234:235], 0, s[10:11]
	s_addc_u32 s15, s15, 0
	s_add_i32 s16, s47, s28
	global_load_lds_dwordx4 v[88:89], off
	v_lshl_add_u64 v[88:89], s[14:15], 0, v[188:189]
	s_mov_b32 m0, s16
	s_nop 0
	global_load_lds_dwordx4 v[88:89], off
	v_lshl_add_u64 v[88:89], s[14:15], 0, v[184:185]
	s_add_i32 m0, s16, 0x2000
	s_nop 0
	global_load_lds_dwordx4 v[88:89], off
	v_lshl_add_u64 v[88:89], v[236:237], 0, s[10:11]
	s_mov_b32 m0, s72
	s_nop 0
	global_load_lds_dwordx4 v[88:89], off
	v_lshl_add_u64 v[88:89], v[250:251], 0, s[10:11]
	s_mov_b32 m0, s73
	s_nop 0
	global_load_lds_dwordx4 v[88:89], off
	s_waitcnt vmcnt(8)
	s_waitcnt lgkmcnt(0)
	s_barrier
	s_waitcnt lgkmcnt(0)
	v_mfma_f32_16x16x32_bf16 v[36:39], v[44:47], v[224:227], v[36:39]
	v_mfma_f32_16x16x32_bf16 v[72:75], v[44:47], v[200:203], v[72:75]
	v_mfma_f32_16x16x32_bf16 v[68:71], v[76:79], v[200:203], v[68:71]
	v_mfma_f32_16x16x32_bf16 v[64:67], v[44:47], v[208:211], v[64:67]
	v_mfma_f32_16x16x32_bf16 v[60:63], v[76:79], v[208:211], v[60:63]
	v_mfma_f32_16x16x32_bf16 v[56:59], v[44:47], v[216:219], v[56:59]
	v_mfma_f32_16x16x32_bf16 v[52:55], v[76:79], v[216:219], v[52:55]
	v_mfma_f32_16x16x32_bf16 v[92:95], v[48:51], v[228:231], v[36:39]
	v_mfma_f32_16x16x32_bf16 v[36:39], v[76:79], v[224:227], v[40:43]
	v_mfma_f32_16x16x32_bf16 v[72:75], v[48:51], v[204:207], v[72:75]
	v_mfma_f32_16x16x32_bf16 v[68:71], v[80:83], v[204:207], v[68:71]
	v_mfma_f32_16x16x32_bf16 v[64:67], v[48:51], v[212:215], v[64:67]
	v_mfma_f32_16x16x32_bf16 v[60:63], v[80:83], v[212:215], v[60:63]
	v_mfma_f32_16x16x32_bf16 v[56:59], v[48:51], v[220:223], v[56:59]
	v_mfma_f32_16x16x32_bf16 v[52:55], v[80:83], v[220:223], v[52:55]
	v_mfma_f32_16x16x32_bf16 v[88:91], v[80:83], v[228:231], v[36:39]
	v_mfma_f32_16x16x32_bf16 v[32:35], v[84:87], v[200:203], v[32:35]
	v_mfma_f32_16x16x32_bf16 v[28:31], v[164:167], v[200:203], v[28:31]
	v_mfma_f32_16x16x32_bf16 v[24:27], v[84:87], v[208:211], v[24:27]
	v_mfma_f32_16x16x32_bf16 v[20:23], v[164:167], v[208:211], v[20:23]
	v_mfma_f32_16x16x32_bf16 v[16:19], v[84:87], v[216:219], v[16:19]
	v_mfma_f32_16x16x32_bf16 v[12:15], v[164:167], v[216:219], v[12:15]
	v_mfma_f32_16x16x32_bf16 v[8:11], v[84:87], v[224:227], v[8:11]
	v_mfma_f32_16x16x32_bf16 v[4:7], v[164:167], v[224:227], v[4:7]
	v_mfma_f32_16x16x32_bf16 v[32:35], v[96:99], v[204:207], v[32:35]
	v_mfma_f32_16x16x32_bf16 v[28:31], v[168:171], v[204:207], v[28:31]
	v_mfma_f32_16x16x32_bf16 v[24:27], v[96:99], v[212:215], v[24:27]
	v_mfma_f32_16x16x32_bf16 v[20:23], v[168:171], v[212:215], v[20:23]
	v_mfma_f32_16x16x32_bf16 v[16:19], v[96:99], v[220:223], v[16:19]
	v_mfma_f32_16x16x32_bf16 v[12:15], v[168:171], v[220:223], v[12:15]
	v_mfma_f32_16x16x32_bf16 v[8:11], v[96:99], v[228:231], v[8:11]
	v_mfma_f32_16x16x32_bf16 v[4:7], v[168:171], v[228:231], v[4:7]
	s_barrier
	s_add_i32 s45, s45, 2
	s_add_u32 s43, s43, 0x100
	s_addc_u32 s44, s44, 0
	s_add_u32 s0, s0, 0x100
	s_addc_u32 s1, s1, 0
	s_cmp_gt_u32 s45, 29
	s_cbranch_scc0 .LBB0_660
	s_and_b64 vcc, exec, s[52:53]
	s_cbranch_vccz .LBB0_663
	s_barrier

; #define PG8_STAGE(bufoff, gbase, voff) do { _Pragma("unroll") for (int _i = 0; _i < 2; ++_i) \
;         __builtin_amdgcn_global_load_lds((const unsigned*)((const char*)(gbase) + (voff)[_i]), (PG8_LAS unsigned*)(lds + (bufoff) + ldsw + _i * 8192), 16, 0, 0); } while (0)
; #define PG8_LDA(dst, b, h) do { _Pragma("unroll") for (int m = 0; m < 4; ++m) _Pragma("unroll") for (int k = 0; k < 2; ++k) dst[m][k] = *(const PG8_LAS bf16x8*)(lds + PG8_SA(b, h) + aoff + m * 2048 + k * 1024); } while (0)
; #define PG8_LDB(dst, b, h) do { _Pragma("unroll") for (int n = 0; n < 2; ++n) _Pragma("unroll") for (int k = 0; k < 2; ++k) dst[n][k] = *(const PG8_LAS bf16x8*)(lds + PG8_SB(b, h) + boff + n * 2048 + k * 1024); } while (0)
; #define PG8_WAIT_V(n) asm volatile("s_waitcnt vmcnt(" #n ")" ::: "memory")
; #define PG8_WAIT_L(n) asm volatile("s_waitcnt lgkmcnt(" #n ")" ::: "memory")
; #define PG8_BAR __builtin_amdgcn_s_barrier()
; template <class Epi, class Sched, bool ALIGN_EPI = false, bool SP2 = false>
; __device__ __forceinline__ void gemm_phase(PG8_LAS unsigned char* lds, const Gemm g, const Sched& S, const Epi& E) {
;     ...
;         const bool has_next = S.next(ui + 1, nxt);
;         const char* nA = has_next ? (const char*)g.A + (size_t)nxt.pm * tstep : cA; const char* nB = has_next ? (const char*)g.Bt + (size_t)nxt.pn * tstep : cB;
;         for (int t = 0; t < nt; t += 2) {
;             const bool last = (t == nt - 2);
;             const char* a1 = cA + (size_t)(t + 1) * kstep;
;             const char* a2 = last ? nA : cA + (size_t)(t + 2) * kstep; const char* b2 = last ? nB : cB + (size_t)(t + 2) * kstep;
;             const char* a3 = a2 + kstep; const char* b3 = b2 + kstep;
;             if (last && has_next) S.a_ready(nxt);
;             if constexpr (SP2) {
;             PG8_LDB(B0, 0, 0); PG8_LDB(B1, 0, 1); PG8_SCHED; PG8_LDA(At, 0, 0); PG8_STAGE(PG8_SA(1, 1), a1 + hstep, voffA);
;             PG8_WAIT_V(8); PG8_WAIT_L(0); PG8_BAR; PG8_MMA(0, 0, At, B0); PG8_MMA(0, 1, At, B1); PG8_BAR; PG8_SCHED;
;     ...
; #pragma unroll
;         for (int a = 0; a < 2; ++a)
; #pragma unroll
;             for (int b = 0; b < 2; ++b)
; #pragma unroll
;                 for (int m = 0; m < 4; ++m)
; #pragma unroll
;                     for (int n = 0; n < 2; ++n) acc[a][b][m][n] = (f32x4){0.f, 0.f, 0.f, 0.f};
;         cur = nxt; cA = nA; cB = nB; ++ui;
.LBB0_821:
	s_add_u32 s23, s14, 0x100
	v_mov_b32_e32 v4, 0
	s_addc_u32 s24, s15, 0
	s_mov_b32 s25, -2
	s_waitcnt lgkmcnt(0)
	v_mov_b32_e32 v5, v4
	v_mov_b32_e32 v6, v4
	v_mov_b32_e32 v7, v4
	v_mov_b32_e32 v8, v4
	v_mov_b32_e32 v9, v4
	v_mov_b32_e32 v10, v4
	v_mov_b32_e32 v11, v4
	v_mov_b32_e32 v20, v4
	v_mov_b32_e32 v21, v4
	v_mov_b32_e32 v22, v4
	v_mov_b32_e32 v23, v4
	v_mov_b32_e32 v24, v4
	v_mov_b32_e32 v25, v4
	v_mov_b32_e32 v26, v4
	v_mov_b32_e32 v27, v4
	s_waitcnt vmcnt(0)
	v_mov_b32_e32 v36, v4
	v_mov_b32_e32 v37, v4
	v_mov_b32_e32 v38, v4
	v_mov_b32_e32 v39, v4
	v_mov_b32_e32 v40, v4
	v_mov_b32_e32 v41, v4
	v_mov_b32_e32 v42, v4
	v_mov_b32_e32 v43, v4
	v_mov_b32_e32 v52, v4
	v_mov_b32_e32 v53, v4
	v_mov_b32_e32 v54, v4
	v_mov_b32_e32 v55, v4
	v_mov_b32_e32 v56, v4
	v_mov_b32_e32 v57, v4
	v_mov_b32_e32 v58, v4
	v_mov_b32_e32 v59, v4
	v_mov_b32_e32 v12, v4
	v_mov_b32_e32 v13, v4
	v_mov_b32_e32 v14, v4
	v_mov_b32_e32 v15, v4
	v_mov_b32_e32 v16, v4
	v_mov_b32_e32 v17, v4
	v_mov_b32_e32 v18, v4
	v_mov_b32_e32 v19, v4
	v_mov_b32_e32 v28, v4
	v_mov_b32_e32 v29, v4
	v_mov_b32_e32 v30, v4
	v_mov_b32_e32 v31, v4
	v_mov_b32_e32 v32, v4
	v_mov_b32_e32 v33, v4
	v_mov_b32_e32 v34, v4
	v_mov_b32_e32 v35, v4
	v_mov_b32_e32 v44, v4
	v_mov_b32_e32 v45, v4
	v_mov_b32_e32 v46, v4
	v_mov_b32_e32 v47, v4
	v_mov_b32_e32 v48, v4
	v_mov_b32_e32 v49, v4
	v_mov_b32_e32 v50, v4
	v_mov_b32_e32 v51, v4
	v_mov_b32_e32 v60, v4
	v_mov_b32_e32 v61, v4
	v_mov_b32_e32 v62, v4
	v_mov_b32_e32 v63, v4
	v_mov_b32_e32 v64, v4
	v_mov_b32_e32 v65, v4
	v_mov_b32_e32 v66, v4
	v_mov_b32_e32 v67, v4
	v_mov_b32_e32 v68, v4
	v_mov_b32_e32 v69, v4
	v_mov_b32_e32 v70, v4
	v_mov_b32_e32 v71, v4
	v_mov_b32_e32 v72, v4
	v_mov_b32_e32 v73, v4
	v_mov_b32_e32 v74, v4
	v_mov_b32_e32 v75, v4
	v_mov_b32_e32 v84, v4
	v_mov_b32_e32 v85, v4
	v_mov_b32_e32 v86, v4
	v_mov_b32_e32 v87, v4
	v_mov_b32_e32 v88, v4
	v_mov_b32_e32 v89, v4
	v_mov_b32_e32 v90, v4
	v_mov_b32_e32 v91, v4
	v_mov_b32_e32 v100, v4
	v_mov_b32_e32 v101, v4
	v_mov_b32_e32 v102, v4
	v_mov_b32_e32 v103, v4
	v_mov_b32_e32 v104, v4
	v_mov_b32_e32 v105, v4
	v_mov_b32_e32 v106, v4
	v_mov_b32_e32 v107, v4
	v_mov_b32_e32 v124, v4
	v_mov_b32_e32 v125, v4
	v_mov_b32_e32 v126, v4
	v_mov_b32_e32 v127, v4
	v_mov_b32_e32 v128, v4
	v_mov_b32_e32 v129, v4
	v_mov_b32_e32 v130, v4
	v_mov_b32_e32 v131, v4
	v_mov_b32_e32 v76, v4
	v_mov_b32_e32 v77, v4
	v_mov_b32_e32 v78, v4
	v_mov_b32_e32 v79, v4
	v_mov_b32_e32 v80, v4
	v_mov_b32_e32 v81, v4
	v_mov_b32_e32 v82, v4
	v_mov_b32_e32 v83, v4
	v_mov_b32_e32 v92, v4
	v_mov_b32_e32 v93, v4
	v_mov_b32_e32 v94, v4
	v_mov_b32_e32 v95, v4
	v_mov_b32_e32 v96, v4
	v_mov_b32_e32 v97, v4
	v_mov_b32_e32 v98, v4
	v_mov_b32_e32 v99, v4
	v_mov_b32_e32 v108, v4
	v_mov_b32_e32 v109, v4
	v_mov_b32_e32 v110, v4
	v_mov_b32_e32 v111, v4
	v_mov_b32_e32 v112, v4
	v_mov_b32_e32 v113, v4
	v_mov_b32_e32 v114, v4
	v_mov_b32_e32 v115, v4
	v_mov_b32_e32 v132, v4
	v_mov_b32_e32 v133, v4
	v_mov_b32_e32 v134, v4
	v_mov_b32_e32 v135, v4
	v_mov_b32_e32 v136, v4
	v_mov_b32_e32 v137, v4
	v_mov_b32_e32 v138, v4
	v_mov_b32_e32 v139, v4
	v_readfirstlane_b32 s101, v172
	s_nop 3
	s_cmp_ge_u32 s101, 0x100
	s_cbranch_scc1 .Lprio_hi_822
	s_setprio 1
	s_branch .Lprio_done_822
.Lprio_hi_822:
	s_setprio 0
.Lprio_done_822:
.LBB0_822:
	s_add_u32 s14, s0, 0x100
	s_addc_u32 s15, s1, 0
	s_add_i32 s60, 0, 0x10000
	s_cmpk_eq_i32 s25, 0x52
	s_cselect_b32 s19, s41, s15
	s_cselect_b32 s18, s40, s14
	s_cselect_b32 s17, s51, s24
	s_cselect_b32 s16, s50, s23
	s_add_i32 s61, 0, 0x14000
	v_add_u32_e32 v154, s60, v159
	v_add_u32_e32 v170, s61, v159
	ds_read_b128 v[116:119], v154
	ds_read_b128 v[120:123], v154 offset:1024
	ds_read_b128 v[150:153], v154 offset:2048
	ds_read_b128 v[154:157], v154 offset:3072
	ds_read_b128 v[162:165], v170
	ds_read_b128 v[166:169], v170 offset:1024
	ds_read_b128 v[184:187], v170 offset:2048
	ds_read_b128 v[188:191], v170 offset:3072
	v_lshl_add_u64 v[170:171], s[0:1], 0, v[148:149]
	s_add_i32 m0, s31, 0xc000
	ds_read_b128 v[192:195], v161
	ds_read_b128 v[196:199], v161 offset:1024
	ds_read_b128 v[200:203], v161 offset:2048
	ds_read_b128 v[204:207], v161 offset:3072
	ds_read_b128 v[208:211], v161 offset:4096
	ds_read_b128 v[212:215], v161 offset:5120
	ds_read_b128 v[216:219], v161 offset:6144
	ds_read_b128 v[220:223], v161 offset:7168
	global_load_lds_dwordx4 v[170:171], off
	v_lshl_add_u64 v[170:171], s[0:1], 0, v[146:147]
	s_add_i32 m0, s31, 0xe000
	s_nop 0
	global_load_lds_dwordx4 v[170:171], off
	s_waitcnt vmcnt(8)
	s_waitcnt lgkmcnt(0)
	s_barrier
; #define PG8_STAGE(bufoff, gbase, voff) do { _Pragma("unroll") for (int _i = 0; _i < 2; ++_i) \
;         __builtin_amdgcn_global_load_lds((const unsigned*)((const char*)(gbase) + (voff)[_i]), (PG8_LAS unsigned*)(lds + (bufoff) + ldsw + _i * 8192), 16, 0, 0); } while (0)
; #define PG8_LDA(dst, b, h) do { _Pragma("unroll") for (int m = 0; m < 4; ++m) _Pragma("unroll") for (int k = 0; k < 2; ++k) dst[m][k] = *(const PG8_LAS bf16x8*)(lds + PG8_SA(b, h) + aoff + m * 2048 + k * 1024); } while (0)
; #define PG8_MMA(ai, bj, At, Bt) do { __builtin_amdgcn_s_setprio(1); _Pragma("unroll") for (int m = 0; m < 4; ++m) _Pragma("unroll") for (int n = 0; n < 2; ++n) _Pragma("unroll") for (int k = 0; k < 2; ++k) \
;         acc[ai][bj][m][n] = __builtin_amdgcn_mfma_f32_16x16x32_bf16(Bt[n][k], At[m][k], acc[ai][bj][m][n], 0, 0, 0); __builtin_amdgcn_s_setprio(0); } while (0)
; #define PG8_WAIT_V(n) asm volatile("s_waitcnt vmcnt(" #n ")" ::: "memory")
; #define PG8_WAIT_L(n) asm volatile("s_waitcnt lgkmcnt(" #n ")" ::: "memory")
; #define PG8_BAR __builtin_amdgcn_s_barrier()
; #define PG8_SCHED __builtin_amdgcn_sched_barrier(0)
; template <class Epi, class Sched, bool ALIGN_EPI = false, bool SP2 = false>
; __device__ __forceinline__ void gemm_phase(PG8_LAS unsigned char* lds, const Gemm g, const Sched& S, const Epi& E) {
;     ...
;             PG8_WAIT_V(8); PG8_WAIT_L(0); PG8_BAR; PG8_MMA(0, 0, At, B0); PG8_MMA(0, 1, At, B1); PG8_BAR; PG8_SCHED;
;             PG8_LDA(At, 0, 1); PG8_STAGE(PG8_SB(0, 0), b2, voffB); PG8_STAGE(PG8_SB(0, 1), b2 + hstep, voffB); PG8_STAGE(PG8_SA(0, 0), a2, voffA);
;             PG8_WAIT_V(8); PG8_WAIT_L(0); PG8_BAR; PG8_MMA(1, 0, At, B0); PG8_MMA(1, 1, At, B1); PG8_BAR; PG8_SCHED;
	s_waitcnt lgkmcnt(0)
	v_mfma_f32_16x16x32_bf16 v[136:139], v[116:119], v[192:195], v[136:139]
	v_mfma_f32_16x16x32_bf16 v[132:135], v[150:153], v[192:195], v[132:135]
	v_mfma_f32_16x16x32_bf16 v[112:115], v[116:119], v[200:203], v[112:115]
	v_mfma_f32_16x16x32_bf16 v[108:111], v[150:153], v[200:203], v[108:111]
	v_mfma_f32_16x16x32_bf16 v[96:99], v[116:119], v[208:211], v[96:99]
	v_mfma_f32_16x16x32_bf16 v[92:95], v[150:153], v[208:211], v[92:95]
	v_mfma_f32_16x16x32_bf16 v[80:83], v[116:119], v[216:219], v[80:83]
	v_mfma_f32_16x16x32_bf16 v[76:79], v[150:153], v[216:219], v[76:79]
	v_mfma_f32_16x16x32_bf16 v[136:139], v[120:123], v[196:199], v[136:139]
	v_mfma_f32_16x16x32_bf16 v[132:135], v[154:157], v[196:199], v[132:135]
	v_mfma_f32_16x16x32_bf16 v[112:115], v[120:123], v[204:207], v[112:115]
	v_mfma_f32_16x16x32_bf16 v[108:111], v[154:157], v[204:207], v[108:111]
	v_mfma_f32_16x16x32_bf16 v[96:99], v[120:123], v[212:215], v[96:99]
	v_mfma_f32_16x16x32_bf16 v[92:95], v[154:157], v[212:215], v[92:95]
	v_mfma_f32_16x16x32_bf16 v[80:83], v[120:123], v[220:223], v[80:83]
	v_mfma_f32_16x16x32_bf16 v[76:79], v[154:157], v[220:223], v[76:79]
	v_mfma_f32_16x16x32_bf16 v[128:131], v[162:165], v[192:195], v[128:131]
	v_mfma_f32_16x16x32_bf16 v[124:127], v[184:187], v[192:195], v[124:127]
	v_mfma_f32_16x16x32_bf16 v[104:107], v[162:165], v[200:203], v[104:107]
	v_mfma_f32_16x16x32_bf16 v[100:103], v[184:187], v[200:203], v[100:103]
	v_mfma_f32_16x16x32_bf16 v[88:91], v[162:165], v[208:211], v[88:91]
	v_mfma_f32_16x16x32_bf16 v[84:87], v[184:187], v[208:211], v[84:87]
	v_mfma_f32_16x16x32_bf16 v[72:75], v[162:165], v[216:219], v[72:75]
	v_mfma_f32_16x16x32_bf16 v[68:71], v[184:187], v[216:219], v[68:71]
	v_mfma_f32_16x16x32_bf16 v[128:131], v[166:169], v[196:199], v[128:131]
	v_mfma_f32_16x16x32_bf16 v[124:127], v[188:191], v[196:199], v[124:127]
	v_mfma_f32_16x16x32_bf16 v[104:107], v[166:169], v[204:207], v[104:107]
	v_mfma_f32_16x16x32_bf16 v[100:103], v[188:191], v[204:207], v[100:103]
	v_mfma_f32_16x16x32_bf16 v[88:91], v[166:169], v[212:215], v[88:91]
	v_mfma_f32_16x16x32_bf16 v[84:87], v[188:191], v[212:215], v[84:87]
	v_mfma_f32_16x16x32_bf16 v[72:75], v[166:169], v[220:223], v[72:75]
	v_mfma_f32_16x16x32_bf16 v[68:71], v[188:191], v[220:223], v[68:71]
	s_barrier
	s_add_i32 s0, s60, s30
	v_lshl_add_u64 v[170:171], s[16:17], 0, v[174:175]
	s_mov_b32 m0, s0
	ds_read_b128 v[192:195], v161 offset:16384
	ds_read_b128 v[196:199], v161 offset:17408
	ds_read_b128 v[200:203], v161 offset:18432
	ds_read_b128 v[204:207], v161 offset:19456
	ds_read_b128 v[208:211], v161 offset:20480
	ds_read_b128 v[212:215], v161 offset:21504
	ds_read_b128 v[216:219], v161 offset:22528
	ds_read_b128 v[220:223], v161 offset:23552
	global_load_lds_dwordx4 v[170:171], off
	s_add_i32 m0, s0, 0x2000
	s_add_u32 s0, s16, 0x158000
	v_lshl_add_u64 v[224:225], s[16:17], 0, v[140:141]
	s_addc_u32 s1, s17, 0
	s_add_i32 s60, s61, s30
	global_load_lds_dwordx4 v[224:225], off
	v_lshl_add_u64 v[226:227], s[0:1], 0, v[174:175]
	s_mov_b32 m0, s60
	v_lshl_add_u64 v[228:229], s[18:19], 0, v[142:143]
	global_load_lds_dwordx4 v[226:227], off
	v_lshl_add_u64 v[226:227], s[0:1], 0, v[140:141]
	s_add_i32 m0, s60, 0x2000
	s_nop 0
	global_load_lds_dwordx4 v[226:227], off
	v_lshl_add_u64 v[226:227], s[18:19], 0, v[144:145]
	s_mov_b32 m0, s31
	s_nop 0
	global_load_lds_dwordx4 v[226:227], off
	s_mov_b32 m0, s34
	s_nop 0
	global_load_lds_dwordx4 v[228:229], off
	s_waitcnt vmcnt(8)
	s_waitcnt lgkmcnt(0)
	s_barrier
	s_waitcnt lgkmcnt(0)
	v_mfma_f32_16x16x32_bf16 v[64:67], v[116:119], v[192:195], v[64:67]
	v_mfma_f32_16x16x32_bf16 v[60:63], v[150:153], v[192:195], v[60:63]
	v_mfma_f32_16x16x32_bf16 v[48:51], v[116:119], v[200:203], v[48:51]
	v_mfma_f32_16x16x32_bf16 v[44:47], v[150:153], v[200:203], v[44:47]
	v_mfma_f32_16x16x32_bf16 v[32:35], v[116:119], v[208:211], v[32:35]
	v_mfma_f32_16x16x32_bf16 v[28:31], v[150:153], v[208:211], v[28:31]
	v_mfma_f32_16x16x32_bf16 v[16:19], v[116:119], v[216:219], v[16:19]
	v_mfma_f32_16x16x32_bf16 v[12:15], v[150:153], v[216:219], v[12:15]
	v_mfma_f32_16x16x32_bf16 v[64:67], v[120:123], v[196:199], v[64:67]
	v_mfma_f32_16x16x32_bf16 v[60:63], v[154:157], v[196:199], v[60:63]
	v_mfma_f32_16x16x32_bf16 v[48:51], v[120:123], v[204:207], v[48:51]
	v_mfma_f32_16x16x32_bf16 v[44:47], v[154:157], v[204:207], v[44:47]
	v_mfma_f32_16x16x32_bf16 v[32:35], v[120:123], v[212:215], v[32:35]
	v_mfma_f32_16x16x32_bf16 v[28:31], v[154:157], v[212:215], v[28:31]
	v_mfma_f32_16x16x32_bf16 v[16:19], v[120:123], v[220:223], v[16:19]
	v_mfma_f32_16x16x32_bf16 v[12:15], v[154:157], v[220:223], v[12:15]
	v_mfma_f32_16x16x32_bf16 v[56:59], v[162:165], v[192:195], v[56:59]
	v_mfma_f32_16x16x32_bf16 v[52:55], v[184:187], v[192:195], v[52:55]
	v_mfma_f32_16x16x32_bf16 v[40:43], v[162:165], v[200:203], v[40:43]
	v_mfma_f32_16x16x32_bf16 v[36:39], v[184:187], v[200:203], v[36:39]
	v_mfma_f32_16x16x32_bf16 v[24:27], v[162:165], v[208:211], v[24:27]
	v_mfma_f32_16x16x32_bf16 v[20:23], v[184:187], v[208:211], v[20:23]
	v_mfma_f32_16x16x32_bf16 v[8:11], v[162:165], v[216:219], v[8:11]
	v_mfma_f32_16x16x32_bf16 v[4:7], v[184:187], v[216:219], v[4:7]
	v_mfma_f32_16x16x32_bf16 v[56:59], v[166:169], v[196:199], v[56:59]
	v_mfma_f32_16x16x32_bf16 v[52:55], v[188:191], v[196:199], v[52:55]
	v_mfma_f32_16x16x32_bf16 v[40:43], v[166:169], v[204:207], v[40:43]
	v_mfma_f32_16x16x32_bf16 v[36:39], v[188:191], v[204:207], v[36:39]
	v_mfma_f32_16x16x32_bf16 v[24:27], v[166:169], v[212:215], v[24:27]
	v_mfma_f32_16x16x32_bf16 v[20:23], v[188:191], v[212:215], v[20:23]
	v_mfma_f32_16x16x32_bf16 v[8:11], v[166:169], v[220:223], v[8:11]
	v_mfma_f32_16x16x32_bf16 v[4:7], v[188:191], v[220:223], v[4:7]
	s_barrier
; #define PG8_STAGE(bufoff, gbase, voff) do { _Pragma("unroll") for (int _i = 0; _i < 2; ++_i) \
;         __builtin_amdgcn_global_load_lds((const unsigned*)((const char*)(gbase) + (voff)[_i]), (PG8_LAS unsigned*)(lds + (bufoff) + ldsw + _i * 8192), 16, 0, 0); } while (0)
; #define PG8_LDA(dst, b, h) do { _Pragma("unroll") for (int m = 0; m < 4; ++m) _Pragma("unroll") for (int k = 0; k < 2; ++k) dst[m][k] = *(const PG8_LAS bf16x8*)(lds + PG8_SA(b, h) + aoff + m * 2048 + k * 1024); } while (0)
; #define PG8_LDB(dst, b, h) do { _Pragma("unroll") for (int n = 0; n < 2; ++n) _Pragma("unroll") for (int k = 0; k < 2; ++k) dst[n][k] = *(const PG8_LAS bf16x8*)(lds + PG8_SB(b, h) + boff + n * 2048 + k * 1024); } while (0)
; #define PG8_MMA(ai, bj, At, Bt) do { __builtin_amdgcn_s_setprio(1); _Pragma("unroll") for (int m = 0; m < 4; ++m) _Pragma("unroll") for (int n = 0; n < 2; ++n) _Pragma("unroll") for (int k = 0; k < 2; ++k) \
;         acc[ai][bj][m][n] = __builtin_amdgcn_mfma_f32_16x16x32_bf16(Bt[n][k], At[m][k], acc[ai][bj][m][n], 0, 0, 0); __builtin_amdgcn_s_setprio(0); } while (0)
; #define PG8_WAIT_V(n) asm volatile("s_waitcnt vmcnt(" #n ")" ::: "memory")
; #define PG8_WAIT_L(n) asm volatile("s_waitcnt lgkmcnt(" #n ")" ::: "memory")
; #define PG8_BAR __builtin_amdgcn_s_barrier()
; #define PG8_SCHED __builtin_amdgcn_sched_barrier(0)
; template <class Epi, class Sched, bool ALIGN_EPI = false, bool SP2 = false>
; __device__ __forceinline__ void gemm_phase(PG8_LAS unsigned char* lds, const Gemm g, const Sched& S, const Epi& E) {
;     ...
;             PG8_WAIT_V(8); PG8_WAIT_L(0); PG8_BAR; PG8_MMA(1, 0, At, B0); PG8_MMA(1, 1, At, B1); PG8_BAR; PG8_SCHED;
;             PG8_LDB(B0, 1, 0); PG8_LDB(B1, 1, 1); PG8_SCHED; PG8_LDA(At, 1, 0); PG8_STAGE(PG8_SA(0, 1), a2 + hstep, voffA);
;             PG8_WAIT_V(8); PG8_WAIT_L(0); PG8_BAR; PG8_MMA(0, 0, At, B0); PG8_MMA(0, 1, At, B1); PG8_BAR; PG8_SCHED;
	s_add_i32 s60, 0, 0x18000
	s_add_i32 s61, 0, 0x1c000
	v_add_u32_e32 v154, s60, v159
	v_add_u32_e32 v179, s61, v159
	ds_read_b128 v[116:119], v154
	ds_read_b128 v[120:123], v154 offset:1024
	ds_read_b128 v[150:153], v154 offset:2048
	ds_read_b128 v[154:157], v154 offset:3072
	ds_read_b128 v[162:165], v179
	ds_read_b128 v[166:169], v179 offset:1024
	ds_read_b128 v[184:187], v179 offset:2048
	ds_read_b128 v[188:191], v179 offset:3072
	s_add_u32 s0, s18, 0x158000
	s_addc_u32 s1, s19, 0
	s_mov_b32 m0, s35
	v_lshl_add_u64 v[230:231], s[0:1], 0, v[144:145]
	ds_read_b128 v[192:195], v161 offset:32768
	ds_read_b128 v[196:199], v161 offset:33792
	ds_read_b128 v[200:203], v161 offset:34816
	ds_read_b128 v[204:207], v161 offset:35840
	ds_read_b128 v[208:211], v161 offset:36864
	ds_read_b128 v[212:215], v161 offset:37888
	ds_read_b128 v[216:219], v161 offset:38912
	ds_read_b128 v[220:223], v161 offset:39936
	global_load_lds_dwordx4 v[230:231], off
	v_lshl_add_u64 v[230:231], s[0:1], 0, v[142:143]
	s_mov_b32 m0, s52
	s_nop 0
	global_load_lds_dwordx4 v[230:231], off
	s_waitcnt vmcnt(8)
	s_waitcnt lgkmcnt(0)
	s_barrier
	s_waitcnt lgkmcnt(0)
	v_mfma_f32_16x16x32_bf16 v[136:139], v[116:119], v[192:195], v[136:139]
	v_mfma_f32_16x16x32_bf16 v[132:135], v[150:153], v[192:195], v[132:135]
	v_mfma_f32_16x16x32_bf16 v[112:115], v[116:119], v[200:203], v[112:115]
	v_mfma_f32_16x16x32_bf16 v[108:111], v[150:153], v[200:203], v[108:111]
	v_mfma_f32_16x16x32_bf16 v[96:99], v[116:119], v[208:211], v[96:99]
	v_mfma_f32_16x16x32_bf16 v[92:95], v[150:153], v[208:211], v[92:95]
	v_mfma_f32_16x16x32_bf16 v[80:83], v[116:119], v[216:219], v[80:83]
	v_mfma_f32_16x16x32_bf16 v[76:79], v[150:153], v[216:219], v[76:79]
	v_mfma_f32_16x16x32_bf16 v[136:139], v[120:123], v[196:199], v[136:139]
	v_mfma_f32_16x16x32_bf16 v[132:135], v[154:157], v[196:199], v[132:135]
	v_mfma_f32_16x16x32_bf16 v[112:115], v[120:123], v[204:207], v[112:115]
	v_mfma_f32_16x16x32_bf16 v[108:111], v[154:157], v[204:207], v[108:111]
	v_mfma_f32_16x16x32_bf16 v[96:99], v[120:123], v[212:215], v[96:99]
	v_mfma_f32_16x16x32_bf16 v[92:95], v[154:157], v[212:215], v[92:95]
	v_mfma_f32_16x16x32_bf16 v[80:83], v[120:123], v[220:223], v[80:83]
	v_mfma_f32_16x16x32_bf16 v[76:79], v[154:157], v[220:223], v[76:79]
	v_mfma_f32_16x16x32_bf16 v[128:131], v[162:165], v[192:195], v[128:131]
	v_mfma_f32_16x16x32_bf16 v[124:127], v[184:187], v[192:195], v[124:127]
	v_mfma_f32_16x16x32_bf16 v[104:107], v[162:165], v[200:203], v[104:107]
	v_mfma_f32_16x16x32_bf16 v[100:103], v[184:187], v[200:203], v[100:103]
	v_mfma_f32_16x16x32_bf16 v[88:91], v[162:165], v[208:211], v[88:91]
	v_mfma_f32_16x16x32_bf16 v[84:87], v[184:187], v[208:211], v[84:87]
	v_mfma_f32_16x16x32_bf16 v[72:75], v[162:165], v[216:219], v[72:75]
	v_mfma_f32_16x16x32_bf16 v[68:71], v[184:187], v[216:219], v[68:71]
	v_mfma_f32_16x16x32_bf16 v[128:131], v[166:169], v[196:199], v[128:131]
	v_mfma_f32_16x16x32_bf16 v[124:127], v[188:191], v[196:199], v[124:127]
	v_mfma_f32_16x16x32_bf16 v[104:107], v[166:169], v[204:207], v[104:107]
	v_mfma_f32_16x16x32_bf16 v[100:103], v[188:191], v[204:207], v[100:103]
	v_mfma_f32_16x16x32_bf16 v[88:91], v[166:169], v[212:215], v[88:91]
	v_mfma_f32_16x16x32_bf16 v[84:87], v[188:191], v[212:215], v[84:87]
	v_mfma_f32_16x16x32_bf16 v[72:75], v[166:169], v[220:223], v[72:75]
	v_mfma_f32_16x16x32_bf16 v[68:71], v[188:191], v[220:223], v[68:71]
	s_barrier
; #define PG8_STAGE(bufoff, gbase, voff) do { _Pragma("unroll") for (int _i = 0; _i < 2; ++_i) \
;         __builtin_amdgcn_global_load_lds((const unsigned*)((const char*)(gbase) + (voff)[_i]), (PG8_LAS unsigned*)(lds + (bufoff) + ldsw + _i * 8192), 16, 0, 0); } while (0)
; #define PG8_LDA(dst, b, h) do { _Pragma("unroll") for (int m = 0; m < 4; ++m) _Pragma("unroll") for (int k = 0; k < 2; ++k) dst[m][k] = *(const PG8_LAS bf16x8*)(lds + PG8_SA(b, h) + aoff + m * 2048 + k * 1024); } while (0)
; #define PG8_MMA(ai, bj, At, Bt) do { __builtin_amdgcn_s_setprio(1); _Pragma("unroll") for (int m = 0; m < 4; ++m) _Pragma("unroll") for (int n = 0; n < 2; ++n) _Pragma("unroll") for (int k = 0; k < 2; ++k) \
;         acc[ai][bj][m][n] = __builtin_amdgcn_mfma_f32_16x16x32_bf16(Bt[n][k], At[m][k], acc[ai][bj][m][n], 0, 0, 0); __builtin_amdgcn_s_setprio(0); } while (0)
; #define PG8_WAIT_V(n) asm volatile("s_waitcnt vmcnt(" #n ")" ::: "memory")
; #define PG8_WAIT_L(n) asm volatile("s_waitcnt lgkmcnt(" #n ")" ::: "memory")
; #define PG8_BAR __builtin_amdgcn_s_barrier()
; #define PG8_SCHED __builtin_amdgcn_sched_barrier(0)
; template <class Epi, class Sched, bool ALIGN_EPI = false, bool SP2 = false>
; __device__ __forceinline__ void gemm_phase(PG8_LAS unsigned char* lds, const Gemm g, const Sched& S, const Epi& E) {
;     ...
;         for (int t = 0; t < nt; t += 2) {
;             const bool last = (t == nt - 2);
;             const char* a1 = cA + (size_t)(t + 1) * kstep;
;             const char* a2 = last ? nA : cA + (size_t)(t + 2) * kstep; const char* b2 = last ? nB : cB + (size_t)(t + 2) * kstep;
;             const char* a3 = a2 + kstep; const char* b3 = b2 + kstep;
;     ...
;             PG8_WAIT_V(8); PG8_WAIT_L(0); PG8_BAR; PG8_MMA(0, 0, At, B0); PG8_MMA(0, 1, At, B1); PG8_BAR; PG8_SCHED;
;             PG8_LDA(At, 1, 1); PG8_STAGE(PG8_SB(1, 0), b3, voffB); PG8_STAGE(PG8_SB(1, 1), b3 + hstep, voffB); PG8_STAGE(PG8_SA(1, 0), a3, voffA);
;             PG8_WAIT_V(8); PG8_WAIT_L(0); PG8_BAR; PG8_MMA(1, 0, At, B0); PG8_MMA(1, 1, At, B1); PG8_BAR; PG8_SCHED;
	s_add_i32 s0, s60, s30
	v_lshl_add_u64 v[170:171], v[170:171], 0, s[10:11]
	s_mov_b32 m0, s0
	ds_read_b128 v[192:195], v161 offset:49152
	ds_read_b128 v[196:199], v161 offset:50176
	ds_read_b128 v[200:203], v161 offset:51200
	ds_read_b128 v[204:207], v161 offset:52224
	ds_read_b128 v[208:211], v161 offset:53248
	ds_read_b128 v[212:215], v161 offset:54272
	ds_read_b128 v[216:219], v161 offset:55296
	ds_read_b128 v[220:223], v161 offset:56320
	global_load_lds_dwordx4 v[170:171], off
	s_add_i32 m0, s0, 0x2000
	s_add_u32 s0, s16, 0x158080
	v_lshl_add_u64 v[170:171], v[224:225], 0, s[10:11]
	s_addc_u32 s1, s17, 0
	s_add_i32 s16, s61, s30
	global_load_lds_dwordx4 v[170:171], off
	v_lshl_add_u64 v[170:171], s[0:1], 0, v[174:175]
	s_mov_b32 m0, s16
	s_nop 0
	global_load_lds_dwordx4 v[170:171], off
	v_lshl_add_u64 v[170:171], s[0:1], 0, v[140:141]
	s_add_i32 m0, s16, 0x2000
	s_nop 0
	global_load_lds_dwordx4 v[170:171], off
	v_lshl_add_u64 v[170:171], v[226:227], 0, s[10:11]
	s_mov_b32 m0, s54
	s_nop 0
	global_load_lds_dwordx4 v[170:171], off
	v_lshl_add_u64 v[170:171], v[228:229], 0, s[10:11]
	s_mov_b32 m0, s55
	s_nop 0
	global_load_lds_dwordx4 v[170:171], off
	s_waitcnt vmcnt(8)
	s_waitcnt lgkmcnt(0)
	s_barrier
	s_waitcnt lgkmcnt(0)
	v_mfma_f32_16x16x32_bf16 v[64:67], v[116:119], v[192:195], v[64:67]
	v_mfma_f32_16x16x32_bf16 v[60:63], v[150:153], v[192:195], v[60:63]
	v_mfma_f32_16x16x32_bf16 v[48:51], v[116:119], v[200:203], v[48:51]
	v_mfma_f32_16x16x32_bf16 v[44:47], v[150:153], v[200:203], v[44:47]
	v_mfma_f32_16x16x32_bf16 v[32:35], v[116:119], v[208:211], v[32:35]
	v_mfma_f32_16x16x32_bf16 v[28:31], v[150:153], v[208:211], v[28:31]
	v_mfma_f32_16x16x32_bf16 v[16:19], v[116:119], v[216:219], v[16:19]
	v_mfma_f32_16x16x32_bf16 v[12:15], v[150:153], v[216:219], v[12:15]
	v_mfma_f32_16x16x32_bf16 v[64:67], v[120:123], v[196:199], v[64:67]
	v_mfma_f32_16x16x32_bf16 v[60:63], v[154:157], v[196:199], v[60:63]
	v_mfma_f32_16x16x32_bf16 v[48:51], v[120:123], v[204:207], v[48:51]
	v_mfma_f32_16x16x32_bf16 v[44:47], v[154:157], v[204:207], v[44:47]
	v_mfma_f32_16x16x32_bf16 v[32:35], v[120:123], v[212:215], v[32:35]
	v_mfma_f32_16x16x32_bf16 v[28:31], v[154:157], v[212:215], v[28:31]
	v_mfma_f32_16x16x32_bf16 v[16:19], v[120:123], v[220:223], v[16:19]
	v_mfma_f32_16x16x32_bf16 v[12:15], v[154:157], v[220:223], v[12:15]
	v_mfma_f32_16x16x32_bf16 v[56:59], v[162:165], v[192:195], v[56:59]
	v_mfma_f32_16x16x32_bf16 v[52:55], v[184:187], v[192:195], v[52:55]
	v_mfma_f32_16x16x32_bf16 v[40:43], v[162:165], v[200:203], v[40:43]
	v_mfma_f32_16x16x32_bf16 v[36:39], v[184:187], v[200:203], v[36:39]
	v_mfma_f32_16x16x32_bf16 v[24:27], v[162:165], v[208:211], v[24:27]
	v_mfma_f32_16x16x32_bf16 v[20:23], v[184:187], v[208:211], v[20:23]
	v_mfma_f32_16x16x32_bf16 v[8:11], v[162:165], v[216:219], v[8:11]
	v_mfma_f32_16x16x32_bf16 v[4:7], v[184:187], v[216:219], v[4:7]
	v_mfma_f32_16x16x32_bf16 v[56:59], v[166:169], v[196:199], v[56:59]
	v_mfma_f32_16x16x32_bf16 v[52:55], v[188:191], v[196:199], v[52:55]
	v_mfma_f32_16x16x32_bf16 v[40:43], v[166:169], v[204:207], v[40:43]
	v_mfma_f32_16x16x32_bf16 v[36:39], v[188:191], v[204:207], v[36:39]
	v_mfma_f32_16x16x32_bf16 v[24:27], v[166:169], v[212:215], v[24:27]
	v_mfma_f32_16x16x32_bf16 v[20:23], v[188:191], v[212:215], v[20:23]
	v_mfma_f32_16x16x32_bf16 v[8:11], v[166:169], v[220:223], v[8:11]
	v_mfma_f32_16x16x32_bf16 v[4:7], v[188:191], v[220:223], v[4:7]
	s_barrier
	s_add_i32 s25, s25, 2
	s_add_u32 s23, s23, 0x100
	s_addc_u32 s24, s24, 0
	s_cmpk_gt_u32 s25, 0x53
	s_mov_b64 s[0:1], s[14:15]
	s_cbranch_scc0 .LBB0_822
	s_and_b64 vcc, exec, s[48:49]
	s_cbranch_vccz .LBB0_825
	s_barrier
